# mid-segment s_setprio 0/1 pair between the two 16-MFMA blocks removed
# baseline (speedup 1.0000x reference)
; #define PG8_STAGE(bufoff, gbase, voff) do { _Pragma("unroll") for (int _i = 0; _i < 2; ++_i) \
;         __builtin_amdgcn_global_load_lds((const unsigned*)((const char*)(gbase) + (voff)[_i]), (PG8_LAS unsigned*)(lds + (bufoff) + ldsw + _i * 8192), 16, 0, 0); } while (0)
; #define PG8_LDA(dst, b, h) do { _Pragma("unroll") for (int m = 0; m < 4; ++m) _Pragma("unroll") for (int k = 0; k < 2; ++k) dst[m][k] = *(const PG8_LAS bf16x8*)(lds + PG8_SA(b, h) + aoff + m * 2048 + k * 1024); } while (0)
; #define PG8_LDB(dst, b, h) do { _Pragma("unroll") for (int n = 0; n < 2; ++n) _Pragma("unroll") for (int k = 0; k < 2; ++k) dst[n][k] = *(const PG8_LAS bf16x8*)(lds + PG8_SB(b, h) + boff + n * 2048 + k * 1024); } while (0)
; #define PG8_WAIT_V(n) asm volatile("s_waitcnt vmcnt(" #n ")" ::: "memory")
; #define PG8_WAIT_L(n) asm volatile("s_waitcnt lgkmcnt(" #n ")" ::: "memory")
; #define PG8_BAR __builtin_amdgcn_s_barrier()
; #define PG8_SCHED __builtin_amdgcn_sched_barrier(0)
; template <class Epi, class Sched, bool ALIGN_EPI = false, bool SP2 = false>
; __device__ __forceinline__ void gemm_phase(PG8_LAS unsigned char* lds, const Gemm g, const Sched& S, const Epi& E) {
;     ...
;         const char* nA = has_next ? (const char*)g.A + (size_t)nxt.pm * tstep : cA; const char* nB = has_next ? (const char*)g.Bt + (size_t)nxt.pn * tstep : cB;
;         for (int t = 0; t < nt; t += 2) {
;             const bool last = (t == nt - 2);
;             const char* a1 = cA + (size_t)(t + 1) * kstep;
;             const char* a2 = last ? nA : cA + (size_t)(t + 2) * kstep; const char* b2 = last ? nB : cB + (size_t)(t + 2) * kstep;
;             const char* a3 = a2 + kstep; const char* b3 = b2 + kstep;
;             if (last && has_next) S.a_ready(nxt, ui + 1);
;             if constexpr (SP2) {
;             PG8_LDB(B0, 0, 0); PG8_LDB(B1, 0, 1); PG8_SCHED; PG8_LDA(At, 0, 0); PG8_STAGE(PG8_SA(1, 1), a1 + hstep, voffA);
;             PG8_WAIT_V(8); PG8_WAIT_L(0); PG8_BAR; PG8_MMA(0, 0, At, B0); PG8_MMA(0, 1, At, B1); PG8_BAR; PG8_SCHED;
;             PG8_LDA(At, 0, 1); PG8_STAGE(PG8_SB(0, 0), b2, voffB); PG8_STAGE(PG8_SB(0, 1), b2 + hstep, voffB); PG8_STAGE(PG8_SA(0, 0), a2, voffA);
;             PG8_WAIT_V(8); PG8_WAIT_L(0); PG8_BAR; PG8_MMA(1, 0, At, B0); PG8_MMA(1, 1, At, B1); PG8_BAR; PG8_SCHED;
.LBB0_336:
	s_ashr_i32 s17, s16, 31
	s_lshl_b64 s[18:19], s[16:17], 19
	s_add_u32 s18, s36, s18
	s_addc_u32 s19, s37, s19
	s_and_b64 s[20:21], s[0:1], exec
	s_cselect_b32 s17, s19, s25
	s_cselect_b32 s50, s18, s24
	s_ashr_i32 s15, s14, 31
	s_lshl_b64 s[20:21], s[14:15], 19
	s_add_u32 s20, s34, s20
	s_addc_u32 s21, s35, s21
	s_and_b64 s[28:29], s[0:1], exec
	s_cselect_b32 s15, s21, s27
	s_cselect_b32 s51, s20, s26
	s_add_u32 s24, s24, 0x40080
	s_addc_u32 s25, s25, 0
	s_add_u32 s52, s26, 0x100
	s_addc_u32 s53, s27, 0
	s_mov_b32 s54, -2
	s_add_u32 s26, s24, 0xfffc0080
	s_addc_u32 s27, s25, -1
	s_cmp_eq_u32 s54, 12
	s_cselect_b32 s29, s17, s27
	s_cselect_b32 s28, s50, s26
	s_cselect_b32 s27, s15, s53
	s_cselect_b32 s26, s51, s52
	v_lshl_add_u64 v[216:217], s[24:25], 0, v[136:137]
	s_add_i32 m0, s23, 0xc000
	global_load_lds_dwordx4 v[216:217], off
	v_lshl_add_u64 v[216:217], s[24:25], 0, v[138:139]
	s_add_i32 m0, s23, 0xe000
	s_nop 0
	global_load_lds_dwordx4 v[216:217], off
	s_waitcnt vmcnt(8)
	s_waitcnt lgkmcnt(0)
	s_setprio 1
	s_barrier
	v_mfma_f32_16x16x32_bf16 v[124:127], v[152:155], v[184:187], 0
	v_mfma_f32_16x16x32_bf16 v[120:123], v[160:163], v[184:187], 0
	v_mfma_f32_16x16x32_bf16 v[108:111], v[152:155], v[192:195], 0
	v_mfma_f32_16x16x32_bf16 v[104:107], v[160:163], v[192:195], 0
	v_mfma_f32_16x16x32_bf16 v[92:95], v[152:155], v[200:203], 0
	v_mfma_f32_16x16x32_bf16 v[88:91], v[160:163], v[200:203], 0
	v_mfma_f32_16x16x32_bf16 v[76:79], v[152:155], v[208:211], 0
	v_mfma_f32_16x16x32_bf16 v[72:75], v[160:163], v[208:211], 0
	v_mfma_f32_16x16x32_bf16 v[124:127], v[156:159], v[188:191], v[124:127]
	v_mfma_f32_16x16x32_bf16 v[120:123], v[164:167], v[188:191], v[120:123]
	v_mfma_f32_16x16x32_bf16 v[108:111], v[156:159], v[196:199], v[108:111]
	v_mfma_f32_16x16x32_bf16 v[104:107], v[164:167], v[196:199], v[104:107]
	v_mfma_f32_16x16x32_bf16 v[92:95], v[156:159], v[204:207], v[92:95]
	v_mfma_f32_16x16x32_bf16 v[88:91], v[164:167], v[204:207], v[88:91]
	v_mfma_f32_16x16x32_bf16 v[76:79], v[156:159], v[212:215], v[76:79]
	v_mfma_f32_16x16x32_bf16 v[72:75], v[164:167], v[212:215], v[72:75]
	v_mfma_f32_16x16x32_bf16 v[116:119], v[168:171], v[184:187], 0
	v_mfma_f32_16x16x32_bf16 v[112:115], v[176:179], v[184:187], 0
	v_mfma_f32_16x16x32_bf16 v[100:103], v[168:171], v[192:195], 0
	v_mfma_f32_16x16x32_bf16 v[96:99], v[176:179], v[192:195], 0
	v_mfma_f32_16x16x32_bf16 v[84:87], v[168:171], v[200:203], 0
	v_mfma_f32_16x16x32_bf16 v[80:83], v[176:179], v[200:203], 0
	v_mfma_f32_16x16x32_bf16 v[68:71], v[168:171], v[208:211], 0
	v_mfma_f32_16x16x32_bf16 v[64:67], v[176:179], v[208:211], 0
	v_mfma_f32_16x16x32_bf16 v[116:119], v[172:175], v[188:191], v[116:119]
	v_mfma_f32_16x16x32_bf16 v[112:115], v[180:183], v[188:191], v[112:115]
	v_mfma_f32_16x16x32_bf16 v[100:103], v[172:175], v[196:199], v[100:103]
	v_mfma_f32_16x16x32_bf16 v[96:99], v[180:183], v[196:199], v[96:99]
	v_mfma_f32_16x16x32_bf16 v[84:87], v[172:175], v[204:207], v[84:87]
	v_mfma_f32_16x16x32_bf16 v[80:83], v[180:183], v[204:207], v[80:83]
	v_mfma_f32_16x16x32_bf16 v[68:71], v[172:175], v[212:215], v[68:71]
	v_mfma_f32_16x16x32_bf16 v[64:67], v[180:183], v[212:215], v[64:67]
	s_barrier
	s_setprio 0
	s_add_i32 s55, s44, s33
	v_lshl_add_u64 v[216:217], s[26:27], 0, v[132:133]
	s_mov_b32 m0, s55
	ds_read_b128 v[184:187], v150 offset:16384
	ds_read_b128 v[188:191], v150 offset:17408
	ds_read_b128 v[192:195], v150 offset:18432
	ds_read_b128 v[196:199], v150 offset:19456
	ds_read_b128 v[200:203], v150 offset:20480
	ds_read_b128 v[204:207], v150 offset:21504
	ds_read_b128 v[208:211], v150 offset:22528
	ds_read_b128 v[212:215], v150 offset:23552
	global_load_lds_dwordx4 v[216:217], off
	s_add_i32 m0, s55, 0x2000
	s_add_u32 s56, s26, 0x40000
	v_lshl_add_u64 v[218:219], s[26:27], 0, v[128:129]
	s_addc_u32 s57, s27, 0
	s_add_i32 s55, s45, s33
	global_load_lds_dwordx4 v[218:219], off
	v_lshl_add_u64 v[220:221], s[56:57], 0, v[132:133]
	s_mov_b32 m0, s55
	v_lshl_add_u64 v[222:223], s[28:29], 0, v[130:131]
	global_load_lds_dwordx4 v[220:221], off
	v_lshl_add_u64 v[220:221], s[56:57], 0, v[128:129]
	s_add_i32 m0, s55, 0x2000
	s_nop 0
	global_load_lds_dwordx4 v[220:221], off
	v_lshl_add_u64 v[220:221], s[28:29], 0, v[134:135]
	s_mov_b32 m0, s23
	s_nop 0
	global_load_lds_dwordx4 v[220:221], off
	s_mov_b32 m0, s39
	s_nop 0
	global_load_lds_dwordx4 v[222:223], off
	s_waitcnt vmcnt(8)
	s_waitcnt lgkmcnt(0)
	s_setprio 1
	s_barrier
	v_mfma_f32_16x16x32_bf16 v[60:63], v[152:155], v[184:187], 0
	v_mfma_f32_16x16x32_bf16 v[56:59], v[160:163], v[184:187], 0
	v_mfma_f32_16x16x32_bf16 v[44:47], v[152:155], v[192:195], 0
	v_mfma_f32_16x16x32_bf16 v[40:43], v[160:163], v[192:195], 0
	v_mfma_f32_16x16x32_bf16 v[28:31], v[152:155], v[200:203], 0
	v_mfma_f32_16x16x32_bf16 v[24:27], v[160:163], v[200:203], 0
	v_mfma_f32_16x16x32_bf16 v[12:15], v[152:155], v[208:211], 0
	v_mfma_f32_16x16x32_bf16 v[8:11], v[160:163], v[208:211], 0
	v_mfma_f32_16x16x32_bf16 v[60:63], v[156:159], v[188:191], v[60:63]
	v_mfma_f32_16x16x32_bf16 v[56:59], v[164:167], v[188:191], v[56:59]
	v_mfma_f32_16x16x32_bf16 v[44:47], v[156:159], v[196:199], v[44:47]
	v_mfma_f32_16x16x32_bf16 v[40:43], v[164:167], v[196:199], v[40:43]
	v_mfma_f32_16x16x32_bf16 v[28:31], v[156:159], v[204:207], v[28:31]
	v_mfma_f32_16x16x32_bf16 v[24:27], v[164:167], v[204:207], v[24:27]
	v_mfma_f32_16x16x32_bf16 v[12:15], v[156:159], v[212:215], v[12:15]
	v_mfma_f32_16x16x32_bf16 v[8:11], v[164:167], v[212:215], v[8:11]
	v_mfma_f32_16x16x32_bf16 v[52:55], v[168:171], v[184:187], 0
	v_mfma_f32_16x16x32_bf16 v[48:51], v[176:179], v[184:187], 0
	v_mfma_f32_16x16x32_bf16 v[36:39], v[168:171], v[192:195], 0
	v_mfma_f32_16x16x32_bf16 v[32:35], v[176:179], v[192:195], 0
	v_mfma_f32_16x16x32_bf16 v[20:23], v[168:171], v[200:203], 0
	v_mfma_f32_16x16x32_bf16 v[16:19], v[176:179], v[200:203], 0
	v_mfma_f32_16x16x32_bf16 v[4:7], v[168:171], v[208:211], 0
	v_mfma_f32_16x16x32_bf16 v[0:3], v[176:179], v[208:211], 0
	v_mfma_f32_16x16x32_bf16 v[52:55], v[172:175], v[188:191], v[52:55]
	v_mfma_f32_16x16x32_bf16 v[48:51], v[180:183], v[188:191], v[48:51]
	v_mfma_f32_16x16x32_bf16 v[36:39], v[172:175], v[196:199], v[36:39]
	v_mfma_f32_16x16x32_bf16 v[32:35], v[180:183], v[196:199], v[32:35]
	v_mfma_f32_16x16x32_bf16 v[20:23], v[172:175], v[204:207], v[20:23]
	v_mfma_f32_16x16x32_bf16 v[16:19], v[180:183], v[204:207], v[16:19]
	v_mfma_f32_16x16x32_bf16 v[4:7], v[172:175], v[212:215], v[4:7]
	v_mfma_f32_16x16x32_bf16 v[0:3], v[180:183], v[212:215], v[0:3]
	s_barrier
; #define PG8_STAGE(bufoff, gbase, voff) do { _Pragma("unroll") for (int _i = 0; _i < 2; ++_i) \
;         __builtin_amdgcn_global_load_lds((const unsigned*)((const char*)(gbase) + (voff)[_i]), (PG8_LAS unsigned*)(lds + (bufoff) + ldsw + _i * 8192), 16, 0, 0); } while (0)
; #define PG8_LDA(dst, b, h) do { _Pragma("unroll") for (int m = 0; m < 4; ++m) _Pragma("unroll") for (int k = 0; k < 2; ++k) dst[m][k] = *(const PG8_LAS bf16x8*)(lds + PG8_SA(b, h) + aoff + m * 2048 + k * 1024); } while (0)
; #define PG8_LDB(dst, b, h) do { _Pragma("unroll") for (int n = 0; n < 2; ++n) _Pragma("unroll") for (int k = 0; k < 2; ++k) dst[n][k] = *(const PG8_LAS bf16x8*)(lds + PG8_SB(b, h) + boff + n * 2048 + k * 1024); } while (0)
; #define PG8_MMA(ai, bj, At, Bt) do { __builtin_amdgcn_s_setprio(1); _Pragma("unroll") for (int m = 0; m < 4; ++m) _Pragma("unroll") for (int n = 0; n < 2; ++n) _Pragma("unroll") for (int k = 0; k < 2; ++k) \
;         acc[ai][bj][m][n] = __builtin_amdgcn_mfma_f32_16x16x32_bf16(Bt[n][k], At[m][k], acc[ai][bj][m][n], 0, 0, 0); __builtin_amdgcn_s_setprio(0); } while (0)
; #define PG8_WAIT_V(n) asm volatile("s_waitcnt vmcnt(" #n ")" ::: "memory")
; #define PG8_WAIT_L(n) asm volatile("s_waitcnt lgkmcnt(" #n ")" ::: "memory")
; #define PG8_BAR __builtin_amdgcn_s_barrier()
; #define PG8_SCHED __builtin_amdgcn_sched_barrier(0)
; template <class Epi, class Sched, bool ALIGN_EPI = false, bool SP2 = false>
; __device__ __forceinline__ void gemm_phase(PG8_LAS unsigned char* lds, const Gemm g, const Sched& S, const Epi& E) {
;     ...
;             PG8_WAIT_V(8); PG8_WAIT_L(0); PG8_BAR; PG8_MMA(1, 0, At, B0); PG8_MMA(1, 1, At, B1); PG8_BAR; PG8_SCHED;
;             PG8_LDB(B0, 1, 0); PG8_LDB(B1, 1, 1); PG8_SCHED; PG8_LDA(At, 1, 0); PG8_STAGE(PG8_SA(0, 1), a2 + hstep, voffA);
;             PG8_WAIT_V(8); PG8_WAIT_L(0); PG8_BAR; PG8_MMA(0, 0, At, B0); PG8_MMA(0, 1, At, B1); PG8_BAR; PG8_SCHED;
;             PG8_LDA(At, 1, 1); PG8_STAGE(PG8_SB(1, 0), b3, voffB); PG8_STAGE(PG8_SB(1, 1), b3 + hstep, voffB); PG8_STAGE(PG8_SA(1, 0), a3, voffA);
;             PG8_WAIT_V(8); PG8_WAIT_L(0); PG8_BAR; PG8_MMA(1, 0, At, B0); PG8_MMA(1, 1, At, B1); PG8_BAR; PG8_SCHED;
	s_setprio 0
	s_add_i32 s55, 0, 0x18000
	v_add_u32_e32 v151, s55, v145
	s_add_i32 s56, 0, 0x1c000
	ds_read_b128 v[152:155], v151
	ds_read_b128 v[156:159], v151 offset:1024
	ds_read_b128 v[160:163], v151 offset:2048
	ds_read_b128 v[164:167], v151 offset:3072
	v_add_u32_e32 v151, s56, v145
	ds_read_b128 v[168:171], v151
	ds_read_b128 v[172:175], v151 offset:1024
	ds_read_b128 v[176:179], v151 offset:2048
	ds_read_b128 v[180:183], v151 offset:3072
	s_add_u32 s28, s28, 0x40000
	s_addc_u32 s29, s29, 0
	s_mov_b32 m0, s40
	v_lshl_add_u64 v[224:225], s[28:29], 0, v[134:135]
	ds_read_b128 v[184:187], v150 offset:32768
	ds_read_b128 v[188:191], v150 offset:33792
	ds_read_b128 v[192:195], v150 offset:34816
	ds_read_b128 v[196:199], v150 offset:35840
	ds_read_b128 v[200:203], v150 offset:36864
	ds_read_b128 v[204:207], v150 offset:37888
	ds_read_b128 v[208:211], v150 offset:38912
	ds_read_b128 v[212:215], v150 offset:39936
	global_load_lds_dwordx4 v[224:225], off
	v_lshl_add_u64 v[224:225], s[28:29], 0, v[130:131]
	s_mov_b32 m0, s41
	s_nop 0
	global_load_lds_dwordx4 v[224:225], off
	s_waitcnt vmcnt(8)
	s_waitcnt lgkmcnt(0)
	s_setprio 1
	s_barrier
	v_mfma_f32_16x16x32_bf16 v[124:127], v[152:155], v[184:187], v[124:127]
	v_mfma_f32_16x16x32_bf16 v[120:123], v[160:163], v[184:187], v[120:123]
	v_mfma_f32_16x16x32_bf16 v[108:111], v[152:155], v[192:195], v[108:111]
	v_mfma_f32_16x16x32_bf16 v[104:107], v[160:163], v[192:195], v[104:107]
	v_mfma_f32_16x16x32_bf16 v[92:95], v[152:155], v[200:203], v[92:95]
	v_mfma_f32_16x16x32_bf16 v[88:91], v[160:163], v[200:203], v[88:91]
	v_mfma_f32_16x16x32_bf16 v[76:79], v[152:155], v[208:211], v[76:79]
	v_mfma_f32_16x16x32_bf16 v[72:75], v[160:163], v[208:211], v[72:75]
	v_mfma_f32_16x16x32_bf16 v[124:127], v[156:159], v[188:191], v[124:127]
	v_mfma_f32_16x16x32_bf16 v[120:123], v[164:167], v[188:191], v[120:123]
	v_mfma_f32_16x16x32_bf16 v[108:111], v[156:159], v[196:199], v[108:111]
	v_mfma_f32_16x16x32_bf16 v[104:107], v[164:167], v[196:199], v[104:107]
	v_mfma_f32_16x16x32_bf16 v[92:95], v[156:159], v[204:207], v[92:95]
	v_mfma_f32_16x16x32_bf16 v[88:91], v[164:167], v[204:207], v[88:91]
	v_mfma_f32_16x16x32_bf16 v[76:79], v[156:159], v[212:215], v[76:79]
	v_mfma_f32_16x16x32_bf16 v[72:75], v[164:167], v[212:215], v[72:75]
	v_mfma_f32_16x16x32_bf16 v[116:119], v[168:171], v[184:187], v[116:119]
	v_mfma_f32_16x16x32_bf16 v[112:115], v[176:179], v[184:187], v[112:115]
	v_mfma_f32_16x16x32_bf16 v[100:103], v[168:171], v[192:195], v[100:103]
	v_mfma_f32_16x16x32_bf16 v[96:99], v[176:179], v[192:195], v[96:99]
	v_mfma_f32_16x16x32_bf16 v[84:87], v[168:171], v[200:203], v[84:87]
	v_mfma_f32_16x16x32_bf16 v[80:83], v[176:179], v[200:203], v[80:83]
	v_mfma_f32_16x16x32_bf16 v[68:71], v[168:171], v[208:211], v[68:71]
	v_mfma_f32_16x16x32_bf16 v[64:67], v[176:179], v[208:211], v[64:67]
	v_mfma_f32_16x16x32_bf16 v[116:119], v[172:175], v[188:191], v[116:119]
	v_mfma_f32_16x16x32_bf16 v[112:115], v[180:183], v[188:191], v[112:115]
	v_mfma_f32_16x16x32_bf16 v[100:103], v[172:175], v[196:199], v[100:103]
	v_mfma_f32_16x16x32_bf16 v[96:99], v[180:183], v[196:199], v[96:99]
	v_mfma_f32_16x16x32_bf16 v[84:87], v[172:175], v[204:207], v[84:87]
	v_mfma_f32_16x16x32_bf16 v[80:83], v[180:183], v[204:207], v[80:83]
	v_mfma_f32_16x16x32_bf16 v[68:71], v[172:175], v[212:215], v[68:71]
	v_mfma_f32_16x16x32_bf16 v[64:67], v[180:183], v[212:215], v[64:67]
	s_barrier
	s_setprio 0
	s_add_i32 s28, s55, s33
	v_lshl_add_u64 v[216:217], v[216:217], 0, s[8:9]
	s_mov_b32 m0, s28
	ds_read_b128 v[184:187], v150 offset:49152
	ds_read_b128 v[188:191], v150 offset:50176
	ds_read_b128 v[192:195], v150 offset:51200
	ds_read_b128 v[196:199], v150 offset:52224
	ds_read_b128 v[200:203], v150 offset:53248
	ds_read_b128 v[204:207], v150 offset:54272
	ds_read_b128 v[208:211], v150 offset:55296
	ds_read_b128 v[212:215], v150 offset:56320
	global_load_lds_dwordx4 v[216:217], off
	s_add_i32 m0, s28, 0x2000
	s_add_u32 s26, s26, 0x40080
	v_lshl_add_u64 v[216:217], v[218:219], 0, s[8:9]
	s_addc_u32 s27, s27, 0
	s_add_i32 s28, s56, s33
	global_load_lds_dwordx4 v[216:217], off
	v_lshl_add_u64 v[216:217], s[26:27], 0, v[132:133]
	s_mov_b32 m0, s28
	s_nop 0
	global_load_lds_dwordx4 v[216:217], off
	v_lshl_add_u64 v[216:217], s[26:27], 0, v[128:129]
	s_add_i32 m0, s28, 0x2000
	s_nop 0
	global_load_lds_dwordx4 v[216:217], off
	v_lshl_add_u64 v[216:217], v[220:221], 0, s[8:9]
	s_mov_b32 m0, s42
	s_nop 0
	global_load_lds_dwordx4 v[216:217], off
	v_lshl_add_u64 v[216:217], v[222:223], 0, s[8:9]
	s_mov_b32 m0, s43
	s_nop 0
	global_load_lds_dwordx4 v[216:217], off
	s_waitcnt vmcnt(8)
	s_waitcnt lgkmcnt(0)
	s_setprio 1
	s_barrier
	v_mfma_f32_16x16x32_bf16 v[60:63], v[152:155], v[184:187], v[60:63]
	v_mfma_f32_16x16x32_bf16 v[56:59], v[160:163], v[184:187], v[56:59]
	v_mfma_f32_16x16x32_bf16 v[44:47], v[152:155], v[192:195], v[44:47]
	v_mfma_f32_16x16x32_bf16 v[40:43], v[160:163], v[192:195], v[40:43]
	v_mfma_f32_16x16x32_bf16 v[28:31], v[152:155], v[200:203], v[28:31]
	v_mfma_f32_16x16x32_bf16 v[24:27], v[160:163], v[200:203], v[24:27]
	v_mfma_f32_16x16x32_bf16 v[12:15], v[152:155], v[208:211], v[12:15]
	v_mfma_f32_16x16x32_bf16 v[8:11], v[160:163], v[208:211], v[8:11]
	v_mfma_f32_16x16x32_bf16 v[60:63], v[156:159], v[188:191], v[60:63]
	v_mfma_f32_16x16x32_bf16 v[56:59], v[164:167], v[188:191], v[56:59]
	v_mfma_f32_16x16x32_bf16 v[44:47], v[156:159], v[196:199], v[44:47]
	v_mfma_f32_16x16x32_bf16 v[40:43], v[164:167], v[196:199], v[40:43]
	v_mfma_f32_16x16x32_bf16 v[28:31], v[156:159], v[204:207], v[28:31]
	v_mfma_f32_16x16x32_bf16 v[24:27], v[164:167], v[204:207], v[24:27]
	v_mfma_f32_16x16x32_bf16 v[12:15], v[156:159], v[212:215], v[12:15]
	v_mfma_f32_16x16x32_bf16 v[8:11], v[164:167], v[212:215], v[8:11]
	v_mfma_f32_16x16x32_bf16 v[52:55], v[168:171], v[184:187], v[52:55]
	v_mfma_f32_16x16x32_bf16 v[48:51], v[176:179], v[184:187], v[48:51]
	v_mfma_f32_16x16x32_bf16 v[36:39], v[168:171], v[192:195], v[36:39]
	v_mfma_f32_16x16x32_bf16 v[32:35], v[176:179], v[192:195], v[32:35]
	v_mfma_f32_16x16x32_bf16 v[20:23], v[168:171], v[200:203], v[20:23]
	v_mfma_f32_16x16x32_bf16 v[16:19], v[176:179], v[200:203], v[16:19]
	v_mfma_f32_16x16x32_bf16 v[4:7], v[168:171], v[208:211], v[4:7]
	v_mfma_f32_16x16x32_bf16 v[0:3], v[176:179], v[208:211], v[0:3]
	v_mfma_f32_16x16x32_bf16 v[52:55], v[172:175], v[188:191], v[52:55]
	v_mfma_f32_16x16x32_bf16 v[48:51], v[180:183], v[188:191], v[48:51]
	v_mfma_f32_16x16x32_bf16 v[36:39], v[172:175], v[196:199], v[36:39]
	v_mfma_f32_16x16x32_bf16 v[32:35], v[180:183], v[196:199], v[32:35]
	v_mfma_f32_16x16x32_bf16 v[20:23], v[172:175], v[204:207], v[20:23]
	v_mfma_f32_16x16x32_bf16 v[16:19], v[180:183], v[204:207], v[16:19]
	v_mfma_f32_16x16x32_bf16 v[4:7], v[172:175], v[212:215], v[4:7]
	v_mfma_f32_16x16x32_bf16 v[0:3], v[180:183], v[212:215], v[0:3]
	s_barrier
	s_setprio 0
	s_add_i32 s54, s54, 2
	s_add_u32 s24, s24, 0x100
	s_addc_u32 s25, s25, 0
	s_add_u32 s52, s52, 0x100
	s_addc_u32 s53, s53, 0
	s_cmp_gt_u32 s54, 13
; #define PG8_STAGE(bufoff, gbase, voff) do { _Pragma("unroll") for (int _i = 0; _i < 2; ++_i) \
;         __builtin_amdgcn_global_load_lds((const unsigned*)((const char*)(gbase) + (voff)[_i]), (PG8_LAS unsigned*)(lds + (bufoff) + ldsw + _i * 8192), 16, 0, 0); } while (0)
; #define PG8_LDA(dst, b, h) do { _Pragma("unroll") for (int m = 0; m < 4; ++m) _Pragma("unroll") for (int k = 0; k < 2; ++k) dst[m][k] = *(const PG8_LAS bf16x8*)(lds + PG8_SA(b, h) + aoff + m * 2048 + k * 1024); } while (0)
; #define PG8_LDB(dst, b, h) do { _Pragma("unroll") for (int n = 0; n < 2; ++n) _Pragma("unroll") for (int k = 0; k < 2; ++k) dst[n][k] = *(const PG8_LAS bf16x8*)(lds + PG8_SB(b, h) + boff + n * 2048 + k * 1024); } while (0)
; #define PG8_MMA(ai, bj, At, Bt) do { __builtin_amdgcn_s_setprio(1); _Pragma("unroll") for (int m = 0; m < 4; ++m) _Pragma("unroll") for (int n = 0; n < 2; ++n) _Pragma("unroll") for (int k = 0; k < 2; ++k) \
;         acc[ai][bj][m][n] = __builtin_amdgcn_mfma_f32_16x16x32_bf16(Bt[n][k], At[m][k], acc[ai][bj][m][n], 0, 0, 0); __builtin_amdgcn_s_setprio(0); } while (0)
; #define PG8_WAIT_V(n) asm volatile("s_waitcnt vmcnt(" #n ")" ::: "memory")
; #define PG8_WAIT_L(n) asm volatile("s_waitcnt lgkmcnt(" #n ")" ::: "memory")
; #define PG8_BAR __builtin_amdgcn_s_barrier()
; #define PG8_SCHED __builtin_amdgcn_sched_barrier(0)
; template <class Epi, class Sched, bool ALIGN_EPI = false, bool SP2 = false>
; __device__ __forceinline__ void gemm_phase(PG8_LAS unsigned char* lds, const Gemm g, const Sched& S, const Epi& E) {
;     ...
;             PG8_LDB(B0, 0, 0); PG8_LDB(B1, 0, 1); PG8_SCHED; PG8_LDA(At, 0, 0); PG8_STAGE(PG8_SA(1, 1), a1 + hstep, voffA);
;             PG8_WAIT_V(8); PG8_WAIT_L(0); PG8_BAR; PG8_MMA(0, 0, At, B0); PG8_MMA(0, 1, At, B1); PG8_BAR; PG8_SCHED;
;             PG8_LDA(At, 0, 1); PG8_STAGE(PG8_SB(0, 0), b2, voffB); PG8_STAGE(PG8_SB(0, 1), b2 + hstep, voffB); PG8_STAGE(PG8_SA(0, 0), a2, voffA);
.LBB0_337:
	ds_read_b128 v[152:155], v148
	ds_read_b128 v[156:159], v148 offset:1024
	ds_read_b128 v[160:163], v148 offset:2048
	ds_read_b128 v[164:167], v148 offset:3072
	ds_read_b128 v[168:171], v149
	ds_read_b128 v[172:175], v149 offset:1024
	ds_read_b128 v[176:179], v149 offset:2048
	ds_read_b128 v[180:183], v149 offset:3072
	s_add_u32 s26, s24, 0xfffc0080
	s_addc_u32 s27, s25, -1
	s_cmp_eq_u32 s54, 12
	s_cselect_b32 s29, s17, s27
	s_cselect_b32 s28, s50, s26
	s_cselect_b32 s27, s15, s53
	s_cselect_b32 s26, s51, s52
	v_lshl_add_u64 v[216:217], s[24:25], 0, v[136:137]
	s_add_i32 m0, s23, 0xc000
	ds_read_b128 v[184:187], v150
	ds_read_b128 v[188:191], v150 offset:1024
	ds_read_b128 v[192:195], v150 offset:2048
	ds_read_b128 v[196:199], v150 offset:3072
	ds_read_b128 v[200:203], v150 offset:4096
	ds_read_b128 v[204:207], v150 offset:5120
	ds_read_b128 v[208:211], v150 offset:6144
	ds_read_b128 v[212:215], v150 offset:7168
	global_load_lds_dwordx4 v[216:217], off
	v_lshl_add_u64 v[216:217], s[24:25], 0, v[138:139]
	s_add_i32 m0, s23, 0xe000
	s_nop 0
	global_load_lds_dwordx4 v[216:217], off
	s_waitcnt vmcnt(8)
	s_waitcnt lgkmcnt(0)
	s_setprio 1
	s_barrier
	v_mfma_f32_16x16x32_bf16 v[124:127], v[152:155], v[184:187], v[124:127]
	v_mfma_f32_16x16x32_bf16 v[120:123], v[160:163], v[184:187], v[120:123]
	v_mfma_f32_16x16x32_bf16 v[108:111], v[152:155], v[192:195], v[108:111]
	v_mfma_f32_16x16x32_bf16 v[104:107], v[160:163], v[192:195], v[104:107]
	v_mfma_f32_16x16x32_bf16 v[92:95], v[152:155], v[200:203], v[92:95]
	v_mfma_f32_16x16x32_bf16 v[88:91], v[160:163], v[200:203], v[88:91]
	v_mfma_f32_16x16x32_bf16 v[76:79], v[152:155], v[208:211], v[76:79]
	v_mfma_f32_16x16x32_bf16 v[72:75], v[160:163], v[208:211], v[72:75]
	v_mfma_f32_16x16x32_bf16 v[124:127], v[156:159], v[188:191], v[124:127]
	v_mfma_f32_16x16x32_bf16 v[120:123], v[164:167], v[188:191], v[120:123]
	v_mfma_f32_16x16x32_bf16 v[108:111], v[156:159], v[196:199], v[108:111]
	v_mfma_f32_16x16x32_bf16 v[104:107], v[164:167], v[196:199], v[104:107]
	v_mfma_f32_16x16x32_bf16 v[92:95], v[156:159], v[204:207], v[92:95]
	v_mfma_f32_16x16x32_bf16 v[88:91], v[164:167], v[204:207], v[88:91]
	v_mfma_f32_16x16x32_bf16 v[76:79], v[156:159], v[212:215], v[76:79]
	v_mfma_f32_16x16x32_bf16 v[72:75], v[164:167], v[212:215], v[72:75]
	v_mfma_f32_16x16x32_bf16 v[116:119], v[168:171], v[184:187], v[116:119]
	v_mfma_f32_16x16x32_bf16 v[112:115], v[176:179], v[184:187], v[112:115]
	v_mfma_f32_16x16x32_bf16 v[100:103], v[168:171], v[192:195], v[100:103]
	v_mfma_f32_16x16x32_bf16 v[96:99], v[176:179], v[192:195], v[96:99]
	v_mfma_f32_16x16x32_bf16 v[84:87], v[168:171], v[200:203], v[84:87]
	v_mfma_f32_16x16x32_bf16 v[80:83], v[176:179], v[200:203], v[80:83]
	v_mfma_f32_16x16x32_bf16 v[68:71], v[168:171], v[208:211], v[68:71]
	v_mfma_f32_16x16x32_bf16 v[64:67], v[176:179], v[208:211], v[64:67]
	v_mfma_f32_16x16x32_bf16 v[116:119], v[172:175], v[188:191], v[116:119]
	v_mfma_f32_16x16x32_bf16 v[112:115], v[180:183], v[188:191], v[112:115]
	v_mfma_f32_16x16x32_bf16 v[100:103], v[172:175], v[196:199], v[100:103]
	v_mfma_f32_16x16x32_bf16 v[96:99], v[180:183], v[196:199], v[96:99]
	v_mfma_f32_16x16x32_bf16 v[84:87], v[172:175], v[204:207], v[84:87]
	v_mfma_f32_16x16x32_bf16 v[80:83], v[180:183], v[204:207], v[80:83]
	v_mfma_f32_16x16x32_bf16 v[68:71], v[172:175], v[212:215], v[68:71]
	v_mfma_f32_16x16x32_bf16 v[64:67], v[180:183], v[212:215], v[64:67]
	s_barrier
	s_setprio 0
	s_add_i32 s55, s44, s33
	v_lshl_add_u64 v[216:217], s[26:27], 0, v[132:133]
	s_mov_b32 m0, s55
	ds_read_b128 v[184:187], v150 offset:16384
	ds_read_b128 v[188:191], v150 offset:17408
	ds_read_b128 v[192:195], v150 offset:18432
	ds_read_b128 v[196:199], v150 offset:19456
	ds_read_b128 v[200:203], v150 offset:20480
	ds_read_b128 v[204:207], v150 offset:21504
	ds_read_b128 v[208:211], v150 offset:22528
	ds_read_b128 v[212:215], v150 offset:23552
	global_load_lds_dwordx4 v[216:217], off
	s_add_i32 m0, s55, 0x2000
	s_add_u32 s56, s26, 0x40000
	v_lshl_add_u64 v[218:219], s[26:27], 0, v[128:129]
	s_addc_u32 s57, s27, 0
	s_add_i32 s55, s45, s33
	global_load_lds_dwordx4 v[218:219], off
	v_lshl_add_u64 v[220:221], s[56:57], 0, v[132:133]
	s_mov_b32 m0, s55
	v_lshl_add_u64 v[222:223], s[28:29], 0, v[130:131]
	global_load_lds_dwordx4 v[220:221], off
	v_lshl_add_u64 v[220:221], s[56:57], 0, v[128:129]
	s_add_i32 m0, s55, 0x2000
	s_nop 0
	global_load_lds_dwordx4 v[220:221], off
	v_lshl_add_u64 v[220:221], s[28:29], 0, v[134:135]
	s_mov_b32 m0, s23
	s_nop 0
	global_load_lds_dwordx4 v[220:221], off
	s_mov_b32 m0, s39
	s_nop 0
	global_load_lds_dwordx4 v[222:223], off
	s_waitcnt vmcnt(8)
	s_waitcnt lgkmcnt(0)
	s_setprio 1
	s_barrier
; #define PG8_STAGE(bufoff, gbase, voff) do { _Pragma("unroll") for (int _i = 0; _i < 2; ++_i) \
;         __builtin_amdgcn_global_load_lds((const unsigned*)((const char*)(gbase) + (voff)[_i]), (PG8_LAS unsigned*)(lds + (bufoff) + ldsw + _i * 8192), 16, 0, 0); } while (0)
; #define PG8_LDA(dst, b, h) do { _Pragma("unroll") for (int m = 0; m < 4; ++m) _Pragma("unroll") for (int k = 0; k < 2; ++k) dst[m][k] = *(const PG8_LAS bf16x8*)(lds + PG8_SA(b, h) + aoff + m * 2048 + k * 1024); } while (0)
; #define PG8_LDB(dst, b, h) do { _Pragma("unroll") for (int n = 0; n < 2; ++n) _Pragma("unroll") for (int k = 0; k < 2; ++k) dst[n][k] = *(const PG8_LAS bf16x8*)(lds + PG8_SB(b, h) + boff + n * 2048 + k * 1024); } while (0)
; #define PG8_MMA(ai, bj, At, Bt) do { __builtin_amdgcn_s_setprio(1); _Pragma("unroll") for (int m = 0; m < 4; ++m) _Pragma("unroll") for (int n = 0; n < 2; ++n) _Pragma("unroll") for (int k = 0; k < 2; ++k) \
;         acc[ai][bj][m][n] = __builtin_amdgcn_mfma_f32_16x16x32_bf16(Bt[n][k], At[m][k], acc[ai][bj][m][n], 0, 0, 0); __builtin_amdgcn_s_setprio(0); } while (0)
; #define PG8_WAIT_V(n) asm volatile("s_waitcnt vmcnt(" #n ")" ::: "memory")
; #define PG8_WAIT_L(n) asm volatile("s_waitcnt lgkmcnt(" #n ")" ::: "memory")
; #define PG8_BAR __builtin_amdgcn_s_barrier()
; #define PG8_SCHED __builtin_amdgcn_sched_barrier(0)
; template <class Epi, class Sched, bool ALIGN_EPI = false, bool SP2 = false>
; __device__ __forceinline__ void gemm_phase(PG8_LAS unsigned char* lds, const Gemm g, const Sched& S, const Epi& E) {
;     ...
;             PG8_WAIT_V(8); PG8_WAIT_L(0); PG8_BAR; PG8_MMA(1, 0, At, B0); PG8_MMA(1, 1, At, B1); PG8_BAR; PG8_SCHED;
;             PG8_LDB(B0, 1, 0); PG8_LDB(B1, 1, 1); PG8_SCHED; PG8_LDA(At, 1, 0); PG8_STAGE(PG8_SA(0, 1), a2 + hstep, voffA);
;             PG8_WAIT_V(8); PG8_WAIT_L(0); PG8_BAR; PG8_MMA(0, 0, At, B0); PG8_MMA(0, 1, At, B1); PG8_BAR; PG8_SCHED;
	v_mfma_f32_16x16x32_bf16 v[60:63], v[152:155], v[184:187], v[60:63]
	v_mfma_f32_16x16x32_bf16 v[56:59], v[160:163], v[184:187], v[56:59]
	v_mfma_f32_16x16x32_bf16 v[44:47], v[152:155], v[192:195], v[44:47]
	v_mfma_f32_16x16x32_bf16 v[40:43], v[160:163], v[192:195], v[40:43]
	v_mfma_f32_16x16x32_bf16 v[28:31], v[152:155], v[200:203], v[28:31]
	v_mfma_f32_16x16x32_bf16 v[24:27], v[160:163], v[200:203], v[24:27]
	v_mfma_f32_16x16x32_bf16 v[12:15], v[152:155], v[208:211], v[12:15]
	v_mfma_f32_16x16x32_bf16 v[8:11], v[160:163], v[208:211], v[8:11]
	v_mfma_f32_16x16x32_bf16 v[60:63], v[156:159], v[188:191], v[60:63]
	v_mfma_f32_16x16x32_bf16 v[56:59], v[164:167], v[188:191], v[56:59]
	v_mfma_f32_16x16x32_bf16 v[44:47], v[156:159], v[196:199], v[44:47]
	v_mfma_f32_16x16x32_bf16 v[40:43], v[164:167], v[196:199], v[40:43]
	v_mfma_f32_16x16x32_bf16 v[28:31], v[156:159], v[204:207], v[28:31]
	v_mfma_f32_16x16x32_bf16 v[24:27], v[164:167], v[204:207], v[24:27]
	v_mfma_f32_16x16x32_bf16 v[12:15], v[156:159], v[212:215], v[12:15]
	v_mfma_f32_16x16x32_bf16 v[8:11], v[164:167], v[212:215], v[8:11]
	v_mfma_f32_16x16x32_bf16 v[52:55], v[168:171], v[184:187], v[52:55]
	v_mfma_f32_16x16x32_bf16 v[48:51], v[176:179], v[184:187], v[48:51]
	v_mfma_f32_16x16x32_bf16 v[36:39], v[168:171], v[192:195], v[36:39]
	v_mfma_f32_16x16x32_bf16 v[32:35], v[176:179], v[192:195], v[32:35]
	v_mfma_f32_16x16x32_bf16 v[20:23], v[168:171], v[200:203], v[20:23]
	v_mfma_f32_16x16x32_bf16 v[16:19], v[176:179], v[200:203], v[16:19]
	v_mfma_f32_16x16x32_bf16 v[4:7], v[168:171], v[208:211], v[4:7]
	v_mfma_f32_16x16x32_bf16 v[0:3], v[176:179], v[208:211], v[0:3]
	v_mfma_f32_16x16x32_bf16 v[52:55], v[172:175], v[188:191], v[52:55]
	v_mfma_f32_16x16x32_bf16 v[48:51], v[180:183], v[188:191], v[48:51]
	v_mfma_f32_16x16x32_bf16 v[36:39], v[172:175], v[196:199], v[36:39]
	v_mfma_f32_16x16x32_bf16 v[32:35], v[180:183], v[196:199], v[32:35]
	v_mfma_f32_16x16x32_bf16 v[20:23], v[172:175], v[204:207], v[20:23]
	v_mfma_f32_16x16x32_bf16 v[16:19], v[180:183], v[204:207], v[16:19]
	v_mfma_f32_16x16x32_bf16 v[4:7], v[172:175], v[212:215], v[4:7]
	v_mfma_f32_16x16x32_bf16 v[0:3], v[180:183], v[212:215], v[0:3]
	s_barrier
	s_setprio 0
	s_add_i32 s55, 0, 0x18000
	v_add_u32_e32 v151, s55, v145
	s_add_i32 s56, 0, 0x1c000
	ds_read_b128 v[152:155], v151
	ds_read_b128 v[156:159], v151 offset:1024
	ds_read_b128 v[160:163], v151 offset:2048
	ds_read_b128 v[164:167], v151 offset:3072
	v_add_u32_e32 v151, s56, v145
	ds_read_b128 v[168:171], v151
	ds_read_b128 v[172:175], v151 offset:1024
	ds_read_b128 v[176:179], v151 offset:2048
	ds_read_b128 v[180:183], v151 offset:3072
	s_add_u32 s28, s28, 0x40000
	s_addc_u32 s29, s29, 0
	s_mov_b32 m0, s40
	v_lshl_add_u64 v[224:225], s[28:29], 0, v[134:135]
	ds_read_b128 v[184:187], v150 offset:32768
	ds_read_b128 v[188:191], v150 offset:33792
	ds_read_b128 v[192:195], v150 offset:34816
	ds_read_b128 v[196:199], v150 offset:35840
	ds_read_b128 v[200:203], v150 offset:36864
	ds_read_b128 v[204:207], v150 offset:37888
	ds_read_b128 v[208:211], v150 offset:38912
	ds_read_b128 v[212:215], v150 offset:39936
	global_load_lds_dwordx4 v[224:225], off
	v_lshl_add_u64 v[224:225], s[28:29], 0, v[130:131]
	s_mov_b32 m0, s41
	s_nop 0
	global_load_lds_dwordx4 v[224:225], off
	s_waitcnt vmcnt(8)
	s_waitcnt lgkmcnt(0)
	s_setprio 1
	s_barrier
	v_mfma_f32_16x16x32_bf16 v[124:127], v[152:155], v[184:187], v[124:127]
	v_mfma_f32_16x16x32_bf16 v[120:123], v[160:163], v[184:187], v[120:123]
	v_mfma_f32_16x16x32_bf16 v[108:111], v[152:155], v[192:195], v[108:111]
	v_mfma_f32_16x16x32_bf16 v[104:107], v[160:163], v[192:195], v[104:107]
	v_mfma_f32_16x16x32_bf16 v[92:95], v[152:155], v[200:203], v[92:95]
	v_mfma_f32_16x16x32_bf16 v[88:91], v[160:163], v[200:203], v[88:91]
	v_mfma_f32_16x16x32_bf16 v[76:79], v[152:155], v[208:211], v[76:79]
	v_mfma_f32_16x16x32_bf16 v[72:75], v[160:163], v[208:211], v[72:75]
	v_mfma_f32_16x16x32_bf16 v[124:127], v[156:159], v[188:191], v[124:127]
	v_mfma_f32_16x16x32_bf16 v[120:123], v[164:167], v[188:191], v[120:123]
	v_mfma_f32_16x16x32_bf16 v[108:111], v[156:159], v[196:199], v[108:111]
	v_mfma_f32_16x16x32_bf16 v[104:107], v[164:167], v[196:199], v[104:107]
	v_mfma_f32_16x16x32_bf16 v[92:95], v[156:159], v[204:207], v[92:95]
	v_mfma_f32_16x16x32_bf16 v[88:91], v[164:167], v[204:207], v[88:91]
	v_mfma_f32_16x16x32_bf16 v[76:79], v[156:159], v[212:215], v[76:79]
	v_mfma_f32_16x16x32_bf16 v[72:75], v[164:167], v[212:215], v[72:75]
	v_mfma_f32_16x16x32_bf16 v[116:119], v[168:171], v[184:187], v[116:119]
	v_mfma_f32_16x16x32_bf16 v[112:115], v[176:179], v[184:187], v[112:115]
	v_mfma_f32_16x16x32_bf16 v[100:103], v[168:171], v[192:195], v[100:103]
	v_mfma_f32_16x16x32_bf16 v[96:99], v[176:179], v[192:195], v[96:99]
	v_mfma_f32_16x16x32_bf16 v[84:87], v[168:171], v[200:203], v[84:87]
	v_mfma_f32_16x16x32_bf16 v[80:83], v[176:179], v[200:203], v[80:83]
	v_mfma_f32_16x16x32_bf16 v[68:71], v[168:171], v[208:211], v[68:71]
	v_mfma_f32_16x16x32_bf16 v[64:67], v[176:179], v[208:211], v[64:67]
	v_mfma_f32_16x16x32_bf16 v[116:119], v[172:175], v[188:191], v[116:119]
	v_mfma_f32_16x16x32_bf16 v[112:115], v[180:183], v[188:191], v[112:115]
	v_mfma_f32_16x16x32_bf16 v[100:103], v[172:175], v[196:199], v[100:103]
	v_mfma_f32_16x16x32_bf16 v[96:99], v[180:183], v[196:199], v[96:99]
	v_mfma_f32_16x16x32_bf16 v[84:87], v[172:175], v[204:207], v[84:87]
	v_mfma_f32_16x16x32_bf16 v[80:83], v[180:183], v[204:207], v[80:83]
	v_mfma_f32_16x16x32_bf16 v[68:71], v[172:175], v[212:215], v[68:71]
	v_mfma_f32_16x16x32_bf16 v[64:67], v[180:183], v[212:215], v[64:67]
	s_barrier
; #define PG8_STAGE(bufoff, gbase, voff) do { _Pragma("unroll") for (int _i = 0; _i < 2; ++_i) \
;         __builtin_amdgcn_global_load_lds((const unsigned*)((const char*)(gbase) + (voff)[_i]), (PG8_LAS unsigned*)(lds + (bufoff) + ldsw + _i * 8192), 16, 0, 0); } while (0)
; #define PG8_LDA(dst, b, h) do { _Pragma("unroll") for (int m = 0; m < 4; ++m) _Pragma("unroll") for (int k = 0; k < 2; ++k) dst[m][k] = *(const PG8_LAS bf16x8*)(lds + PG8_SA(b, h) + aoff + m * 2048 + k * 1024); } while (0)
; #define PG8_WAIT_V(n) asm volatile("s_waitcnt vmcnt(" #n ")" ::: "memory")
; template <class Epi, class Sched, bool ALIGN_EPI = false, bool SP2 = false>
; __device__ __forceinline__ void gemm_phase(PG8_LAS unsigned char* lds, const Gemm g, const Sched& S, const Epi& E) {
;     ...
;             PG8_LDA(At, 1, 1); PG8_STAGE(PG8_SB(1, 0), b3, voffB); PG8_STAGE(PG8_SB(1, 1), b3 + hstep, voffB); PG8_STAGE(PG8_SA(1, 0), a3, voffA);
;             PG8_WAIT_V(8); PG8_WAIT_L(0); PG8_BAR; PG8_MMA(1, 0, At, B0); PG8_MMA(1, 1, At, B1); PG8_BAR; PG8_SCHED;
;             } else {
;             PG8_LDB(B0, 0, 0); PG8_SCHED; PG8_LDA(At, 0, 0); PG8_STAGE(PG8_SA(1, 1), a1 + hstep, voffA);
;             PG8_WAIT_L(8); PG8_BAR; PG8_WAIT_L(0); PG8_MMA(0, 0, At, B0); PG8_BAR; PG8_SCHED;
;             PG8_LDB(B1, 0, 1); PG8_STAGE(PG8_SB(0, 0), b2, voffB);
;             PG8_BAR; PG8_WAIT_L(0); PG8_MMA(0, 1, At, B1); PG8_BAR;
;             PG8_LDA(At, 0, 1); PG8_STAGE(PG8_SA(0, 0), a2, voffA);
;             PG8_BAR; PG8_WAIT_L(0); PG8_MMA(1, 0, At, B0); PG8_BAR; PG8_SCHED;
;             PG8_STAGE(PG8_SB(0, 1), b2 + hstep, voffB);
;             PG8_WAIT_V(6); PG8_BAR; PG8_MMA(1, 1, At, B1); PG8_BAR;
;             PG8_LDB(B0, 1, 0); PG8_SCHED; PG8_LDA(At, 1, 0); PG8_STAGE(PG8_SA(0, 1), a2 + hstep, voffA);
;             PG8_WAIT_L(8); PG8_BAR; PG8_WAIT_L(0); PG8_MMA(0, 0, At, B0); PG8_BAR; PG8_SCHED;
;             PG8_LDB(B1, 1, 1); PG8_STAGE(PG8_SB(1, 0), b3, voffB);
;             PG8_BAR; PG8_WAIT_L(0); PG8_MMA(0, 1, At, B1); PG8_BAR;
;             PG8_LDA(At, 1, 1); PG8_STAGE(PG8_SA(1, 0), a3, voffA);
;             PG8_BAR; PG8_WAIT_L(0); PG8_MMA(1, 0, At, B0); PG8_BAR; PG8_SCHED;
;             PG8_STAGE(PG8_SB(1, 1), b3 + hstep, voffB);
;             PG8_WAIT_V(6); PG8_BAR; PG8_MMA(1, 1, At, B1); PG8_BAR;
;             }
;         }
;         if constexpr (ALIGN_EPI) { if (wr == 0) PG8_BAR; }
	s_setprio 0
	s_add_i32 s28, s55, s33
	v_lshl_add_u64 v[216:217], v[216:217], 0, s[8:9]
	s_mov_b32 m0, s28
	ds_read_b128 v[184:187], v150 offset:49152
	ds_read_b128 v[188:191], v150 offset:50176
	ds_read_b128 v[192:195], v150 offset:51200
	ds_read_b128 v[196:199], v150 offset:52224
	ds_read_b128 v[200:203], v150 offset:53248
	ds_read_b128 v[204:207], v150 offset:54272
	ds_read_b128 v[208:211], v150 offset:55296
	ds_read_b128 v[212:215], v150 offset:56320
	global_load_lds_dwordx4 v[216:217], off
	s_add_i32 m0, s28, 0x2000
	s_add_u32 s26, s26, 0x40080
	v_lshl_add_u64 v[216:217], v[218:219], 0, s[8:9]
	s_addc_u32 s27, s27, 0
	s_add_i32 s28, s56, s33
	global_load_lds_dwordx4 v[216:217], off
	v_lshl_add_u64 v[216:217], s[26:27], 0, v[132:133]
	s_mov_b32 m0, s28
	s_nop 0
	global_load_lds_dwordx4 v[216:217], off
	v_lshl_add_u64 v[216:217], s[26:27], 0, v[128:129]
	s_add_i32 m0, s28, 0x2000
	s_nop 0
	global_load_lds_dwordx4 v[216:217], off
	v_lshl_add_u64 v[216:217], v[220:221], 0, s[8:9]
	s_mov_b32 m0, s42
	s_nop 0
	global_load_lds_dwordx4 v[216:217], off
	v_lshl_add_u64 v[216:217], v[222:223], 0, s[8:9]
	s_mov_b32 m0, s43
	s_nop 0
	global_load_lds_dwordx4 v[216:217], off
	s_waitcnt vmcnt(8)
	s_waitcnt lgkmcnt(0)
	s_setprio 1
	s_barrier
	v_mfma_f32_16x16x32_bf16 v[60:63], v[152:155], v[184:187], v[60:63]
	v_mfma_f32_16x16x32_bf16 v[56:59], v[160:163], v[184:187], v[56:59]
	v_mfma_f32_16x16x32_bf16 v[44:47], v[152:155], v[192:195], v[44:47]
	v_mfma_f32_16x16x32_bf16 v[40:43], v[160:163], v[192:195], v[40:43]
	v_mfma_f32_16x16x32_bf16 v[28:31], v[152:155], v[200:203], v[28:31]
	v_mfma_f32_16x16x32_bf16 v[24:27], v[160:163], v[200:203], v[24:27]
	v_mfma_f32_16x16x32_bf16 v[12:15], v[152:155], v[208:211], v[12:15]
	v_mfma_f32_16x16x32_bf16 v[8:11], v[160:163], v[208:211], v[8:11]
	v_mfma_f32_16x16x32_bf16 v[60:63], v[156:159], v[188:191], v[60:63]
	v_mfma_f32_16x16x32_bf16 v[56:59], v[164:167], v[188:191], v[56:59]
	v_mfma_f32_16x16x32_bf16 v[44:47], v[156:159], v[196:199], v[44:47]
	v_mfma_f32_16x16x32_bf16 v[40:43], v[164:167], v[196:199], v[40:43]
	v_mfma_f32_16x16x32_bf16 v[28:31], v[156:159], v[204:207], v[28:31]
	v_mfma_f32_16x16x32_bf16 v[24:27], v[164:167], v[204:207], v[24:27]
	v_mfma_f32_16x16x32_bf16 v[12:15], v[156:159], v[212:215], v[12:15]
	v_mfma_f32_16x16x32_bf16 v[8:11], v[164:167], v[212:215], v[8:11]
	v_mfma_f32_16x16x32_bf16 v[52:55], v[168:171], v[184:187], v[52:55]
	v_mfma_f32_16x16x32_bf16 v[48:51], v[176:179], v[184:187], v[48:51]
	v_mfma_f32_16x16x32_bf16 v[36:39], v[168:171], v[192:195], v[36:39]
	v_mfma_f32_16x16x32_bf16 v[32:35], v[176:179], v[192:195], v[32:35]
	v_mfma_f32_16x16x32_bf16 v[20:23], v[168:171], v[200:203], v[20:23]
	v_mfma_f32_16x16x32_bf16 v[16:19], v[176:179], v[200:203], v[16:19]
	v_mfma_f32_16x16x32_bf16 v[4:7], v[168:171], v[208:211], v[4:7]
	v_mfma_f32_16x16x32_bf16 v[0:3], v[176:179], v[208:211], v[0:3]
	v_mfma_f32_16x16x32_bf16 v[52:55], v[172:175], v[188:191], v[52:55]
	v_mfma_f32_16x16x32_bf16 v[48:51], v[180:183], v[188:191], v[48:51]
	v_mfma_f32_16x16x32_bf16 v[36:39], v[172:175], v[196:199], v[36:39]
	v_mfma_f32_16x16x32_bf16 v[32:35], v[180:183], v[196:199], v[32:35]
	v_mfma_f32_16x16x32_bf16 v[20:23], v[172:175], v[204:207], v[20:23]
	v_mfma_f32_16x16x32_bf16 v[16:19], v[180:183], v[204:207], v[16:19]
	v_mfma_f32_16x16x32_bf16 v[4:7], v[172:175], v[212:215], v[4:7]
	v_mfma_f32_16x16x32_bf16 v[0:3], v[180:183], v[212:215], v[0:3]
	s_barrier
	s_setprio 0
	s_add_i32 s54, s54, 2
	s_add_u32 s24, s24, 0x100
	s_addc_u32 s25, s25, 0
	s_add_u32 s52, s52, 0x100
	s_addc_u32 s53, s53, 0
	s_cmp_gt_u32 s54, 13
	s_cbranch_scc0 .LBB0_337
	s_and_b64 vcc, exec, s[12:13]
	s_cbranch_vccz .LBB0_340
	s_barrier

; #define PG8_STAGE(bufoff, gbase, voff) do { _Pragma("unroll") for (int _i = 0; _i < 2; ++_i) \
;         __builtin_amdgcn_global_load_lds((const unsigned*)((const char*)(gbase) + (voff)[_i]), (PG8_LAS unsigned*)(lds + (bufoff) + ldsw + _i * 8192), 16, 0, 0); } while (0)
; #define PG8_LDA(dst, b, h) do { _Pragma("unroll") for (int m = 0; m < 4; ++m) _Pragma("unroll") for (int k = 0; k < 2; ++k) dst[m][k] = *(const PG8_LAS bf16x8*)(lds + PG8_SA(b, h) + aoff + m * 2048 + k * 1024); } while (0)
; #define PG8_LDB(dst, b, h) do { _Pragma("unroll") for (int n = 0; n < 2; ++n) _Pragma("unroll") for (int k = 0; k < 2; ++k) dst[n][k] = *(const PG8_LAS bf16x8*)(lds + PG8_SB(b, h) + boff + n * 2048 + k * 1024); } while (0)
; #define PG8_WAIT_V(n) asm volatile("s_waitcnt vmcnt(" #n ")" ::: "memory")
; #define PG8_WAIT_L(n) asm volatile("s_waitcnt lgkmcnt(" #n ")" ::: "memory")
; #define PG8_BAR __builtin_amdgcn_s_barrier()
; #define PG8_SCHED __builtin_amdgcn_sched_barrier(0)
; template <class Epi, class Sched, bool ALIGN_EPI = false, bool SP2 = false>
; __device__ __forceinline__ void gemm_phase(PG8_LAS unsigned char* lds, const Gemm g, const Sched& S, const Epi& E) {
;     ...
;         const char* nA = has_next ? (const char*)g.A + (size_t)nxt.pm * tstep : cA; const char* nB = has_next ? (const char*)g.Bt + (size_t)nxt.pn * tstep : cB;
;         for (int t = 0; t < nt; t += 2) {
;             const bool last = (t == nt - 2);
;             const char* a1 = cA + (size_t)(t + 1) * kstep;
;             const char* a2 = last ? nA : cA + (size_t)(t + 2) * kstep; const char* b2 = last ? nB : cB + (size_t)(t + 2) * kstep;
;             const char* a3 = a2 + kstep; const char* b3 = b2 + kstep;
;             if (last && has_next) S.a_ready(nxt, ui + 1);
;             if constexpr (SP2) {
;             PG8_LDB(B0, 0, 0); PG8_LDB(B1, 0, 1); PG8_SCHED; PG8_LDA(At, 0, 0); PG8_STAGE(PG8_SA(1, 1), a1 + hstep, voffA);
;             PG8_WAIT_V(8); PG8_WAIT_L(0); PG8_BAR; PG8_MMA(0, 0, At, B0); PG8_MMA(0, 1, At, B1); PG8_BAR; PG8_SCHED;
;             PG8_LDA(At, 0, 1); PG8_STAGE(PG8_SB(0, 0), b2, voffB); PG8_STAGE(PG8_SB(0, 1), b2 + hstep, voffB); PG8_STAGE(PG8_SA(0, 0), a2, voffA);
;             PG8_WAIT_V(8); PG8_WAIT_L(0); PG8_BAR; PG8_MMA(1, 0, At, B0); PG8_MMA(1, 1, At, B1); PG8_BAR; PG8_SCHED;
.LBB0_417:
	s_add_u32 s24, s24, 0xb0080
	s_addc_u32 s25, s25, 0
	s_add_u32 s51, s26, 0x100
	s_addc_u32 s52, s27, 0
	s_mov_b32 s53, -2
	s_waitcnt lgkmcnt(0)
	s_add_u32 s26, s24, 0xfff50080
	s_addc_u32 s27, s25, -1
	s_cmp_eq_u32 s53, 40
	s_cselect_b32 s29, s7, s27
	s_cselect_b32 s28, s6, s26
	s_cselect_b32 s27, s23, s52
	s_cselect_b32 s26, s22, s51
	v_lshl_add_u64 v[204:205], s[24:25], 0, v[200:201]
	s_add_i32 m0, s35, 0xc000
	global_load_lds_dwordx4 v[204:205], off
	v_lshl_add_u64 v[204:205], s[24:25], 0, v[202:203]
	s_add_i32 m0, s35, 0xe000
	s_nop 0
	global_load_lds_dwordx4 v[204:205], off
	s_waitcnt vmcnt(8)
	s_waitcnt lgkmcnt(0)
	s_setprio 1
	s_barrier
	v_mfma_f32_16x16x32_bf16 v[132:135], v[120:123], v[160:163], 0
	v_mfma_f32_16x16x32_bf16 v[124:127], v[136:139], v[160:163], 0
	v_mfma_f32_16x16x32_bf16 v[108:111], v[120:123], v[168:171], 0
	v_mfma_f32_16x16x32_bf16 v[104:107], v[136:139], v[168:171], 0
	v_mfma_f32_16x16x32_bf16 v[92:95], v[120:123], v[176:179], 0
	v_mfma_f32_16x16x32_bf16 v[88:91], v[136:139], v[176:179], 0
	v_mfma_f32_16x16x32_bf16 v[76:79], v[120:123], v[184:187], 0
	v_mfma_f32_16x16x32_bf16 v[72:75], v[136:139], v[184:187], 0
	v_mfma_f32_16x16x32_bf16 v[132:135], v[128:131], v[164:167], v[132:135]
	v_mfma_f32_16x16x32_bf16 v[124:127], v[140:143], v[164:167], v[124:127]
	v_mfma_f32_16x16x32_bf16 v[108:111], v[128:131], v[172:175], v[108:111]
	v_mfma_f32_16x16x32_bf16 v[104:107], v[140:143], v[172:175], v[104:107]
	v_mfma_f32_16x16x32_bf16 v[92:95], v[128:131], v[180:183], v[92:95]
	v_mfma_f32_16x16x32_bf16 v[88:91], v[140:143], v[180:183], v[88:91]
	v_mfma_f32_16x16x32_bf16 v[76:79], v[128:131], v[188:191], v[76:79]
	v_mfma_f32_16x16x32_bf16 v[72:75], v[140:143], v[188:191], v[72:75]
	v_mfma_f32_16x16x32_bf16 v[116:119], v[144:147], v[160:163], 0
	v_mfma_f32_16x16x32_bf16 v[112:115], v[152:155], v[160:163], 0
	v_mfma_f32_16x16x32_bf16 v[100:103], v[144:147], v[168:171], 0
	v_mfma_f32_16x16x32_bf16 v[96:99], v[152:155], v[168:171], 0
	v_mfma_f32_16x16x32_bf16 v[84:87], v[144:147], v[176:179], 0
	v_mfma_f32_16x16x32_bf16 v[80:83], v[152:155], v[176:179], 0
	v_mfma_f32_16x16x32_bf16 v[68:71], v[144:147], v[184:187], 0
	v_mfma_f32_16x16x32_bf16 v[64:67], v[152:155], v[184:187], 0
	v_mfma_f32_16x16x32_bf16 v[116:119], v[148:151], v[164:167], v[116:119]
	v_mfma_f32_16x16x32_bf16 v[112:115], v[156:159], v[164:167], v[112:115]
	v_mfma_f32_16x16x32_bf16 v[100:103], v[148:151], v[172:175], v[100:103]
	v_mfma_f32_16x16x32_bf16 v[96:99], v[156:159], v[172:175], v[96:99]
	v_mfma_f32_16x16x32_bf16 v[84:87], v[148:151], v[180:183], v[84:87]
	v_mfma_f32_16x16x32_bf16 v[80:83], v[156:159], v[180:183], v[80:83]
	v_mfma_f32_16x16x32_bf16 v[68:71], v[148:151], v[188:191], v[68:71]
	v_mfma_f32_16x16x32_bf16 v[64:67], v[156:159], v[188:191], v[64:67]
	s_barrier
	s_setprio 0
	s_add_i32 s54, s45, s34
	v_lshl_add_u64 v[204:205], s[26:27], 0, v[194:195]
	s_mov_b32 m0, s54
	ds_read_b128 v[160:163], v247 offset:16384
	ds_read_b128 v[164:167], v247 offset:17408
	ds_read_b128 v[168:171], v247 offset:18432
	ds_read_b128 v[172:175], v247 offset:19456
	ds_read_b128 v[176:179], v247 offset:20480
	ds_read_b128 v[180:183], v247 offset:21504
	ds_read_b128 v[184:187], v247 offset:22528
	ds_read_b128 v[188:191], v247 offset:23552
	global_load_lds_dwordx4 v[204:205], off
	s_add_i32 m0, s54, 0x2000
	s_add_u32 s54, s26, 0xb0000
	v_lshl_add_u64 v[206:207], s[26:27], 0, v[198:199]
	s_addc_u32 s55, s27, 0
	s_add_i32 s56, s46, s34
	global_load_lds_dwordx4 v[206:207], off
	v_lshl_add_u64 v[208:209], s[54:55], 0, v[194:195]
	s_mov_b32 m0, s56
	v_lshl_add_u64 v[210:211], s[28:29], 0, v[196:197]
	global_load_lds_dwordx4 v[208:209], off
	v_lshl_add_u64 v[208:209], s[54:55], 0, v[198:199]
	s_add_i32 m0, s56, 0x2000
	s_nop 0
	global_load_lds_dwordx4 v[208:209], off
	v_lshl_add_u64 v[208:209], s[28:29], 0, v[192:193]
	s_mov_b32 m0, s35
	s_nop 0
	global_load_lds_dwordx4 v[208:209], off
	s_mov_b32 m0, s36
	s_nop 0
	global_load_lds_dwordx4 v[210:211], off
	s_waitcnt vmcnt(8)
	s_waitcnt lgkmcnt(0)
	s_setprio 1
	s_barrier
	v_mfma_f32_16x16x32_bf16 v[60:63], v[120:123], v[160:163], 0
	v_mfma_f32_16x16x32_bf16 v[56:59], v[136:139], v[160:163], 0
	v_mfma_f32_16x16x32_bf16 v[44:47], v[120:123], v[168:171], 0
	v_mfma_f32_16x16x32_bf16 v[40:43], v[136:139], v[168:171], 0
	v_mfma_f32_16x16x32_bf16 v[28:31], v[120:123], v[176:179], 0
	v_mfma_f32_16x16x32_bf16 v[24:27], v[136:139], v[176:179], 0
	v_mfma_f32_16x16x32_bf16 v[12:15], v[120:123], v[184:187], 0
	v_mfma_f32_16x16x32_bf16 v[8:11], v[136:139], v[184:187], 0
	v_mfma_f32_16x16x32_bf16 v[60:63], v[128:131], v[164:167], v[60:63]
	v_mfma_f32_16x16x32_bf16 v[56:59], v[140:143], v[164:167], v[56:59]
	v_mfma_f32_16x16x32_bf16 v[44:47], v[128:131], v[172:175], v[44:47]
	v_mfma_f32_16x16x32_bf16 v[40:43], v[140:143], v[172:175], v[40:43]
	v_mfma_f32_16x16x32_bf16 v[28:31], v[128:131], v[180:183], v[28:31]
	v_mfma_f32_16x16x32_bf16 v[24:27], v[140:143], v[180:183], v[24:27]
	v_mfma_f32_16x16x32_bf16 v[12:15], v[128:131], v[188:191], v[12:15]
	v_mfma_f32_16x16x32_bf16 v[8:11], v[140:143], v[188:191], v[8:11]
	v_mfma_f32_16x16x32_bf16 v[52:55], v[144:147], v[160:163], 0
	v_mfma_f32_16x16x32_bf16 v[48:51], v[152:155], v[160:163], 0
	v_mfma_f32_16x16x32_bf16 v[36:39], v[144:147], v[168:171], 0
	v_mfma_f32_16x16x32_bf16 v[32:35], v[152:155], v[168:171], 0
	v_mfma_f32_16x16x32_bf16 v[20:23], v[144:147], v[176:179], 0
	v_mfma_f32_16x16x32_bf16 v[16:19], v[152:155], v[176:179], 0
	v_mfma_f32_16x16x32_bf16 v[4:7], v[144:147], v[184:187], 0
	v_mfma_f32_16x16x32_bf16 v[0:3], v[152:155], v[184:187], 0
	v_mfma_f32_16x16x32_bf16 v[52:55], v[148:151], v[164:167], v[52:55]
	v_mfma_f32_16x16x32_bf16 v[48:51], v[156:159], v[164:167], v[48:51]
	v_mfma_f32_16x16x32_bf16 v[36:39], v[148:151], v[172:175], v[36:39]
	v_mfma_f32_16x16x32_bf16 v[32:35], v[156:159], v[172:175], v[32:35]
	v_mfma_f32_16x16x32_bf16 v[20:23], v[148:151], v[180:183], v[20:23]
	v_mfma_f32_16x16x32_bf16 v[16:19], v[156:159], v[180:183], v[16:19]
	v_mfma_f32_16x16x32_bf16 v[4:7], v[148:151], v[188:191], v[4:7]
	v_mfma_f32_16x16x32_bf16 v[0:3], v[156:159], v[188:191], v[0:3]
	s_barrier
; #define PG8_STAGE(bufoff, gbase, voff) do { _Pragma("unroll") for (int _i = 0; _i < 2; ++_i) \
;         __builtin_amdgcn_global_load_lds((const unsigned*)((const char*)(gbase) + (voff)[_i]), (PG8_LAS unsigned*)(lds + (bufoff) + ldsw + _i * 8192), 16, 0, 0); } while (0)
; #define PG8_LDA(dst, b, h) do { _Pragma("unroll") for (int m = 0; m < 4; ++m) _Pragma("unroll") for (int k = 0; k < 2; ++k) dst[m][k] = *(const PG8_LAS bf16x8*)(lds + PG8_SA(b, h) + aoff + m * 2048 + k * 1024); } while (0)
; #define PG8_LDB(dst, b, h) do { _Pragma("unroll") for (int n = 0; n < 2; ++n) _Pragma("unroll") for (int k = 0; k < 2; ++k) dst[n][k] = *(const PG8_LAS bf16x8*)(lds + PG8_SB(b, h) + boff + n * 2048 + k * 1024); } while (0)
; #define PG8_MMA(ai, bj, At, Bt) do { __builtin_amdgcn_s_setprio(1); _Pragma("unroll") for (int m = 0; m < 4; ++m) _Pragma("unroll") for (int n = 0; n < 2; ++n) _Pragma("unroll") for (int k = 0; k < 2; ++k) \
;         acc[ai][bj][m][n] = __builtin_amdgcn_mfma_f32_16x16x32_bf16(Bt[n][k], At[m][k], acc[ai][bj][m][n], 0, 0, 0); __builtin_amdgcn_s_setprio(0); } while (0)
; #define PG8_WAIT_V(n) asm volatile("s_waitcnt vmcnt(" #n ")" ::: "memory")
; #define PG8_WAIT_L(n) asm volatile("s_waitcnt lgkmcnt(" #n ")" ::: "memory")
; #define PG8_BAR __builtin_amdgcn_s_barrier()
; #define PG8_SCHED __builtin_amdgcn_sched_barrier(0)
; template <class Epi, class Sched, bool ALIGN_EPI = false, bool SP2 = false>
; __device__ __forceinline__ void gemm_phase(PG8_LAS unsigned char* lds, const Gemm g, const Sched& S, const Epi& E) {
;     ...
;             PG8_LDB(B0, 1, 0); PG8_LDB(B1, 1, 1); PG8_SCHED; PG8_LDA(At, 1, 0); PG8_STAGE(PG8_SA(0, 1), a2 + hstep, voffA);
;             PG8_WAIT_V(8); PG8_WAIT_L(0); PG8_BAR; PG8_MMA(0, 0, At, B0); PG8_MMA(0, 1, At, B1); PG8_BAR; PG8_SCHED;
;             PG8_LDA(At, 1, 1); PG8_STAGE(PG8_SB(1, 0), b3, voffB); PG8_STAGE(PG8_SB(1, 1), b3 + hstep, voffB); PG8_STAGE(PG8_SA(1, 0), a3, voffA);
;             PG8_WAIT_V(8); PG8_WAIT_L(0); PG8_BAR; PG8_MMA(1, 0, At, B0); PG8_MMA(1, 1, At, B1); PG8_BAR; PG8_SCHED;
	s_setprio 0
	s_add_i32 s54, 0, 0x18000
	s_add_i32 s55, 0, 0x1c000
	v_add_u32_e32 v140, s54, v243
	v_add_u32_e32 v156, s55, v243
	ds_read_b128 v[120:123], v140
	ds_read_b128 v[128:131], v140 offset:1024
	ds_read_b128 v[136:139], v140 offset:2048
	ds_read_b128 v[140:143], v140 offset:3072
	ds_read_b128 v[144:147], v156
	ds_read_b128 v[148:151], v156 offset:1024
	ds_read_b128 v[152:155], v156 offset:2048
	ds_read_b128 v[156:159], v156 offset:3072
	s_add_u32 s28, s28, 0xb0000
	s_addc_u32 s29, s29, 0
	s_mov_b32 m0, s37
	v_lshl_add_u64 v[212:213], s[28:29], 0, v[192:193]
	ds_read_b128 v[160:163], v247 offset:32768
	ds_read_b128 v[164:167], v247 offset:33792
	ds_read_b128 v[168:171], v247 offset:34816
	ds_read_b128 v[172:175], v247 offset:35840
	ds_read_b128 v[176:179], v247 offset:36864
	ds_read_b128 v[180:183], v247 offset:37888
	ds_read_b128 v[184:187], v247 offset:38912
	ds_read_b128 v[188:191], v247 offset:39936
	global_load_lds_dwordx4 v[212:213], off
	v_lshl_add_u64 v[212:213], s[28:29], 0, v[196:197]
	s_mov_b32 m0, s38
	s_nop 0
	global_load_lds_dwordx4 v[212:213], off
	s_waitcnt vmcnt(8)
	s_waitcnt lgkmcnt(0)
	s_setprio 1
	s_barrier
	v_mfma_f32_16x16x32_bf16 v[132:135], v[120:123], v[160:163], v[132:135]
	v_mfma_f32_16x16x32_bf16 v[124:127], v[136:139], v[160:163], v[124:127]
	v_mfma_f32_16x16x32_bf16 v[108:111], v[120:123], v[168:171], v[108:111]
	v_mfma_f32_16x16x32_bf16 v[104:107], v[136:139], v[168:171], v[104:107]
	v_mfma_f32_16x16x32_bf16 v[92:95], v[120:123], v[176:179], v[92:95]
	v_mfma_f32_16x16x32_bf16 v[88:91], v[136:139], v[176:179], v[88:91]
	v_mfma_f32_16x16x32_bf16 v[76:79], v[120:123], v[184:187], v[76:79]
	v_mfma_f32_16x16x32_bf16 v[72:75], v[136:139], v[184:187], v[72:75]
	v_mfma_f32_16x16x32_bf16 v[132:135], v[128:131], v[164:167], v[132:135]
	v_mfma_f32_16x16x32_bf16 v[124:127], v[140:143], v[164:167], v[124:127]
	v_mfma_f32_16x16x32_bf16 v[108:111], v[128:131], v[172:175], v[108:111]
	v_mfma_f32_16x16x32_bf16 v[104:107], v[140:143], v[172:175], v[104:107]
	v_mfma_f32_16x16x32_bf16 v[92:95], v[128:131], v[180:183], v[92:95]
	v_mfma_f32_16x16x32_bf16 v[88:91], v[140:143], v[180:183], v[88:91]
	v_mfma_f32_16x16x32_bf16 v[76:79], v[128:131], v[188:191], v[76:79]
	v_mfma_f32_16x16x32_bf16 v[72:75], v[140:143], v[188:191], v[72:75]
	v_mfma_f32_16x16x32_bf16 v[116:119], v[144:147], v[160:163], v[116:119]
	v_mfma_f32_16x16x32_bf16 v[112:115], v[152:155], v[160:163], v[112:115]
	v_mfma_f32_16x16x32_bf16 v[100:103], v[144:147], v[168:171], v[100:103]
	v_mfma_f32_16x16x32_bf16 v[96:99], v[152:155], v[168:171], v[96:99]
	v_mfma_f32_16x16x32_bf16 v[84:87], v[144:147], v[176:179], v[84:87]
	v_mfma_f32_16x16x32_bf16 v[80:83], v[152:155], v[176:179], v[80:83]
	v_mfma_f32_16x16x32_bf16 v[68:71], v[144:147], v[184:187], v[68:71]
	v_mfma_f32_16x16x32_bf16 v[64:67], v[152:155], v[184:187], v[64:67]
	v_mfma_f32_16x16x32_bf16 v[116:119], v[148:151], v[164:167], v[116:119]
	v_mfma_f32_16x16x32_bf16 v[112:115], v[156:159], v[164:167], v[112:115]
	v_mfma_f32_16x16x32_bf16 v[100:103], v[148:151], v[172:175], v[100:103]
	v_mfma_f32_16x16x32_bf16 v[96:99], v[156:159], v[172:175], v[96:99]
	v_mfma_f32_16x16x32_bf16 v[84:87], v[148:151], v[180:183], v[84:87]
	v_mfma_f32_16x16x32_bf16 v[80:83], v[156:159], v[180:183], v[80:83]
	v_mfma_f32_16x16x32_bf16 v[68:71], v[148:151], v[188:191], v[68:71]
	v_mfma_f32_16x16x32_bf16 v[64:67], v[156:159], v[188:191], v[64:67]
	s_barrier
	s_setprio 0
	s_add_i32 s28, s54, s34
	v_lshl_add_u64 v[204:205], v[204:205], 0, s[18:19]
	s_mov_b32 m0, s28
	ds_read_b128 v[160:163], v247 offset:49152
	ds_read_b128 v[164:167], v247 offset:50176
	ds_read_b128 v[168:171], v247 offset:51200
	ds_read_b128 v[172:175], v247 offset:52224
	ds_read_b128 v[176:179], v247 offset:53248
	ds_read_b128 v[180:183], v247 offset:54272
	ds_read_b128 v[184:187], v247 offset:55296
	ds_read_b128 v[188:191], v247 offset:56320
	global_load_lds_dwordx4 v[204:205], off
	s_add_i32 m0, s28, 0x2000
	s_add_u32 s26, s26, 0xb0080
	v_lshl_add_u64 v[204:205], v[206:207], 0, s[18:19]
	s_addc_u32 s27, s27, 0
	s_add_i32 s28, s55, s34
	global_load_lds_dwordx4 v[204:205], off
	v_lshl_add_u64 v[204:205], s[26:27], 0, v[194:195]
	s_mov_b32 m0, s28
	s_nop 0
	global_load_lds_dwordx4 v[204:205], off
	v_lshl_add_u64 v[204:205], s[26:27], 0, v[198:199]
	s_add_i32 m0, s28, 0x2000
	s_nop 0
	global_load_lds_dwordx4 v[204:205], off
	v_lshl_add_u64 v[204:205], v[208:209], 0, s[18:19]
	s_mov_b32 m0, s40
	s_nop 0
	global_load_lds_dwordx4 v[204:205], off
	v_lshl_add_u64 v[204:205], v[210:211], 0, s[18:19]
	s_mov_b32 m0, s41
	s_nop 0
	global_load_lds_dwordx4 v[204:205], off
	s_waitcnt vmcnt(8)
	s_waitcnt lgkmcnt(0)
	s_setprio 1
	s_barrier
	v_mfma_f32_16x16x32_bf16 v[60:63], v[120:123], v[160:163], v[60:63]
	v_mfma_f32_16x16x32_bf16 v[56:59], v[136:139], v[160:163], v[56:59]
	v_mfma_f32_16x16x32_bf16 v[44:47], v[120:123], v[168:171], v[44:47]
	v_mfma_f32_16x16x32_bf16 v[40:43], v[136:139], v[168:171], v[40:43]
	v_mfma_f32_16x16x32_bf16 v[28:31], v[120:123], v[176:179], v[28:31]
	v_mfma_f32_16x16x32_bf16 v[24:27], v[136:139], v[176:179], v[24:27]
	v_mfma_f32_16x16x32_bf16 v[12:15], v[120:123], v[184:187], v[12:15]
	v_mfma_f32_16x16x32_bf16 v[8:11], v[136:139], v[184:187], v[8:11]
	v_mfma_f32_16x16x32_bf16 v[60:63], v[128:131], v[164:167], v[60:63]
	v_mfma_f32_16x16x32_bf16 v[56:59], v[140:143], v[164:167], v[56:59]
	v_mfma_f32_16x16x32_bf16 v[44:47], v[128:131], v[172:175], v[44:47]
	v_mfma_f32_16x16x32_bf16 v[40:43], v[140:143], v[172:175], v[40:43]
	v_mfma_f32_16x16x32_bf16 v[28:31], v[128:131], v[180:183], v[28:31]
	v_mfma_f32_16x16x32_bf16 v[24:27], v[140:143], v[180:183], v[24:27]
	v_mfma_f32_16x16x32_bf16 v[12:15], v[128:131], v[188:191], v[12:15]
	v_mfma_f32_16x16x32_bf16 v[8:11], v[140:143], v[188:191], v[8:11]
	v_mfma_f32_16x16x32_bf16 v[52:55], v[144:147], v[160:163], v[52:55]
	v_mfma_f32_16x16x32_bf16 v[48:51], v[152:155], v[160:163], v[48:51]
	v_mfma_f32_16x16x32_bf16 v[36:39], v[144:147], v[168:171], v[36:39]
	v_mfma_f32_16x16x32_bf16 v[32:35], v[152:155], v[168:171], v[32:35]
	v_mfma_f32_16x16x32_bf16 v[20:23], v[144:147], v[176:179], v[20:23]
	v_mfma_f32_16x16x32_bf16 v[16:19], v[152:155], v[176:179], v[16:19]
	v_mfma_f32_16x16x32_bf16 v[4:7], v[144:147], v[184:187], v[4:7]
	v_mfma_f32_16x16x32_bf16 v[0:3], v[152:155], v[184:187], v[0:3]
	v_mfma_f32_16x16x32_bf16 v[52:55], v[148:151], v[164:167], v[52:55]
	v_mfma_f32_16x16x32_bf16 v[48:51], v[156:159], v[164:167], v[48:51]
	v_mfma_f32_16x16x32_bf16 v[36:39], v[148:151], v[172:175], v[36:39]
	v_mfma_f32_16x16x32_bf16 v[32:35], v[156:159], v[172:175], v[32:35]
	v_mfma_f32_16x16x32_bf16 v[20:23], v[148:151], v[180:183], v[20:23]
	v_mfma_f32_16x16x32_bf16 v[16:19], v[156:159], v[180:183], v[16:19]
	v_mfma_f32_16x16x32_bf16 v[4:7], v[148:151], v[188:191], v[4:7]
	v_mfma_f32_16x16x32_bf16 v[0:3], v[156:159], v[188:191], v[0:3]
	s_barrier
	s_setprio 0
	s_add_i32 s53, s53, 2
	s_add_u32 s24, s24, 0x100
	s_addc_u32 s25, s25, 0
	s_add_u32 s51, s51, 0x100
	s_addc_u32 s52, s52, 0
	s_cmp_gt_u32 s53, 41
; #define PG8_STAGE(bufoff, gbase, voff) do { _Pragma("unroll") for (int _i = 0; _i < 2; ++_i) \
;         __builtin_amdgcn_global_load_lds((const unsigned*)((const char*)(gbase) + (voff)[_i]), (PG8_LAS unsigned*)(lds + (bufoff) + ldsw + _i * 8192), 16, 0, 0); } while (0)
; #define PG8_LDA(dst, b, h) do { _Pragma("unroll") for (int m = 0; m < 4; ++m) _Pragma("unroll") for (int k = 0; k < 2; ++k) dst[m][k] = *(const PG8_LAS bf16x8*)(lds + PG8_SA(b, h) + aoff + m * 2048 + k * 1024); } while (0)
; #define PG8_LDB(dst, b, h) do { _Pragma("unroll") for (int n = 0; n < 2; ++n) _Pragma("unroll") for (int k = 0; k < 2; ++k) dst[n][k] = *(const PG8_LAS bf16x8*)(lds + PG8_SB(b, h) + boff + n * 2048 + k * 1024); } while (0)
; #define PG8_MMA(ai, bj, At, Bt) do { __builtin_amdgcn_s_setprio(1); _Pragma("unroll") for (int m = 0; m < 4; ++m) _Pragma("unroll") for (int n = 0; n < 2; ++n) _Pragma("unroll") for (int k = 0; k < 2; ++k) \
;         acc[ai][bj][m][n] = __builtin_amdgcn_mfma_f32_16x16x32_bf16(Bt[n][k], At[m][k], acc[ai][bj][m][n], 0, 0, 0); __builtin_amdgcn_s_setprio(0); } while (0)
; #define PG8_WAIT_V(n) asm volatile("s_waitcnt vmcnt(" #n ")" ::: "memory")
; #define PG8_WAIT_L(n) asm volatile("s_waitcnt lgkmcnt(" #n ")" ::: "memory")
; #define PG8_BAR __builtin_amdgcn_s_barrier()
; #define PG8_SCHED __builtin_amdgcn_sched_barrier(0)
; template <class Epi, class Sched, bool ALIGN_EPI = false, bool SP2 = false>
; __device__ __forceinline__ void gemm_phase(PG8_LAS unsigned char* lds, const Gemm g, const Sched& S, const Epi& E) {
;     ...
;             PG8_LDB(B0, 0, 0); PG8_LDB(B1, 0, 1); PG8_SCHED; PG8_LDA(At, 0, 0); PG8_STAGE(PG8_SA(1, 1), a1 + hstep, voffA);
;             PG8_WAIT_V(8); PG8_WAIT_L(0); PG8_BAR; PG8_MMA(0, 0, At, B0); PG8_MMA(0, 1, At, B1); PG8_BAR; PG8_SCHED;
;             PG8_LDA(At, 0, 1); PG8_STAGE(PG8_SB(0, 0), b2, voffB); PG8_STAGE(PG8_SB(0, 1), b2 + hstep, voffB); PG8_STAGE(PG8_SA(0, 0), a2, voffA);
.LBB0_418:
	ds_read_b128 v[120:123], v245
	ds_read_b128 v[128:131], v245 offset:1024
	ds_read_b128 v[136:139], v245 offset:2048
	ds_read_b128 v[140:143], v245 offset:3072
	ds_read_b128 v[144:147], v246
	ds_read_b128 v[148:151], v246 offset:1024
	ds_read_b128 v[152:155], v246 offset:2048
	ds_read_b128 v[156:159], v246 offset:3072
	s_add_u32 s26, s24, 0xfff50080
	s_addc_u32 s27, s25, -1
	s_cmp_eq_u32 s53, 40
	s_cselect_b32 s29, s7, s27
	s_cselect_b32 s28, s6, s26
	s_cselect_b32 s27, s23, s52
	s_cselect_b32 s26, s22, s51
	v_lshl_add_u64 v[204:205], s[24:25], 0, v[200:201]
	s_add_i32 m0, s35, 0xc000
	ds_read_b128 v[160:163], v247
	ds_read_b128 v[164:167], v247 offset:1024
	ds_read_b128 v[168:171], v247 offset:2048
	ds_read_b128 v[172:175], v247 offset:3072
	ds_read_b128 v[176:179], v247 offset:4096
	ds_read_b128 v[180:183], v247 offset:5120
	ds_read_b128 v[184:187], v247 offset:6144
	ds_read_b128 v[188:191], v247 offset:7168
	global_load_lds_dwordx4 v[204:205], off
	v_lshl_add_u64 v[204:205], s[24:25], 0, v[202:203]
	s_add_i32 m0, s35, 0xe000
	s_nop 0
	global_load_lds_dwordx4 v[204:205], off
	s_waitcnt vmcnt(8)
	s_waitcnt lgkmcnt(0)
	s_setprio 1
	s_barrier
	v_mfma_f32_16x16x32_bf16 v[132:135], v[120:123], v[160:163], v[132:135]
	v_mfma_f32_16x16x32_bf16 v[124:127], v[136:139], v[160:163], v[124:127]
	v_mfma_f32_16x16x32_bf16 v[108:111], v[120:123], v[168:171], v[108:111]
	v_mfma_f32_16x16x32_bf16 v[104:107], v[136:139], v[168:171], v[104:107]
	v_mfma_f32_16x16x32_bf16 v[92:95], v[120:123], v[176:179], v[92:95]
	v_mfma_f32_16x16x32_bf16 v[88:91], v[136:139], v[176:179], v[88:91]
	v_mfma_f32_16x16x32_bf16 v[76:79], v[120:123], v[184:187], v[76:79]
	v_mfma_f32_16x16x32_bf16 v[72:75], v[136:139], v[184:187], v[72:75]
	v_mfma_f32_16x16x32_bf16 v[132:135], v[128:131], v[164:167], v[132:135]
	v_mfma_f32_16x16x32_bf16 v[124:127], v[140:143], v[164:167], v[124:127]
	v_mfma_f32_16x16x32_bf16 v[108:111], v[128:131], v[172:175], v[108:111]
	v_mfma_f32_16x16x32_bf16 v[104:107], v[140:143], v[172:175], v[104:107]
	v_mfma_f32_16x16x32_bf16 v[92:95], v[128:131], v[180:183], v[92:95]
	v_mfma_f32_16x16x32_bf16 v[88:91], v[140:143], v[180:183], v[88:91]
	v_mfma_f32_16x16x32_bf16 v[76:79], v[128:131], v[188:191], v[76:79]
	v_mfma_f32_16x16x32_bf16 v[72:75], v[140:143], v[188:191], v[72:75]
	v_mfma_f32_16x16x32_bf16 v[116:119], v[144:147], v[160:163], v[116:119]
	v_mfma_f32_16x16x32_bf16 v[112:115], v[152:155], v[160:163], v[112:115]
	v_mfma_f32_16x16x32_bf16 v[100:103], v[144:147], v[168:171], v[100:103]
	v_mfma_f32_16x16x32_bf16 v[96:99], v[152:155], v[168:171], v[96:99]
	v_mfma_f32_16x16x32_bf16 v[84:87], v[144:147], v[176:179], v[84:87]
	v_mfma_f32_16x16x32_bf16 v[80:83], v[152:155], v[176:179], v[80:83]
	v_mfma_f32_16x16x32_bf16 v[68:71], v[144:147], v[184:187], v[68:71]
	v_mfma_f32_16x16x32_bf16 v[64:67], v[152:155], v[184:187], v[64:67]
	v_mfma_f32_16x16x32_bf16 v[116:119], v[148:151], v[164:167], v[116:119]
	v_mfma_f32_16x16x32_bf16 v[112:115], v[156:159], v[164:167], v[112:115]
	v_mfma_f32_16x16x32_bf16 v[100:103], v[148:151], v[172:175], v[100:103]
	v_mfma_f32_16x16x32_bf16 v[96:99], v[156:159], v[172:175], v[96:99]
	v_mfma_f32_16x16x32_bf16 v[84:87], v[148:151], v[180:183], v[84:87]
	v_mfma_f32_16x16x32_bf16 v[80:83], v[156:159], v[180:183], v[80:83]
	v_mfma_f32_16x16x32_bf16 v[68:71], v[148:151], v[188:191], v[68:71]
	v_mfma_f32_16x16x32_bf16 v[64:67], v[156:159], v[188:191], v[64:67]
	s_barrier
	s_setprio 0
	s_add_i32 s54, s45, s34
	v_lshl_add_u64 v[204:205], s[26:27], 0, v[194:195]
	s_mov_b32 m0, s54
	ds_read_b128 v[160:163], v247 offset:16384
	ds_read_b128 v[164:167], v247 offset:17408
	ds_read_b128 v[168:171], v247 offset:18432
	ds_read_b128 v[172:175], v247 offset:19456
	ds_read_b128 v[176:179], v247 offset:20480
	ds_read_b128 v[180:183], v247 offset:21504
	ds_read_b128 v[184:187], v247 offset:22528
	ds_read_b128 v[188:191], v247 offset:23552
	global_load_lds_dwordx4 v[204:205], off
	s_add_i32 m0, s54, 0x2000
	s_add_u32 s54, s26, 0xb0000
	v_lshl_add_u64 v[206:207], s[26:27], 0, v[198:199]
	s_addc_u32 s55, s27, 0
	s_add_i32 s56, s46, s34
	global_load_lds_dwordx4 v[206:207], off
	v_lshl_add_u64 v[208:209], s[54:55], 0, v[194:195]
	s_mov_b32 m0, s56
	v_lshl_add_u64 v[210:211], s[28:29], 0, v[196:197]
	global_load_lds_dwordx4 v[208:209], off
	v_lshl_add_u64 v[208:209], s[54:55], 0, v[198:199]
	s_add_i32 m0, s56, 0x2000
	s_nop 0
	global_load_lds_dwordx4 v[208:209], off
	v_lshl_add_u64 v[208:209], s[28:29], 0, v[192:193]
	s_mov_b32 m0, s35
	s_nop 0
	global_load_lds_dwordx4 v[208:209], off
	s_mov_b32 m0, s36
	s_nop 0
	global_load_lds_dwordx4 v[210:211], off
	s_waitcnt vmcnt(8)
	s_waitcnt lgkmcnt(0)
	s_setprio 1
	s_barrier
; #define PG8_STAGE(bufoff, gbase, voff) do { _Pragma("unroll") for (int _i = 0; _i < 2; ++_i) \
;         __builtin_amdgcn_global_load_lds((const unsigned*)((const char*)(gbase) + (voff)[_i]), (PG8_LAS unsigned*)(lds + (bufoff) + ldsw + _i * 8192), 16, 0, 0); } while (0)
; #define PG8_LDA(dst, b, h) do { _Pragma("unroll") for (int m = 0; m < 4; ++m) _Pragma("unroll") for (int k = 0; k < 2; ++k) dst[m][k] = *(const PG8_LAS bf16x8*)(lds + PG8_SA(b, h) + aoff + m * 2048 + k * 1024); } while (0)
; #define PG8_LDB(dst, b, h) do { _Pragma("unroll") for (int n = 0; n < 2; ++n) _Pragma("unroll") for (int k = 0; k < 2; ++k) dst[n][k] = *(const PG8_LAS bf16x8*)(lds + PG8_SB(b, h) + boff + n * 2048 + k * 1024); } while (0)
; #define PG8_MMA(ai, bj, At, Bt) do { __builtin_amdgcn_s_setprio(1); _Pragma("unroll") for (int m = 0; m < 4; ++m) _Pragma("unroll") for (int n = 0; n < 2; ++n) _Pragma("unroll") for (int k = 0; k < 2; ++k) \
;         acc[ai][bj][m][n] = __builtin_amdgcn_mfma_f32_16x16x32_bf16(Bt[n][k], At[m][k], acc[ai][bj][m][n], 0, 0, 0); __builtin_amdgcn_s_setprio(0); } while (0)
; #define PG8_WAIT_V(n) asm volatile("s_waitcnt vmcnt(" #n ")" ::: "memory")
; #define PG8_WAIT_L(n) asm volatile("s_waitcnt lgkmcnt(" #n ")" ::: "memory")
; #define PG8_BAR __builtin_amdgcn_s_barrier()
; #define PG8_SCHED __builtin_amdgcn_sched_barrier(0)
; template <class Epi, class Sched, bool ALIGN_EPI = false, bool SP2 = false>
; __device__ __forceinline__ void gemm_phase(PG8_LAS unsigned char* lds, const Gemm g, const Sched& S, const Epi& E) {
;     ...
;             PG8_WAIT_V(8); PG8_WAIT_L(0); PG8_BAR; PG8_MMA(1, 0, At, B0); PG8_MMA(1, 1, At, B1); PG8_BAR; PG8_SCHED;
;             PG8_LDB(B0, 1, 0); PG8_LDB(B1, 1, 1); PG8_SCHED; PG8_LDA(At, 1, 0); PG8_STAGE(PG8_SA(0, 1), a2 + hstep, voffA);
;             PG8_WAIT_V(8); PG8_WAIT_L(0); PG8_BAR; PG8_MMA(0, 0, At, B0); PG8_MMA(0, 1, At, B1); PG8_BAR; PG8_SCHED;
	v_mfma_f32_16x16x32_bf16 v[60:63], v[120:123], v[160:163], v[60:63]
	v_mfma_f32_16x16x32_bf16 v[56:59], v[136:139], v[160:163], v[56:59]
	v_mfma_f32_16x16x32_bf16 v[44:47], v[120:123], v[168:171], v[44:47]
	v_mfma_f32_16x16x32_bf16 v[40:43], v[136:139], v[168:171], v[40:43]
	v_mfma_f32_16x16x32_bf16 v[28:31], v[120:123], v[176:179], v[28:31]
	v_mfma_f32_16x16x32_bf16 v[24:27], v[136:139], v[176:179], v[24:27]
	v_mfma_f32_16x16x32_bf16 v[12:15], v[120:123], v[184:187], v[12:15]
	v_mfma_f32_16x16x32_bf16 v[8:11], v[136:139], v[184:187], v[8:11]
	v_mfma_f32_16x16x32_bf16 v[60:63], v[128:131], v[164:167], v[60:63]
	v_mfma_f32_16x16x32_bf16 v[56:59], v[140:143], v[164:167], v[56:59]
	v_mfma_f32_16x16x32_bf16 v[44:47], v[128:131], v[172:175], v[44:47]
	v_mfma_f32_16x16x32_bf16 v[40:43], v[140:143], v[172:175], v[40:43]
	v_mfma_f32_16x16x32_bf16 v[28:31], v[128:131], v[180:183], v[28:31]
	v_mfma_f32_16x16x32_bf16 v[24:27], v[140:143], v[180:183], v[24:27]
	v_mfma_f32_16x16x32_bf16 v[12:15], v[128:131], v[188:191], v[12:15]
	v_mfma_f32_16x16x32_bf16 v[8:11], v[140:143], v[188:191], v[8:11]
	v_mfma_f32_16x16x32_bf16 v[52:55], v[144:147], v[160:163], v[52:55]
	v_mfma_f32_16x16x32_bf16 v[48:51], v[152:155], v[160:163], v[48:51]
	v_mfma_f32_16x16x32_bf16 v[36:39], v[144:147], v[168:171], v[36:39]
	v_mfma_f32_16x16x32_bf16 v[32:35], v[152:155], v[168:171], v[32:35]
	v_mfma_f32_16x16x32_bf16 v[20:23], v[144:147], v[176:179], v[20:23]
	v_mfma_f32_16x16x32_bf16 v[16:19], v[152:155], v[176:179], v[16:19]
	v_mfma_f32_16x16x32_bf16 v[4:7], v[144:147], v[184:187], v[4:7]
	v_mfma_f32_16x16x32_bf16 v[0:3], v[152:155], v[184:187], v[0:3]
	v_mfma_f32_16x16x32_bf16 v[52:55], v[148:151], v[164:167], v[52:55]
	v_mfma_f32_16x16x32_bf16 v[48:51], v[156:159], v[164:167], v[48:51]
	v_mfma_f32_16x16x32_bf16 v[36:39], v[148:151], v[172:175], v[36:39]
	v_mfma_f32_16x16x32_bf16 v[32:35], v[156:159], v[172:175], v[32:35]
	v_mfma_f32_16x16x32_bf16 v[20:23], v[148:151], v[180:183], v[20:23]
	v_mfma_f32_16x16x32_bf16 v[16:19], v[156:159], v[180:183], v[16:19]
	v_mfma_f32_16x16x32_bf16 v[4:7], v[148:151], v[188:191], v[4:7]
	v_mfma_f32_16x16x32_bf16 v[0:3], v[156:159], v[188:191], v[0:3]
	s_barrier
	s_setprio 0
	s_add_i32 s54, 0, 0x18000
	s_add_i32 s55, 0, 0x1c000
	v_add_u32_e32 v140, s54, v243
	v_add_u32_e32 v156, s55, v243
	ds_read_b128 v[120:123], v140
	ds_read_b128 v[128:131], v140 offset:1024
	ds_read_b128 v[136:139], v140 offset:2048
	ds_read_b128 v[140:143], v140 offset:3072
	ds_read_b128 v[144:147], v156
	ds_read_b128 v[148:151], v156 offset:1024
	ds_read_b128 v[152:155], v156 offset:2048
	ds_read_b128 v[156:159], v156 offset:3072
	s_add_u32 s28, s28, 0xb0000
	s_addc_u32 s29, s29, 0
	s_mov_b32 m0, s37
	v_lshl_add_u64 v[212:213], s[28:29], 0, v[192:193]
	ds_read_b128 v[160:163], v247 offset:32768
	ds_read_b128 v[164:167], v247 offset:33792
	ds_read_b128 v[168:171], v247 offset:34816
	ds_read_b128 v[172:175], v247 offset:35840
	ds_read_b128 v[176:179], v247 offset:36864
	ds_read_b128 v[180:183], v247 offset:37888
	ds_read_b128 v[184:187], v247 offset:38912
	ds_read_b128 v[188:191], v247 offset:39936
	global_load_lds_dwordx4 v[212:213], off
	v_lshl_add_u64 v[212:213], s[28:29], 0, v[196:197]
	s_mov_b32 m0, s38
	s_nop 0
	global_load_lds_dwordx4 v[212:213], off
	s_waitcnt vmcnt(8)
	s_waitcnt lgkmcnt(0)
	s_setprio 1
	s_barrier
	v_mfma_f32_16x16x32_bf16 v[132:135], v[120:123], v[160:163], v[132:135]
	v_mfma_f32_16x16x32_bf16 v[124:127], v[136:139], v[160:163], v[124:127]
	v_mfma_f32_16x16x32_bf16 v[108:111], v[120:123], v[168:171], v[108:111]
	v_mfma_f32_16x16x32_bf16 v[104:107], v[136:139], v[168:171], v[104:107]
	v_mfma_f32_16x16x32_bf16 v[92:95], v[120:123], v[176:179], v[92:95]
	v_mfma_f32_16x16x32_bf16 v[88:91], v[136:139], v[176:179], v[88:91]
	v_mfma_f32_16x16x32_bf16 v[76:79], v[120:123], v[184:187], v[76:79]
	v_mfma_f32_16x16x32_bf16 v[72:75], v[136:139], v[184:187], v[72:75]
	v_mfma_f32_16x16x32_bf16 v[132:135], v[128:131], v[164:167], v[132:135]
	v_mfma_f32_16x16x32_bf16 v[124:127], v[140:143], v[164:167], v[124:127]
	v_mfma_f32_16x16x32_bf16 v[108:111], v[128:131], v[172:175], v[108:111]
	v_mfma_f32_16x16x32_bf16 v[104:107], v[140:143], v[172:175], v[104:107]
	v_mfma_f32_16x16x32_bf16 v[92:95], v[128:131], v[180:183], v[92:95]
	v_mfma_f32_16x16x32_bf16 v[88:91], v[140:143], v[180:183], v[88:91]
	v_mfma_f32_16x16x32_bf16 v[76:79], v[128:131], v[188:191], v[76:79]
	v_mfma_f32_16x16x32_bf16 v[72:75], v[140:143], v[188:191], v[72:75]
	v_mfma_f32_16x16x32_bf16 v[116:119], v[144:147], v[160:163], v[116:119]
	v_mfma_f32_16x16x32_bf16 v[112:115], v[152:155], v[160:163], v[112:115]
	v_mfma_f32_16x16x32_bf16 v[100:103], v[144:147], v[168:171], v[100:103]
	v_mfma_f32_16x16x32_bf16 v[96:99], v[152:155], v[168:171], v[96:99]
	v_mfma_f32_16x16x32_bf16 v[84:87], v[144:147], v[176:179], v[84:87]
	v_mfma_f32_16x16x32_bf16 v[80:83], v[152:155], v[176:179], v[80:83]
	v_mfma_f32_16x16x32_bf16 v[68:71], v[144:147], v[184:187], v[68:71]
	v_mfma_f32_16x16x32_bf16 v[64:67], v[152:155], v[184:187], v[64:67]
	v_mfma_f32_16x16x32_bf16 v[116:119], v[148:151], v[164:167], v[116:119]
	v_mfma_f32_16x16x32_bf16 v[112:115], v[156:159], v[164:167], v[112:115]
	v_mfma_f32_16x16x32_bf16 v[100:103], v[148:151], v[172:175], v[100:103]
	v_mfma_f32_16x16x32_bf16 v[96:99], v[156:159], v[172:175], v[96:99]
	v_mfma_f32_16x16x32_bf16 v[84:87], v[148:151], v[180:183], v[84:87]
	v_mfma_f32_16x16x32_bf16 v[80:83], v[156:159], v[180:183], v[80:83]
	v_mfma_f32_16x16x32_bf16 v[68:71], v[148:151], v[188:191], v[68:71]
	v_mfma_f32_16x16x32_bf16 v[64:67], v[156:159], v[188:191], v[64:67]
	s_barrier
; #define PG8_STAGE(bufoff, gbase, voff) do { _Pragma("unroll") for (int _i = 0; _i < 2; ++_i) \
;         __builtin_amdgcn_global_load_lds((const unsigned*)((const char*)(gbase) + (voff)[_i]), (PG8_LAS unsigned*)(lds + (bufoff) + ldsw + _i * 8192), 16, 0, 0); } while (0)
; #define PG8_LDA(dst, b, h) do { _Pragma("unroll") for (int m = 0; m < 4; ++m) _Pragma("unroll") for (int k = 0; k < 2; ++k) dst[m][k] = *(const PG8_LAS bf16x8*)(lds + PG8_SA(b, h) + aoff + m * 2048 + k * 1024); } while (0)
; #define PG8_WAIT_V(n) asm volatile("s_waitcnt vmcnt(" #n ")" ::: "memory")
; template <class Epi, class Sched, bool ALIGN_EPI = false, bool SP2 = false>
; __device__ __forceinline__ void gemm_phase(PG8_LAS unsigned char* lds, const Gemm g, const Sched& S, const Epi& E) {
;     ...
;             PG8_LDA(At, 1, 1); PG8_STAGE(PG8_SB(1, 0), b3, voffB); PG8_STAGE(PG8_SB(1, 1), b3 + hstep, voffB); PG8_STAGE(PG8_SA(1, 0), a3, voffA);
;             PG8_WAIT_V(8); PG8_WAIT_L(0); PG8_BAR; PG8_MMA(1, 0, At, B0); PG8_MMA(1, 1, At, B1); PG8_BAR; PG8_SCHED;
;             } else {
;             PG8_LDB(B0, 0, 0); PG8_SCHED; PG8_LDA(At, 0, 0); PG8_STAGE(PG8_SA(1, 1), a1 + hstep, voffA);
;             PG8_WAIT_L(8); PG8_BAR; PG8_WAIT_L(0); PG8_MMA(0, 0, At, B0); PG8_BAR; PG8_SCHED;
;             PG8_LDB(B1, 0, 1); PG8_STAGE(PG8_SB(0, 0), b2, voffB);
;             PG8_BAR; PG8_WAIT_L(0); PG8_MMA(0, 1, At, B1); PG8_BAR;
;             PG8_LDA(At, 0, 1); PG8_STAGE(PG8_SA(0, 0), a2, voffA);
;             PG8_BAR; PG8_WAIT_L(0); PG8_MMA(1, 0, At, B0); PG8_BAR; PG8_SCHED;
;             PG8_STAGE(PG8_SB(0, 1), b2 + hstep, voffB);
;             PG8_WAIT_V(6); PG8_BAR; PG8_MMA(1, 1, At, B1); PG8_BAR;
;             PG8_LDB(B0, 1, 0); PG8_SCHED; PG8_LDA(At, 1, 0); PG8_STAGE(PG8_SA(0, 1), a2 + hstep, voffA);
;             PG8_WAIT_L(8); PG8_BAR; PG8_WAIT_L(0); PG8_MMA(0, 0, At, B0); PG8_BAR; PG8_SCHED;
;             PG8_LDB(B1, 1, 1); PG8_STAGE(PG8_SB(1, 0), b3, voffB);
;             PG8_BAR; PG8_WAIT_L(0); PG8_MMA(0, 1, At, B1); PG8_BAR;
;             PG8_LDA(At, 1, 1); PG8_STAGE(PG8_SA(1, 0), a3, voffA);
;             PG8_BAR; PG8_WAIT_L(0); PG8_MMA(1, 0, At, B0); PG8_BAR; PG8_SCHED;
;             PG8_STAGE(PG8_SB(1, 1), b3 + hstep, voffB);
;             PG8_WAIT_V(6); PG8_BAR; PG8_MMA(1, 1, At, B1); PG8_BAR;
;             }
;         }
;         if constexpr (ALIGN_EPI) { if (wr == 0) PG8_BAR; }
	s_setprio 0
	s_add_i32 s28, s54, s34
	v_lshl_add_u64 v[204:205], v[204:205], 0, s[18:19]
	s_mov_b32 m0, s28
	ds_read_b128 v[160:163], v247 offset:49152
	ds_read_b128 v[164:167], v247 offset:50176
	ds_read_b128 v[168:171], v247 offset:51200
	ds_read_b128 v[172:175], v247 offset:52224
	ds_read_b128 v[176:179], v247 offset:53248
	ds_read_b128 v[180:183], v247 offset:54272
	ds_read_b128 v[184:187], v247 offset:55296
	ds_read_b128 v[188:191], v247 offset:56320
	global_load_lds_dwordx4 v[204:205], off
	s_add_i32 m0, s28, 0x2000
	s_add_u32 s26, s26, 0xb0080
	v_lshl_add_u64 v[204:205], v[206:207], 0, s[18:19]
	s_addc_u32 s27, s27, 0
	s_add_i32 s28, s55, s34
	global_load_lds_dwordx4 v[204:205], off
	v_lshl_add_u64 v[204:205], s[26:27], 0, v[194:195]
	s_mov_b32 m0, s28
	s_nop 0
	global_load_lds_dwordx4 v[204:205], off
	v_lshl_add_u64 v[204:205], s[26:27], 0, v[198:199]
	s_add_i32 m0, s28, 0x2000
	s_nop 0
	global_load_lds_dwordx4 v[204:205], off
	v_lshl_add_u64 v[204:205], v[208:209], 0, s[18:19]
	s_mov_b32 m0, s40
	s_nop 0
	global_load_lds_dwordx4 v[204:205], off
	v_lshl_add_u64 v[204:205], v[210:211], 0, s[18:19]
	s_mov_b32 m0, s41
	s_nop 0
	global_load_lds_dwordx4 v[204:205], off
	s_waitcnt vmcnt(8)
	s_waitcnt lgkmcnt(0)
	s_setprio 1
	s_barrier
	v_mfma_f32_16x16x32_bf16 v[60:63], v[120:123], v[160:163], v[60:63]
	v_mfma_f32_16x16x32_bf16 v[56:59], v[136:139], v[160:163], v[56:59]
	v_mfma_f32_16x16x32_bf16 v[44:47], v[120:123], v[168:171], v[44:47]
	v_mfma_f32_16x16x32_bf16 v[40:43], v[136:139], v[168:171], v[40:43]
	v_mfma_f32_16x16x32_bf16 v[28:31], v[120:123], v[176:179], v[28:31]
	v_mfma_f32_16x16x32_bf16 v[24:27], v[136:139], v[176:179], v[24:27]
	v_mfma_f32_16x16x32_bf16 v[12:15], v[120:123], v[184:187], v[12:15]
	v_mfma_f32_16x16x32_bf16 v[8:11], v[136:139], v[184:187], v[8:11]
	v_mfma_f32_16x16x32_bf16 v[60:63], v[128:131], v[164:167], v[60:63]
	v_mfma_f32_16x16x32_bf16 v[56:59], v[140:143], v[164:167], v[56:59]
	v_mfma_f32_16x16x32_bf16 v[44:47], v[128:131], v[172:175], v[44:47]
	v_mfma_f32_16x16x32_bf16 v[40:43], v[140:143], v[172:175], v[40:43]
	v_mfma_f32_16x16x32_bf16 v[28:31], v[128:131], v[180:183], v[28:31]
	v_mfma_f32_16x16x32_bf16 v[24:27], v[140:143], v[180:183], v[24:27]
	v_mfma_f32_16x16x32_bf16 v[12:15], v[128:131], v[188:191], v[12:15]
	v_mfma_f32_16x16x32_bf16 v[8:11], v[140:143], v[188:191], v[8:11]
	v_mfma_f32_16x16x32_bf16 v[52:55], v[144:147], v[160:163], v[52:55]
	v_mfma_f32_16x16x32_bf16 v[48:51], v[152:155], v[160:163], v[48:51]
	v_mfma_f32_16x16x32_bf16 v[36:39], v[144:147], v[168:171], v[36:39]
	v_mfma_f32_16x16x32_bf16 v[32:35], v[152:155], v[168:171], v[32:35]
	v_mfma_f32_16x16x32_bf16 v[20:23], v[144:147], v[176:179], v[20:23]
	v_mfma_f32_16x16x32_bf16 v[16:19], v[152:155], v[176:179], v[16:19]
	v_mfma_f32_16x16x32_bf16 v[4:7], v[144:147], v[184:187], v[4:7]
	v_mfma_f32_16x16x32_bf16 v[0:3], v[152:155], v[184:187], v[0:3]
	v_mfma_f32_16x16x32_bf16 v[52:55], v[148:151], v[164:167], v[52:55]
	v_mfma_f32_16x16x32_bf16 v[48:51], v[156:159], v[164:167], v[48:51]
	v_mfma_f32_16x16x32_bf16 v[36:39], v[148:151], v[172:175], v[36:39]
	v_mfma_f32_16x16x32_bf16 v[32:35], v[156:159], v[172:175], v[32:35]
	v_mfma_f32_16x16x32_bf16 v[20:23], v[148:151], v[180:183], v[20:23]
	v_mfma_f32_16x16x32_bf16 v[16:19], v[156:159], v[180:183], v[16:19]
	v_mfma_f32_16x16x32_bf16 v[4:7], v[148:151], v[188:191], v[4:7]
	v_mfma_f32_16x16x32_bf16 v[0:3], v[156:159], v[188:191], v[0:3]
	s_barrier
	s_setprio 0
	s_add_i32 s53, s53, 2
	s_add_u32 s24, s24, 0x100
	s_addc_u32 s25, s25, 0
	s_add_u32 s51, s51, 0x100
	s_addc_u32 s52, s52, 0
	s_cmp_gt_u32 s53, 41
	s_cbranch_scc0 .LBB0_418
	s_and_b64 vcc, exec, s[20:21]
	s_cbranch_vccz .LBB0_421
	s_barrier

; #define PG8_STAGE(bufoff, gbase, voff) do { _Pragma("unroll") for (int _i = 0; _i < 2; ++_i) \
;         __builtin_amdgcn_global_load_lds((const unsigned*)((const char*)(gbase) + (voff)[_i]), (PG8_LAS unsigned*)(lds + (bufoff) + ldsw + _i * 8192), 16, 0, 0); } while (0)
; #define PG8_LDA(dst, b, h) do { _Pragma("unroll") for (int m = 0; m < 4; ++m) _Pragma("unroll") for (int k = 0; k < 2; ++k) dst[m][k] = *(const PG8_LAS bf16x8*)(lds + PG8_SA(b, h) + aoff + m * 2048 + k * 1024); } while (0)
; #define PG8_LDB(dst, b, h) do { _Pragma("unroll") for (int n = 0; n < 2; ++n) _Pragma("unroll") for (int k = 0; k < 2; ++k) dst[n][k] = *(const PG8_LAS bf16x8*)(lds + PG8_SB(b, h) + boff + n * 2048 + k * 1024); } while (0)
; #define PG8_WAIT_V(n) asm volatile("s_waitcnt vmcnt(" #n ")" ::: "memory")
; #define PG8_WAIT_L(n) asm volatile("s_waitcnt lgkmcnt(" #n ")" ::: "memory")
; #define PG8_BAR __builtin_amdgcn_s_barrier()
; #define PG8_SCHED __builtin_amdgcn_sched_barrier(0)
; template <class Epi, class Sched, bool ALIGN_EPI = false, bool SP2 = false>
; __device__ __forceinline__ void gemm_phase(PG8_LAS unsigned char* lds, const Gemm g, const Sched& S, const Epi& E) {
;     ...
;         const char* nA = has_next ? (const char*)g.A + (size_t)nxt.pm * tstep : cA; const char* nB = has_next ? (const char*)g.Bt + (size_t)nxt.pn * tstep : cB;
;         for (int t = 0; t < nt; t += 2) {
;             const bool last = (t == nt - 2);
;             const char* a1 = cA + (size_t)(t + 1) * kstep;
;             const char* a2 = last ? nA : cA + (size_t)(t + 2) * kstep; const char* b2 = last ? nB : cB + (size_t)(t + 2) * kstep;
;             const char* a3 = a2 + kstep; const char* b3 = b2 + kstep;
;             if (last && has_next) S.a_ready(nxt, ui + 1);
;             if constexpr (SP2) {
;             PG8_LDB(B0, 0, 0); PG8_LDB(B1, 0, 1); PG8_SCHED; PG8_LDA(At, 0, 0); PG8_STAGE(PG8_SA(1, 1), a1 + hstep, voffA);
;             PG8_WAIT_V(8); PG8_WAIT_L(0); PG8_BAR; PG8_MMA(0, 0, At, B0); PG8_MMA(0, 1, At, B1); PG8_BAR; PG8_SCHED;
;             PG8_LDA(At, 0, 1); PG8_STAGE(PG8_SB(0, 0), b2, voffB); PG8_STAGE(PG8_SB(0, 1), b2 + hstep, voffB); PG8_STAGE(PG8_SA(0, 0), a2, voffA);
;             PG8_WAIT_V(8); PG8_WAIT_L(0); PG8_BAR; PG8_MMA(1, 0, At, B0); PG8_MMA(1, 1, At, B1); PG8_BAR; PG8_SCHED;
.LBB0_508:
	s_ashr_i32 s31, s30, 31
	s_lshl_b64 s[34:35], s[30:31], 19
	s_add_u32 s34, s48, s34
	s_addc_u32 s35, s49, s35
	s_and_b64 s[36:37], s[4:5], exec
	s_cselect_b32 s9, s35, s39
	s_cselect_b32 s14, s34, s38
	s_ashr_i32 s29, s28, 31
	s_lshl_b64 s[36:37], s[28:29], 19
	s_add_u32 s36, s50, s36
	s_addc_u32 s37, s51, s37
	s_and_b64 s[42:43], s[4:5], exec
	s_cselect_b32 s29, s37, s41
	s_cselect_b32 s31, s36, s40
	s_add_u32 s38, s38, 0x40080
	s_addc_u32 s39, s39, 0
	s_add_u32 s44, s40, 0x100
	s_addc_u32 s45, s41, 0
	s_mov_b32 s70, -2
	s_add_u32 s40, s38, 0xfffc0080
	s_addc_u32 s41, s39, -1
	s_cmp_eq_u32 s70, 12
	s_cselect_b32 s43, s9, s41
	s_cselect_b32 s42, s14, s40
	s_cselect_b32 s41, s29, s45
	s_cselect_b32 s40, s31, s44
	v_lshl_add_u64 v[226:227], s[38:39], 0, v[132:133]
	s_add_i32 m0, s52, 0xc000
	global_load_lds_dwordx4 v[226:227], off
	v_lshl_add_u64 v[226:227], s[38:39], 0, v[134:135]
	s_add_i32 m0, s52, 0xe000
	s_nop 0
	global_load_lds_dwordx4 v[226:227], off
	s_waitcnt vmcnt(8)
	s_waitcnt lgkmcnt(0)
	s_setprio 1
	s_barrier
	v_mfma_f32_16x16x32_bf16 v[124:127], v[148:151], v[194:197], 0
	v_mfma_f32_16x16x32_bf16 v[120:123], v[170:173], v[194:197], 0
	v_mfma_f32_16x16x32_bf16 v[108:111], v[148:151], v[202:205], 0
	v_mfma_f32_16x16x32_bf16 v[104:107], v[170:173], v[202:205], 0
	v_mfma_f32_16x16x32_bf16 v[92:95], v[148:151], v[210:213], 0
	v_mfma_f32_16x16x32_bf16 v[88:91], v[170:173], v[210:213], 0
	v_mfma_f32_16x16x32_bf16 v[76:79], v[148:151], v[218:221], 0
	v_mfma_f32_16x16x32_bf16 v[72:75], v[170:173], v[218:221], 0
	v_mfma_f32_16x16x32_bf16 v[124:127], v[166:169], v[198:201], v[124:127]
	v_mfma_f32_16x16x32_bf16 v[120:123], v[174:177], v[198:201], v[120:123]
	v_mfma_f32_16x16x32_bf16 v[108:111], v[166:169], v[206:209], v[108:111]
	v_mfma_f32_16x16x32_bf16 v[104:107], v[174:177], v[206:209], v[104:107]
	v_mfma_f32_16x16x32_bf16 v[92:95], v[166:169], v[214:217], v[92:95]
	v_mfma_f32_16x16x32_bf16 v[88:91], v[174:177], v[214:217], v[88:91]
	v_mfma_f32_16x16x32_bf16 v[76:79], v[166:169], v[222:225], v[76:79]
	v_mfma_f32_16x16x32_bf16 v[72:75], v[174:177], v[222:225], v[72:75]
	v_mfma_f32_16x16x32_bf16 v[116:119], v[178:181], v[194:197], 0
	v_mfma_f32_16x16x32_bf16 v[112:115], v[186:189], v[194:197], 0
	v_mfma_f32_16x16x32_bf16 v[100:103], v[178:181], v[202:205], 0
	v_mfma_f32_16x16x32_bf16 v[96:99], v[186:189], v[202:205], 0
	v_mfma_f32_16x16x32_bf16 v[84:87], v[178:181], v[210:213], 0
	v_mfma_f32_16x16x32_bf16 v[80:83], v[186:189], v[210:213], 0
	v_mfma_f32_16x16x32_bf16 v[68:71], v[178:181], v[218:221], 0
	v_mfma_f32_16x16x32_bf16 v[64:67], v[186:189], v[218:221], 0
	v_mfma_f32_16x16x32_bf16 v[116:119], v[182:185], v[198:201], v[116:119]
	v_mfma_f32_16x16x32_bf16 v[112:115], v[190:193], v[198:201], v[112:115]
	v_mfma_f32_16x16x32_bf16 v[100:103], v[182:185], v[206:209], v[100:103]
	v_mfma_f32_16x16x32_bf16 v[96:99], v[190:193], v[206:209], v[96:99]
	v_mfma_f32_16x16x32_bf16 v[84:87], v[182:185], v[214:217], v[84:87]
	v_mfma_f32_16x16x32_bf16 v[80:83], v[190:193], v[214:217], v[80:83]
	v_mfma_f32_16x16x32_bf16 v[68:71], v[182:185], v[222:225], v[68:71]
	v_mfma_f32_16x16x32_bf16 v[64:67], v[190:193], v[222:225], v[64:67]
	s_barrier
	s_setprio 0
	s_add_i32 s71, s61, s33
	v_lshl_add_u64 v[226:227], s[40:41], 0, v[138:139]
	s_mov_b32 m0, s71
	ds_read_b128 v[194:197], v164 offset:16384
	ds_read_b128 v[198:201], v164 offset:17408
	ds_read_b128 v[202:205], v164 offset:18432
	ds_read_b128 v[206:209], v164 offset:19456
	ds_read_b128 v[210:213], v164 offset:20480
	ds_read_b128 v[214:217], v164 offset:21504
	ds_read_b128 v[218:221], v164 offset:22528
	ds_read_b128 v[222:225], v164 offset:23552
	global_load_lds_dwordx4 v[226:227], off
	s_add_i32 m0, s71, 0x2000
	s_add_u32 s72, s40, 0x40000
	v_lshl_add_u64 v[228:229], s[40:41], 0, v[142:143]
	s_addc_u32 s73, s41, 0
	s_add_i32 s71, s62, s33
	global_load_lds_dwordx4 v[228:229], off
	v_lshl_add_u64 v[230:231], s[72:73], 0, v[138:139]
	s_mov_b32 m0, s71
	v_lshl_add_u64 v[232:233], s[42:43], 0, v[140:141]
	global_load_lds_dwordx4 v[230:231], off
	v_lshl_add_u64 v[230:231], s[72:73], 0, v[142:143]
	s_add_i32 m0, s71, 0x2000
	s_nop 0
	global_load_lds_dwordx4 v[230:231], off
	v_lshl_add_u64 v[230:231], s[42:43], 0, v[136:137]
	s_mov_b32 m0, s52
	s_nop 0
	global_load_lds_dwordx4 v[230:231], off
	s_mov_b32 m0, s53
	s_nop 0
	global_load_lds_dwordx4 v[232:233], off
	s_waitcnt vmcnt(8)
	s_waitcnt lgkmcnt(0)
	s_setprio 1
	s_barrier
	v_mfma_f32_16x16x32_bf16 v[60:63], v[148:151], v[194:197], 0
	v_mfma_f32_16x16x32_bf16 v[56:59], v[170:173], v[194:197], 0
	v_mfma_f32_16x16x32_bf16 v[44:47], v[148:151], v[202:205], 0
	v_mfma_f32_16x16x32_bf16 v[40:43], v[170:173], v[202:205], 0
	v_mfma_f32_16x16x32_bf16 v[28:31], v[148:151], v[210:213], 0
	v_mfma_f32_16x16x32_bf16 v[24:27], v[170:173], v[210:213], 0
	v_mfma_f32_16x16x32_bf16 v[12:15], v[148:151], v[218:221], 0
	v_mfma_f32_16x16x32_bf16 v[8:11], v[170:173], v[218:221], 0
	v_mfma_f32_16x16x32_bf16 v[60:63], v[166:169], v[198:201], v[60:63]
	v_mfma_f32_16x16x32_bf16 v[56:59], v[174:177], v[198:201], v[56:59]
	v_mfma_f32_16x16x32_bf16 v[44:47], v[166:169], v[206:209], v[44:47]
	v_mfma_f32_16x16x32_bf16 v[40:43], v[174:177], v[206:209], v[40:43]
	v_mfma_f32_16x16x32_bf16 v[28:31], v[166:169], v[214:217], v[28:31]
	v_mfma_f32_16x16x32_bf16 v[24:27], v[174:177], v[214:217], v[24:27]
	v_mfma_f32_16x16x32_bf16 v[12:15], v[166:169], v[222:225], v[12:15]
	v_mfma_f32_16x16x32_bf16 v[8:11], v[174:177], v[222:225], v[8:11]
	v_mfma_f32_16x16x32_bf16 v[52:55], v[178:181], v[194:197], 0
	v_mfma_f32_16x16x32_bf16 v[48:51], v[186:189], v[194:197], 0
	v_mfma_f32_16x16x32_bf16 v[36:39], v[178:181], v[202:205], 0
	v_mfma_f32_16x16x32_bf16 v[32:35], v[186:189], v[202:205], 0
	v_mfma_f32_16x16x32_bf16 v[20:23], v[178:181], v[210:213], 0
	v_mfma_f32_16x16x32_bf16 v[16:19], v[186:189], v[210:213], 0
	v_mfma_f32_16x16x32_bf16 v[4:7], v[178:181], v[218:221], 0
	v_mfma_f32_16x16x32_bf16 v[0:3], v[186:189], v[218:221], 0
	v_mfma_f32_16x16x32_bf16 v[52:55], v[182:185], v[198:201], v[52:55]
	v_mfma_f32_16x16x32_bf16 v[48:51], v[190:193], v[198:201], v[48:51]
	v_mfma_f32_16x16x32_bf16 v[36:39], v[182:185], v[206:209], v[36:39]
	v_mfma_f32_16x16x32_bf16 v[32:35], v[190:193], v[206:209], v[32:35]
	v_mfma_f32_16x16x32_bf16 v[20:23], v[182:185], v[214:217], v[20:23]
	v_mfma_f32_16x16x32_bf16 v[16:19], v[190:193], v[214:217], v[16:19]
	v_mfma_f32_16x16x32_bf16 v[4:7], v[182:185], v[222:225], v[4:7]
	v_mfma_f32_16x16x32_bf16 v[0:3], v[190:193], v[222:225], v[0:3]
	s_barrier
; #define PG8_STAGE(bufoff, gbase, voff) do { _Pragma("unroll") for (int _i = 0; _i < 2; ++_i) \
;         __builtin_amdgcn_global_load_lds((const unsigned*)((const char*)(gbase) + (voff)[_i]), (PG8_LAS unsigned*)(lds + (bufoff) + ldsw + _i * 8192), 16, 0, 0); } while (0)
; #define PG8_LDA(dst, b, h) do { _Pragma("unroll") for (int m = 0; m < 4; ++m) _Pragma("unroll") for (int k = 0; k < 2; ++k) dst[m][k] = *(const PG8_LAS bf16x8*)(lds + PG8_SA(b, h) + aoff + m * 2048 + k * 1024); } while (0)
; #define PG8_LDB(dst, b, h) do { _Pragma("unroll") for (int n = 0; n < 2; ++n) _Pragma("unroll") for (int k = 0; k < 2; ++k) dst[n][k] = *(const PG8_LAS bf16x8*)(lds + PG8_SB(b, h) + boff + n * 2048 + k * 1024); } while (0)
; #define PG8_MMA(ai, bj, At, Bt) do { __builtin_amdgcn_s_setprio(1); _Pragma("unroll") for (int m = 0; m < 4; ++m) _Pragma("unroll") for (int n = 0; n < 2; ++n) _Pragma("unroll") for (int k = 0; k < 2; ++k) \
;         acc[ai][bj][m][n] = __builtin_amdgcn_mfma_f32_16x16x32_bf16(Bt[n][k], At[m][k], acc[ai][bj][m][n], 0, 0, 0); __builtin_amdgcn_s_setprio(0); } while (0)
; #define PG8_WAIT_V(n) asm volatile("s_waitcnt vmcnt(" #n ")" ::: "memory")
; #define PG8_WAIT_L(n) asm volatile("s_waitcnt lgkmcnt(" #n ")" ::: "memory")
; #define PG8_BAR __builtin_amdgcn_s_barrier()
; #define PG8_SCHED __builtin_amdgcn_sched_barrier(0)
; template <class Epi, class Sched, bool ALIGN_EPI = false, bool SP2 = false>
; __device__ __forceinline__ void gemm_phase(PG8_LAS unsigned char* lds, const Gemm g, const Sched& S, const Epi& E) {
;     ...
;             PG8_LDB(B0, 1, 0); PG8_LDB(B1, 1, 1); PG8_SCHED; PG8_LDA(At, 1, 0); PG8_STAGE(PG8_SA(0, 1), a2 + hstep, voffA);
;             PG8_WAIT_V(8); PG8_WAIT_L(0); PG8_BAR; PG8_MMA(0, 0, At, B0); PG8_MMA(0, 1, At, B1); PG8_BAR; PG8_SCHED;
;             PG8_LDA(At, 1, 1); PG8_STAGE(PG8_SB(1, 0), b3, voffB); PG8_STAGE(PG8_SB(1, 1), b3 + hstep, voffB); PG8_STAGE(PG8_SA(1, 0), a3, voffA);
;             PG8_WAIT_V(8); PG8_WAIT_L(0); PG8_BAR; PG8_MMA(1, 0, At, B0); PG8_MMA(1, 1, At, B1); PG8_BAR; PG8_SCHED;
	s_setprio 0
	s_add_i32 s71, 0, 0x18000
	v_add_u32_e32 v130, s71, v160
	s_add_i32 s72, 0, 0x1c000
	ds_read_b128 v[148:151], v130
	ds_read_b128 v[166:169], v130 offset:1024
	ds_read_b128 v[170:173], v130 offset:2048
	ds_read_b128 v[174:177], v130 offset:3072
	v_add_u32_e32 v130, s72, v160
	ds_read_b128 v[178:181], v130
	ds_read_b128 v[182:185], v130 offset:1024
	ds_read_b128 v[186:189], v130 offset:2048
	ds_read_b128 v[190:193], v130 offset:3072
	s_add_u32 s42, s42, 0x40000
	s_addc_u32 s43, s43, 0
	s_mov_b32 m0, s54
	v_lshl_add_u64 v[234:235], s[42:43], 0, v[136:137]
	ds_read_b128 v[194:197], v164 offset:32768
	ds_read_b128 v[198:201], v164 offset:33792
	ds_read_b128 v[202:205], v164 offset:34816
	ds_read_b128 v[206:209], v164 offset:35840
	ds_read_b128 v[210:213], v164 offset:36864
	ds_read_b128 v[214:217], v164 offset:37888
	ds_read_b128 v[218:221], v164 offset:38912
	ds_read_b128 v[222:225], v164 offset:39936
	global_load_lds_dwordx4 v[234:235], off
	v_lshl_add_u64 v[234:235], s[42:43], 0, v[140:141]
	s_mov_b32 m0, s55
	s_nop 0
	global_load_lds_dwordx4 v[234:235], off
	s_waitcnt vmcnt(8)
	s_waitcnt lgkmcnt(0)
	s_setprio 1
	s_barrier
	v_mfma_f32_16x16x32_bf16 v[124:127], v[148:151], v[194:197], v[124:127]
	v_mfma_f32_16x16x32_bf16 v[120:123], v[170:173], v[194:197], v[120:123]
	v_mfma_f32_16x16x32_bf16 v[108:111], v[148:151], v[202:205], v[108:111]
	v_mfma_f32_16x16x32_bf16 v[104:107], v[170:173], v[202:205], v[104:107]
	v_mfma_f32_16x16x32_bf16 v[92:95], v[148:151], v[210:213], v[92:95]
	v_mfma_f32_16x16x32_bf16 v[88:91], v[170:173], v[210:213], v[88:91]
	v_mfma_f32_16x16x32_bf16 v[76:79], v[148:151], v[218:221], v[76:79]
	v_mfma_f32_16x16x32_bf16 v[72:75], v[170:173], v[218:221], v[72:75]
	v_mfma_f32_16x16x32_bf16 v[124:127], v[166:169], v[198:201], v[124:127]
	v_mfma_f32_16x16x32_bf16 v[120:123], v[174:177], v[198:201], v[120:123]
	v_mfma_f32_16x16x32_bf16 v[108:111], v[166:169], v[206:209], v[108:111]
	v_mfma_f32_16x16x32_bf16 v[104:107], v[174:177], v[206:209], v[104:107]
	v_mfma_f32_16x16x32_bf16 v[92:95], v[166:169], v[214:217], v[92:95]
	v_mfma_f32_16x16x32_bf16 v[88:91], v[174:177], v[214:217], v[88:91]
	v_mfma_f32_16x16x32_bf16 v[76:79], v[166:169], v[222:225], v[76:79]
	v_mfma_f32_16x16x32_bf16 v[72:75], v[174:177], v[222:225], v[72:75]
	v_mfma_f32_16x16x32_bf16 v[116:119], v[178:181], v[194:197], v[116:119]
	v_mfma_f32_16x16x32_bf16 v[112:115], v[186:189], v[194:197], v[112:115]
	v_mfma_f32_16x16x32_bf16 v[100:103], v[178:181], v[202:205], v[100:103]
	v_mfma_f32_16x16x32_bf16 v[96:99], v[186:189], v[202:205], v[96:99]
	v_mfma_f32_16x16x32_bf16 v[84:87], v[178:181], v[210:213], v[84:87]
	v_mfma_f32_16x16x32_bf16 v[80:83], v[186:189], v[210:213], v[80:83]
	v_mfma_f32_16x16x32_bf16 v[68:71], v[178:181], v[218:221], v[68:71]
	v_mfma_f32_16x16x32_bf16 v[64:67], v[186:189], v[218:221], v[64:67]
	v_mfma_f32_16x16x32_bf16 v[116:119], v[182:185], v[198:201], v[116:119]
	v_mfma_f32_16x16x32_bf16 v[112:115], v[190:193], v[198:201], v[112:115]
	v_mfma_f32_16x16x32_bf16 v[100:103], v[182:185], v[206:209], v[100:103]
	v_mfma_f32_16x16x32_bf16 v[96:99], v[190:193], v[206:209], v[96:99]
	v_mfma_f32_16x16x32_bf16 v[84:87], v[182:185], v[214:217], v[84:87]
	v_mfma_f32_16x16x32_bf16 v[80:83], v[190:193], v[214:217], v[80:83]
	v_mfma_f32_16x16x32_bf16 v[68:71], v[182:185], v[222:225], v[68:71]
	v_mfma_f32_16x16x32_bf16 v[64:67], v[190:193], v[222:225], v[64:67]
	s_barrier
	s_setprio 0
	s_add_i32 s42, s71, s33
	v_lshl_add_u64 v[226:227], v[226:227], 0, s[24:25]
	s_mov_b32 m0, s42
	ds_read_b128 v[194:197], v164 offset:49152
	ds_read_b128 v[198:201], v164 offset:50176
	ds_read_b128 v[202:205], v164 offset:51200
	ds_read_b128 v[206:209], v164 offset:52224
	ds_read_b128 v[210:213], v164 offset:53248
	ds_read_b128 v[214:217], v164 offset:54272
	ds_read_b128 v[218:221], v164 offset:55296
	ds_read_b128 v[222:225], v164 offset:56320
	global_load_lds_dwordx4 v[226:227], off
	s_add_i32 m0, s42, 0x2000
	s_add_u32 s40, s40, 0x40080
	v_lshl_add_u64 v[226:227], v[228:229], 0, s[24:25]
	s_addc_u32 s41, s41, 0
	s_add_i32 s42, s72, s33
	global_load_lds_dwordx4 v[226:227], off
	v_lshl_add_u64 v[226:227], s[40:41], 0, v[138:139]
	s_mov_b32 m0, s42
	s_nop 0
	global_load_lds_dwordx4 v[226:227], off
	v_lshl_add_u64 v[226:227], s[40:41], 0, v[142:143]
	s_add_i32 m0, s42, 0x2000
	s_nop 0
	global_load_lds_dwordx4 v[226:227], off
	v_lshl_add_u64 v[226:227], v[230:231], 0, s[24:25]
	s_mov_b32 m0, s57
	s_nop 0
	global_load_lds_dwordx4 v[226:227], off
	v_lshl_add_u64 v[226:227], v[232:233], 0, s[24:25]
	s_mov_b32 m0, s58
	s_nop 0
	global_load_lds_dwordx4 v[226:227], off
	s_waitcnt vmcnt(8)
	s_waitcnt lgkmcnt(0)
	s_setprio 1
	s_barrier
	v_mfma_f32_16x16x32_bf16 v[60:63], v[148:151], v[194:197], v[60:63]
	v_mfma_f32_16x16x32_bf16 v[56:59], v[170:173], v[194:197], v[56:59]
	v_mfma_f32_16x16x32_bf16 v[44:47], v[148:151], v[202:205], v[44:47]
	v_mfma_f32_16x16x32_bf16 v[40:43], v[170:173], v[202:205], v[40:43]
	v_mfma_f32_16x16x32_bf16 v[28:31], v[148:151], v[210:213], v[28:31]
	v_mfma_f32_16x16x32_bf16 v[24:27], v[170:173], v[210:213], v[24:27]
	v_mfma_f32_16x16x32_bf16 v[12:15], v[148:151], v[218:221], v[12:15]
	v_mfma_f32_16x16x32_bf16 v[8:11], v[170:173], v[218:221], v[8:11]
	v_mfma_f32_16x16x32_bf16 v[60:63], v[166:169], v[198:201], v[60:63]
	v_mfma_f32_16x16x32_bf16 v[56:59], v[174:177], v[198:201], v[56:59]
	v_mfma_f32_16x16x32_bf16 v[44:47], v[166:169], v[206:209], v[44:47]
	v_mfma_f32_16x16x32_bf16 v[40:43], v[174:177], v[206:209], v[40:43]
	v_mfma_f32_16x16x32_bf16 v[28:31], v[166:169], v[214:217], v[28:31]
	v_mfma_f32_16x16x32_bf16 v[24:27], v[174:177], v[214:217], v[24:27]
	v_mfma_f32_16x16x32_bf16 v[12:15], v[166:169], v[222:225], v[12:15]
	v_mfma_f32_16x16x32_bf16 v[8:11], v[174:177], v[222:225], v[8:11]
	v_mfma_f32_16x16x32_bf16 v[52:55], v[178:181], v[194:197], v[52:55]
	v_mfma_f32_16x16x32_bf16 v[48:51], v[186:189], v[194:197], v[48:51]
	v_mfma_f32_16x16x32_bf16 v[36:39], v[178:181], v[202:205], v[36:39]
	v_mfma_f32_16x16x32_bf16 v[32:35], v[186:189], v[202:205], v[32:35]
	v_mfma_f32_16x16x32_bf16 v[20:23], v[178:181], v[210:213], v[20:23]
	v_mfma_f32_16x16x32_bf16 v[16:19], v[186:189], v[210:213], v[16:19]
	v_mfma_f32_16x16x32_bf16 v[4:7], v[178:181], v[218:221], v[4:7]
	v_mfma_f32_16x16x32_bf16 v[0:3], v[186:189], v[218:221], v[0:3]
	v_mfma_f32_16x16x32_bf16 v[52:55], v[182:185], v[198:201], v[52:55]
	v_mfma_f32_16x16x32_bf16 v[48:51], v[190:193], v[198:201], v[48:51]
	v_mfma_f32_16x16x32_bf16 v[36:39], v[182:185], v[206:209], v[36:39]
	v_mfma_f32_16x16x32_bf16 v[32:35], v[190:193], v[206:209], v[32:35]
	v_mfma_f32_16x16x32_bf16 v[20:23], v[182:185], v[214:217], v[20:23]
	v_mfma_f32_16x16x32_bf16 v[16:19], v[190:193], v[214:217], v[16:19]
	v_mfma_f32_16x16x32_bf16 v[4:7], v[182:185], v[222:225], v[4:7]
	v_mfma_f32_16x16x32_bf16 v[0:3], v[190:193], v[222:225], v[0:3]
	s_barrier
	s_setprio 0
	s_add_i32 s70, s70, 2
	s_add_u32 s38, s38, 0x100
	s_addc_u32 s39, s39, 0
	s_add_u32 s44, s44, 0x100
	s_addc_u32 s45, s45, 0
	s_cmp_gt_u32 s70, 13
; #define PG8_STAGE(bufoff, gbase, voff) do { _Pragma("unroll") for (int _i = 0; _i < 2; ++_i) \
;         __builtin_amdgcn_global_load_lds((const unsigned*)((const char*)(gbase) + (voff)[_i]), (PG8_LAS unsigned*)(lds + (bufoff) + ldsw + _i * 8192), 16, 0, 0); } while (0)
; #define PG8_LDA(dst, b, h) do { _Pragma("unroll") for (int m = 0; m < 4; ++m) _Pragma("unroll") for (int k = 0; k < 2; ++k) dst[m][k] = *(const PG8_LAS bf16x8*)(lds + PG8_SA(b, h) + aoff + m * 2048 + k * 1024); } while (0)
; #define PG8_LDB(dst, b, h) do { _Pragma("unroll") for (int n = 0; n < 2; ++n) _Pragma("unroll") for (int k = 0; k < 2; ++k) dst[n][k] = *(const PG8_LAS bf16x8*)(lds + PG8_SB(b, h) + boff + n * 2048 + k * 1024); } while (0)
; #define PG8_MMA(ai, bj, At, Bt) do { __builtin_amdgcn_s_setprio(1); _Pragma("unroll") for (int m = 0; m < 4; ++m) _Pragma("unroll") for (int n = 0; n < 2; ++n) _Pragma("unroll") for (int k = 0; k < 2; ++k) \
;         acc[ai][bj][m][n] = __builtin_amdgcn_mfma_f32_16x16x32_bf16(Bt[n][k], At[m][k], acc[ai][bj][m][n], 0, 0, 0); __builtin_amdgcn_s_setprio(0); } while (0)
; #define PG8_WAIT_V(n) asm volatile("s_waitcnt vmcnt(" #n ")" ::: "memory")
; #define PG8_WAIT_L(n) asm volatile("s_waitcnt lgkmcnt(" #n ")" ::: "memory")
; #define PG8_BAR __builtin_amdgcn_s_barrier()
; #define PG8_SCHED __builtin_amdgcn_sched_barrier(0)
; template <class Epi, class Sched, bool ALIGN_EPI = false, bool SP2 = false>
; __device__ __forceinline__ void gemm_phase(PG8_LAS unsigned char* lds, const Gemm g, const Sched& S, const Epi& E) {
;     ...
;             PG8_LDB(B0, 0, 0); PG8_LDB(B1, 0, 1); PG8_SCHED; PG8_LDA(At, 0, 0); PG8_STAGE(PG8_SA(1, 1), a1 + hstep, voffA);
;             PG8_WAIT_V(8); PG8_WAIT_L(0); PG8_BAR; PG8_MMA(0, 0, At, B0); PG8_MMA(0, 1, At, B1); PG8_BAR; PG8_SCHED;
;             PG8_LDA(At, 0, 1); PG8_STAGE(PG8_SB(0, 0), b2, voffB); PG8_STAGE(PG8_SB(0, 1), b2 + hstep, voffB); PG8_STAGE(PG8_SA(0, 0), a2, voffA);
;             PG8_WAIT_V(8); PG8_WAIT_L(0); PG8_BAR; PG8_MMA(1, 0, At, B0); PG8_MMA(1, 1, At, B1); PG8_BAR; PG8_SCHED;
.LBB0_509:
	ds_read_b128 v[148:151], v162
	ds_read_b128 v[166:169], v162 offset:1024
	ds_read_b128 v[170:173], v162 offset:2048
	ds_read_b128 v[174:177], v162 offset:3072
	ds_read_b128 v[178:181], v163
	ds_read_b128 v[182:185], v163 offset:1024
	ds_read_b128 v[186:189], v163 offset:2048
	ds_read_b128 v[190:193], v163 offset:3072
	s_add_u32 s40, s38, 0xfffc0080
	s_addc_u32 s41, s39, -1
	s_cmp_eq_u32 s70, 12
	s_cselect_b32 s43, s9, s41
	s_cselect_b32 s42, s14, s40
	s_cselect_b32 s41, s29, s45
	s_cselect_b32 s40, s31, s44
	v_lshl_add_u64 v[226:227], s[38:39], 0, v[132:133]
	s_add_i32 m0, s52, 0xc000
	ds_read_b128 v[194:197], v164
	ds_read_b128 v[198:201], v164 offset:1024
	ds_read_b128 v[202:205], v164 offset:2048
	ds_read_b128 v[206:209], v164 offset:3072
	ds_read_b128 v[210:213], v164 offset:4096
	ds_read_b128 v[214:217], v164 offset:5120
	ds_read_b128 v[218:221], v164 offset:6144
	ds_read_b128 v[222:225], v164 offset:7168
	global_load_lds_dwordx4 v[226:227], off
	v_lshl_add_u64 v[226:227], s[38:39], 0, v[134:135]
	s_add_i32 m0, s52, 0xe000
	s_nop 0
	global_load_lds_dwordx4 v[226:227], off
	s_waitcnt vmcnt(8)
	s_waitcnt lgkmcnt(0)
	s_setprio 1
	s_barrier
	v_mfma_f32_16x16x32_bf16 v[124:127], v[148:151], v[194:197], v[124:127]
	v_mfma_f32_16x16x32_bf16 v[120:123], v[170:173], v[194:197], v[120:123]
	v_mfma_f32_16x16x32_bf16 v[108:111], v[148:151], v[202:205], v[108:111]
	v_mfma_f32_16x16x32_bf16 v[104:107], v[170:173], v[202:205], v[104:107]
	v_mfma_f32_16x16x32_bf16 v[92:95], v[148:151], v[210:213], v[92:95]
	v_mfma_f32_16x16x32_bf16 v[88:91], v[170:173], v[210:213], v[88:91]
	v_mfma_f32_16x16x32_bf16 v[76:79], v[148:151], v[218:221], v[76:79]
	v_mfma_f32_16x16x32_bf16 v[72:75], v[170:173], v[218:221], v[72:75]
	v_mfma_f32_16x16x32_bf16 v[124:127], v[166:169], v[198:201], v[124:127]
	v_mfma_f32_16x16x32_bf16 v[120:123], v[174:177], v[198:201], v[120:123]
	v_mfma_f32_16x16x32_bf16 v[108:111], v[166:169], v[206:209], v[108:111]
	v_mfma_f32_16x16x32_bf16 v[104:107], v[174:177], v[206:209], v[104:107]
	v_mfma_f32_16x16x32_bf16 v[92:95], v[166:169], v[214:217], v[92:95]
	v_mfma_f32_16x16x32_bf16 v[88:91], v[174:177], v[214:217], v[88:91]
	v_mfma_f32_16x16x32_bf16 v[76:79], v[166:169], v[222:225], v[76:79]
	v_mfma_f32_16x16x32_bf16 v[72:75], v[174:177], v[222:225], v[72:75]
	v_mfma_f32_16x16x32_bf16 v[116:119], v[178:181], v[194:197], v[116:119]
	v_mfma_f32_16x16x32_bf16 v[112:115], v[186:189], v[194:197], v[112:115]
	v_mfma_f32_16x16x32_bf16 v[100:103], v[178:181], v[202:205], v[100:103]
	v_mfma_f32_16x16x32_bf16 v[96:99], v[186:189], v[202:205], v[96:99]
	v_mfma_f32_16x16x32_bf16 v[84:87], v[178:181], v[210:213], v[84:87]
	v_mfma_f32_16x16x32_bf16 v[80:83], v[186:189], v[210:213], v[80:83]
	v_mfma_f32_16x16x32_bf16 v[68:71], v[178:181], v[218:221], v[68:71]
	v_mfma_f32_16x16x32_bf16 v[64:67], v[186:189], v[218:221], v[64:67]
	v_mfma_f32_16x16x32_bf16 v[116:119], v[182:185], v[198:201], v[116:119]
	v_mfma_f32_16x16x32_bf16 v[112:115], v[190:193], v[198:201], v[112:115]
	v_mfma_f32_16x16x32_bf16 v[100:103], v[182:185], v[206:209], v[100:103]
	v_mfma_f32_16x16x32_bf16 v[96:99], v[190:193], v[206:209], v[96:99]
	v_mfma_f32_16x16x32_bf16 v[84:87], v[182:185], v[214:217], v[84:87]
	v_mfma_f32_16x16x32_bf16 v[80:83], v[190:193], v[214:217], v[80:83]
	v_mfma_f32_16x16x32_bf16 v[68:71], v[182:185], v[222:225], v[68:71]
	v_mfma_f32_16x16x32_bf16 v[64:67], v[190:193], v[222:225], v[64:67]
	s_barrier
	s_setprio 0
	s_add_i32 s71, s61, s33
	v_lshl_add_u64 v[226:227], s[40:41], 0, v[138:139]
	s_mov_b32 m0, s71
	ds_read_b128 v[194:197], v164 offset:16384
	ds_read_b128 v[198:201], v164 offset:17408
	ds_read_b128 v[202:205], v164 offset:18432
	ds_read_b128 v[206:209], v164 offset:19456
	ds_read_b128 v[210:213], v164 offset:20480
	ds_read_b128 v[214:217], v164 offset:21504
	ds_read_b128 v[218:221], v164 offset:22528
	ds_read_b128 v[222:225], v164 offset:23552
	global_load_lds_dwordx4 v[226:227], off
	s_add_i32 m0, s71, 0x2000
	s_add_u32 s72, s40, 0x40000
	v_lshl_add_u64 v[228:229], s[40:41], 0, v[142:143]
	s_addc_u32 s73, s41, 0
	s_add_i32 s71, s62, s33
	global_load_lds_dwordx4 v[228:229], off
	v_lshl_add_u64 v[230:231], s[72:73], 0, v[138:139]
	s_mov_b32 m0, s71
	v_lshl_add_u64 v[232:233], s[42:43], 0, v[140:141]
	global_load_lds_dwordx4 v[230:231], off
	v_lshl_add_u64 v[230:231], s[72:73], 0, v[142:143]
	s_add_i32 m0, s71, 0x2000
	s_nop 0
	global_load_lds_dwordx4 v[230:231], off
	v_lshl_add_u64 v[230:231], s[42:43], 0, v[136:137]
	s_mov_b32 m0, s52
	s_nop 0
	global_load_lds_dwordx4 v[230:231], off
	s_mov_b32 m0, s53
	s_nop 0
	global_load_lds_dwordx4 v[232:233], off
	s_waitcnt vmcnt(8)
	s_waitcnt lgkmcnt(0)
	s_setprio 1
	s_barrier
; #define PG8_STAGE(bufoff, gbase, voff) do { _Pragma("unroll") for (int _i = 0; _i < 2; ++_i) \
;         __builtin_amdgcn_global_load_lds((const unsigned*)((const char*)(gbase) + (voff)[_i]), (PG8_LAS unsigned*)(lds + (bufoff) + ldsw + _i * 8192), 16, 0, 0); } while (0)
; #define PG8_LDA(dst, b, h) do { _Pragma("unroll") for (int m = 0; m < 4; ++m) _Pragma("unroll") for (int k = 0; k < 2; ++k) dst[m][k] = *(const PG8_LAS bf16x8*)(lds + PG8_SA(b, h) + aoff + m * 2048 + k * 1024); } while (0)
; #define PG8_LDB(dst, b, h) do { _Pragma("unroll") for (int n = 0; n < 2; ++n) _Pragma("unroll") for (int k = 0; k < 2; ++k) dst[n][k] = *(const PG8_LAS bf16x8*)(lds + PG8_SB(b, h) + boff + n * 2048 + k * 1024); } while (0)
; #define PG8_MMA(ai, bj, At, Bt) do { __builtin_amdgcn_s_setprio(1); _Pragma("unroll") for (int m = 0; m < 4; ++m) _Pragma("unroll") for (int n = 0; n < 2; ++n) _Pragma("unroll") for (int k = 0; k < 2; ++k) \
;         acc[ai][bj][m][n] = __builtin_amdgcn_mfma_f32_16x16x32_bf16(Bt[n][k], At[m][k], acc[ai][bj][m][n], 0, 0, 0); __builtin_amdgcn_s_setprio(0); } while (0)
; #define PG8_WAIT_V(n) asm volatile("s_waitcnt vmcnt(" #n ")" ::: "memory")
; #define PG8_WAIT_L(n) asm volatile("s_waitcnt lgkmcnt(" #n ")" ::: "memory")
; #define PG8_BAR __builtin_amdgcn_s_barrier()
; #define PG8_SCHED __builtin_amdgcn_sched_barrier(0)
; template <class Epi, class Sched, bool ALIGN_EPI = false, bool SP2 = false>
; __device__ __forceinline__ void gemm_phase(PG8_LAS unsigned char* lds, const Gemm g, const Sched& S, const Epi& E) {
;     ...
;             PG8_WAIT_V(8); PG8_WAIT_L(0); PG8_BAR; PG8_MMA(1, 0, At, B0); PG8_MMA(1, 1, At, B1); PG8_BAR; PG8_SCHED;
;             PG8_LDB(B0, 1, 0); PG8_LDB(B1, 1, 1); PG8_SCHED; PG8_LDA(At, 1, 0); PG8_STAGE(PG8_SA(0, 1), a2 + hstep, voffA);
;             PG8_WAIT_V(8); PG8_WAIT_L(0); PG8_BAR; PG8_MMA(0, 0, At, B0); PG8_MMA(0, 1, At, B1); PG8_BAR; PG8_SCHED;
	v_mfma_f32_16x16x32_bf16 v[60:63], v[148:151], v[194:197], v[60:63]
	v_mfma_f32_16x16x32_bf16 v[56:59], v[170:173], v[194:197], v[56:59]
	v_mfma_f32_16x16x32_bf16 v[44:47], v[148:151], v[202:205], v[44:47]
	v_mfma_f32_16x16x32_bf16 v[40:43], v[170:173], v[202:205], v[40:43]
	v_mfma_f32_16x16x32_bf16 v[28:31], v[148:151], v[210:213], v[28:31]
	v_mfma_f32_16x16x32_bf16 v[24:27], v[170:173], v[210:213], v[24:27]
	v_mfma_f32_16x16x32_bf16 v[12:15], v[148:151], v[218:221], v[12:15]
	v_mfma_f32_16x16x32_bf16 v[8:11], v[170:173], v[218:221], v[8:11]
	v_mfma_f32_16x16x32_bf16 v[60:63], v[166:169], v[198:201], v[60:63]
	v_mfma_f32_16x16x32_bf16 v[56:59], v[174:177], v[198:201], v[56:59]
	v_mfma_f32_16x16x32_bf16 v[44:47], v[166:169], v[206:209], v[44:47]
	v_mfma_f32_16x16x32_bf16 v[40:43], v[174:177], v[206:209], v[40:43]
	v_mfma_f32_16x16x32_bf16 v[28:31], v[166:169], v[214:217], v[28:31]
	v_mfma_f32_16x16x32_bf16 v[24:27], v[174:177], v[214:217], v[24:27]
	v_mfma_f32_16x16x32_bf16 v[12:15], v[166:169], v[222:225], v[12:15]
	v_mfma_f32_16x16x32_bf16 v[8:11], v[174:177], v[222:225], v[8:11]
	v_mfma_f32_16x16x32_bf16 v[52:55], v[178:181], v[194:197], v[52:55]
	v_mfma_f32_16x16x32_bf16 v[48:51], v[186:189], v[194:197], v[48:51]
	v_mfma_f32_16x16x32_bf16 v[36:39], v[178:181], v[202:205], v[36:39]
	v_mfma_f32_16x16x32_bf16 v[32:35], v[186:189], v[202:205], v[32:35]
	v_mfma_f32_16x16x32_bf16 v[20:23], v[178:181], v[210:213], v[20:23]
	v_mfma_f32_16x16x32_bf16 v[16:19], v[186:189], v[210:213], v[16:19]
	v_mfma_f32_16x16x32_bf16 v[4:7], v[178:181], v[218:221], v[4:7]
	v_mfma_f32_16x16x32_bf16 v[0:3], v[186:189], v[218:221], v[0:3]
	v_mfma_f32_16x16x32_bf16 v[52:55], v[182:185], v[198:201], v[52:55]
	v_mfma_f32_16x16x32_bf16 v[48:51], v[190:193], v[198:201], v[48:51]
	v_mfma_f32_16x16x32_bf16 v[36:39], v[182:185], v[206:209], v[36:39]
	v_mfma_f32_16x16x32_bf16 v[32:35], v[190:193], v[206:209], v[32:35]
	v_mfma_f32_16x16x32_bf16 v[20:23], v[182:185], v[214:217], v[20:23]
	v_mfma_f32_16x16x32_bf16 v[16:19], v[190:193], v[214:217], v[16:19]
	v_mfma_f32_16x16x32_bf16 v[4:7], v[182:185], v[222:225], v[4:7]
	v_mfma_f32_16x16x32_bf16 v[0:3], v[190:193], v[222:225], v[0:3]
	s_barrier
	s_setprio 0
	s_add_i32 s71, 0, 0x18000
	v_add_u32_e32 v130, s71, v160
	s_add_i32 s72, 0, 0x1c000
	ds_read_b128 v[148:151], v130
	ds_read_b128 v[166:169], v130 offset:1024
	ds_read_b128 v[170:173], v130 offset:2048
	ds_read_b128 v[174:177], v130 offset:3072
	v_add_u32_e32 v130, s72, v160
	ds_read_b128 v[178:181], v130
	ds_read_b128 v[182:185], v130 offset:1024
	ds_read_b128 v[186:189], v130 offset:2048
	ds_read_b128 v[190:193], v130 offset:3072
	s_add_u32 s42, s42, 0x40000
	s_addc_u32 s43, s43, 0
	s_mov_b32 m0, s54
	v_lshl_add_u64 v[234:235], s[42:43], 0, v[136:137]
	ds_read_b128 v[194:197], v164 offset:32768
	ds_read_b128 v[198:201], v164 offset:33792
	ds_read_b128 v[202:205], v164 offset:34816
	ds_read_b128 v[206:209], v164 offset:35840
	ds_read_b128 v[210:213], v164 offset:36864
	ds_read_b128 v[214:217], v164 offset:37888
	ds_read_b128 v[218:221], v164 offset:38912
	ds_read_b128 v[222:225], v164 offset:39936
	global_load_lds_dwordx4 v[234:235], off
	v_lshl_add_u64 v[234:235], s[42:43], 0, v[140:141]
	s_mov_b32 m0, s55
	s_nop 0
	global_load_lds_dwordx4 v[234:235], off
	s_waitcnt vmcnt(8)
	s_waitcnt lgkmcnt(0)
	s_setprio 1
	s_barrier
	v_mfma_f32_16x16x32_bf16 v[124:127], v[148:151], v[194:197], v[124:127]
	v_mfma_f32_16x16x32_bf16 v[120:123], v[170:173], v[194:197], v[120:123]
	v_mfma_f32_16x16x32_bf16 v[108:111], v[148:151], v[202:205], v[108:111]
	v_mfma_f32_16x16x32_bf16 v[104:107], v[170:173], v[202:205], v[104:107]
	v_mfma_f32_16x16x32_bf16 v[92:95], v[148:151], v[210:213], v[92:95]
	v_mfma_f32_16x16x32_bf16 v[88:91], v[170:173], v[210:213], v[88:91]
	v_mfma_f32_16x16x32_bf16 v[76:79], v[148:151], v[218:221], v[76:79]
	v_mfma_f32_16x16x32_bf16 v[72:75], v[170:173], v[218:221], v[72:75]
	v_mfma_f32_16x16x32_bf16 v[124:127], v[166:169], v[198:201], v[124:127]
	v_mfma_f32_16x16x32_bf16 v[120:123], v[174:177], v[198:201], v[120:123]
	v_mfma_f32_16x16x32_bf16 v[108:111], v[166:169], v[206:209], v[108:111]
	v_mfma_f32_16x16x32_bf16 v[104:107], v[174:177], v[206:209], v[104:107]
	v_mfma_f32_16x16x32_bf16 v[92:95], v[166:169], v[214:217], v[92:95]
	v_mfma_f32_16x16x32_bf16 v[88:91], v[174:177], v[214:217], v[88:91]
	v_mfma_f32_16x16x32_bf16 v[76:79], v[166:169], v[222:225], v[76:79]
	v_mfma_f32_16x16x32_bf16 v[72:75], v[174:177], v[222:225], v[72:75]
	v_mfma_f32_16x16x32_bf16 v[116:119], v[178:181], v[194:197], v[116:119]
	v_mfma_f32_16x16x32_bf16 v[112:115], v[186:189], v[194:197], v[112:115]
	v_mfma_f32_16x16x32_bf16 v[100:103], v[178:181], v[202:205], v[100:103]
	v_mfma_f32_16x16x32_bf16 v[96:99], v[186:189], v[202:205], v[96:99]
	v_mfma_f32_16x16x32_bf16 v[84:87], v[178:181], v[210:213], v[84:87]
	v_mfma_f32_16x16x32_bf16 v[80:83], v[186:189], v[210:213], v[80:83]
	v_mfma_f32_16x16x32_bf16 v[68:71], v[178:181], v[218:221], v[68:71]
	v_mfma_f32_16x16x32_bf16 v[64:67], v[186:189], v[218:221], v[64:67]
	v_mfma_f32_16x16x32_bf16 v[116:119], v[182:185], v[198:201], v[116:119]
	v_mfma_f32_16x16x32_bf16 v[112:115], v[190:193], v[198:201], v[112:115]
	v_mfma_f32_16x16x32_bf16 v[100:103], v[182:185], v[206:209], v[100:103]
	v_mfma_f32_16x16x32_bf16 v[96:99], v[190:193], v[206:209], v[96:99]
	v_mfma_f32_16x16x32_bf16 v[84:87], v[182:185], v[214:217], v[84:87]
	v_mfma_f32_16x16x32_bf16 v[80:83], v[190:193], v[214:217], v[80:83]
	v_mfma_f32_16x16x32_bf16 v[68:71], v[182:185], v[222:225], v[68:71]
	v_mfma_f32_16x16x32_bf16 v[64:67], v[190:193], v[222:225], v[64:67]
	s_barrier
; #define PG8_STAGE(bufoff, gbase, voff) do { _Pragma("unroll") for (int _i = 0; _i < 2; ++_i) \
;         __builtin_amdgcn_global_load_lds((const unsigned*)((const char*)(gbase) + (voff)[_i]), (PG8_LAS unsigned*)(lds + (bufoff) + ldsw + _i * 8192), 16, 0, 0); } while (0)
; #define PG8_LDA(dst, b, h) do { _Pragma("unroll") for (int m = 0; m < 4; ++m) _Pragma("unroll") for (int k = 0; k < 2; ++k) dst[m][k] = *(const PG8_LAS bf16x8*)(lds + PG8_SA(b, h) + aoff + m * 2048 + k * 1024); } while (0)
; #define PG8_MMA(ai, bj, At, Bt) do { __builtin_amdgcn_s_setprio(1); _Pragma("unroll") for (int m = 0; m < 4; ++m) _Pragma("unroll") for (int n = 0; n < 2; ++n) _Pragma("unroll") for (int k = 0; k < 2; ++k) \
;         acc[ai][bj][m][n] = __builtin_amdgcn_mfma_f32_16x16x32_bf16(Bt[n][k], At[m][k], acc[ai][bj][m][n], 0, 0, 0); __builtin_amdgcn_s_setprio(0); } while (0)
; #define PG8_WAIT_V(n) asm volatile("s_waitcnt vmcnt(" #n ")" ::: "memory")
; #define PG8_WAIT_L(n) asm volatile("s_waitcnt lgkmcnt(" #n ")" ::: "memory")
; #define PG8_BAR __builtin_amdgcn_s_barrier()
; #define PG8_SCHED __builtin_amdgcn_sched_barrier(0)
; template <class Epi, class Sched, bool ALIGN_EPI = false, bool SP2 = false>
; __device__ __forceinline__ void gemm_phase(PG8_LAS unsigned char* lds, const Gemm g, const Sched& S, const Epi& E) {
;     ...
;             PG8_LDA(At, 1, 1); PG8_STAGE(PG8_SB(1, 0), b3, voffB); PG8_STAGE(PG8_SB(1, 1), b3 + hstep, voffB); PG8_STAGE(PG8_SA(1, 0), a3, voffA);
;             PG8_WAIT_V(8); PG8_WAIT_L(0); PG8_BAR; PG8_MMA(1, 0, At, B0); PG8_MMA(1, 1, At, B1); PG8_BAR; PG8_SCHED;
;     ...
;         if constexpr (ALIGN_EPI) { if (wr == 0) PG8_BAR; }
	s_setprio 0
	s_add_i32 s42, s71, s33
	v_lshl_add_u64 v[226:227], v[226:227], 0, s[24:25]
	s_mov_b32 m0, s42
	ds_read_b128 v[194:197], v164 offset:49152
	ds_read_b128 v[198:201], v164 offset:50176
	ds_read_b128 v[202:205], v164 offset:51200
	ds_read_b128 v[206:209], v164 offset:52224
	ds_read_b128 v[210:213], v164 offset:53248
	ds_read_b128 v[214:217], v164 offset:54272
	ds_read_b128 v[218:221], v164 offset:55296
	ds_read_b128 v[222:225], v164 offset:56320
	global_load_lds_dwordx4 v[226:227], off
	s_add_i32 m0, s42, 0x2000
	s_add_u32 s40, s40, 0x40080
	v_lshl_add_u64 v[226:227], v[228:229], 0, s[24:25]
	s_addc_u32 s41, s41, 0
	s_add_i32 s42, s72, s33
	global_load_lds_dwordx4 v[226:227], off
	v_lshl_add_u64 v[226:227], s[40:41], 0, v[138:139]
	s_mov_b32 m0, s42
	s_nop 0
	global_load_lds_dwordx4 v[226:227], off
	v_lshl_add_u64 v[226:227], s[40:41], 0, v[142:143]
	s_add_i32 m0, s42, 0x2000
	s_nop 0
	global_load_lds_dwordx4 v[226:227], off
	v_lshl_add_u64 v[226:227], v[230:231], 0, s[24:25]
	s_mov_b32 m0, s57
	s_nop 0
	global_load_lds_dwordx4 v[226:227], off
	v_lshl_add_u64 v[226:227], v[232:233], 0, s[24:25]
	s_mov_b32 m0, s58
	s_nop 0
	global_load_lds_dwordx4 v[226:227], off
	s_waitcnt vmcnt(8)
	s_waitcnt lgkmcnt(0)
	s_setprio 1
	s_barrier
	v_mfma_f32_16x16x32_bf16 v[60:63], v[148:151], v[194:197], v[60:63]
	v_mfma_f32_16x16x32_bf16 v[56:59], v[170:173], v[194:197], v[56:59]
	v_mfma_f32_16x16x32_bf16 v[44:47], v[148:151], v[202:205], v[44:47]
	v_mfma_f32_16x16x32_bf16 v[40:43], v[170:173], v[202:205], v[40:43]
	v_mfma_f32_16x16x32_bf16 v[28:31], v[148:151], v[210:213], v[28:31]
	v_mfma_f32_16x16x32_bf16 v[24:27], v[170:173], v[210:213], v[24:27]
	v_mfma_f32_16x16x32_bf16 v[12:15], v[148:151], v[218:221], v[12:15]
	v_mfma_f32_16x16x32_bf16 v[8:11], v[170:173], v[218:221], v[8:11]
	v_mfma_f32_16x16x32_bf16 v[60:63], v[166:169], v[198:201], v[60:63]
	v_mfma_f32_16x16x32_bf16 v[56:59], v[174:177], v[198:201], v[56:59]
	v_mfma_f32_16x16x32_bf16 v[44:47], v[166:169], v[206:209], v[44:47]
	v_mfma_f32_16x16x32_bf16 v[40:43], v[174:177], v[206:209], v[40:43]
	v_mfma_f32_16x16x32_bf16 v[28:31], v[166:169], v[214:217], v[28:31]
	v_mfma_f32_16x16x32_bf16 v[24:27], v[174:177], v[214:217], v[24:27]
	v_mfma_f32_16x16x32_bf16 v[12:15], v[166:169], v[222:225], v[12:15]
	v_mfma_f32_16x16x32_bf16 v[8:11], v[174:177], v[222:225], v[8:11]
	v_mfma_f32_16x16x32_bf16 v[52:55], v[178:181], v[194:197], v[52:55]
	v_mfma_f32_16x16x32_bf16 v[48:51], v[186:189], v[194:197], v[48:51]
	v_mfma_f32_16x16x32_bf16 v[36:39], v[178:181], v[202:205], v[36:39]
	v_mfma_f32_16x16x32_bf16 v[32:35], v[186:189], v[202:205], v[32:35]
	v_mfma_f32_16x16x32_bf16 v[20:23], v[178:181], v[210:213], v[20:23]
	v_mfma_f32_16x16x32_bf16 v[16:19], v[186:189], v[210:213], v[16:19]
	v_mfma_f32_16x16x32_bf16 v[4:7], v[178:181], v[218:221], v[4:7]
	v_mfma_f32_16x16x32_bf16 v[0:3], v[186:189], v[218:221], v[0:3]
	v_mfma_f32_16x16x32_bf16 v[52:55], v[182:185], v[198:201], v[52:55]
	v_mfma_f32_16x16x32_bf16 v[48:51], v[190:193], v[198:201], v[48:51]
	v_mfma_f32_16x16x32_bf16 v[36:39], v[182:185], v[206:209], v[36:39]
	v_mfma_f32_16x16x32_bf16 v[32:35], v[190:193], v[206:209], v[32:35]
	v_mfma_f32_16x16x32_bf16 v[20:23], v[182:185], v[214:217], v[20:23]
	v_mfma_f32_16x16x32_bf16 v[16:19], v[190:193], v[214:217], v[16:19]
	v_mfma_f32_16x16x32_bf16 v[4:7], v[182:185], v[222:225], v[4:7]
	v_mfma_f32_16x16x32_bf16 v[0:3], v[190:193], v[222:225], v[0:3]
	s_barrier
	s_setprio 0
	s_add_i32 s70, s70, 2
	s_add_u32 s38, s38, 0x100
	s_addc_u32 s39, s39, 0
	s_add_u32 s44, s44, 0x100
	s_addc_u32 s45, s45, 0
	s_cmp_gt_u32 s70, 13
	s_cbranch_scc0 .LBB0_509
	s_and_b64 vcc, exec, s[26:27]
	s_cbranch_vccz .LBB0_512
	s_barrier

; #define PG8_STAGE(bufoff, gbase, voff) do { _Pragma("unroll") for (int _i = 0; _i < 2; ++_i) \
;         __builtin_amdgcn_global_load_lds((const unsigned*)((const char*)(gbase) + (voff)[_i]), (PG8_LAS unsigned*)(lds + (bufoff) + ldsw + _i * 8192), 16, 0, 0); } while (0)
; #define PG8_LDA(dst, b, h) do { _Pragma("unroll") for (int m = 0; m < 4; ++m) _Pragma("unroll") for (int k = 0; k < 2; ++k) dst[m][k] = *(const PG8_LAS bf16x8*)(lds + PG8_SA(b, h) + aoff + m * 2048 + k * 1024); } while (0)
; #define PG8_LDB(dst, b, h) do { _Pragma("unroll") for (int n = 0; n < 2; ++n) _Pragma("unroll") for (int k = 0; k < 2; ++k) dst[n][k] = *(const PG8_LAS bf16x8*)(lds + PG8_SB(b, h) + boff + n * 2048 + k * 1024); } while (0)
; #define PG8_WAIT_V(n) asm volatile("s_waitcnt vmcnt(" #n ")" ::: "memory")
; #define PG8_WAIT_L(n) asm volatile("s_waitcnt lgkmcnt(" #n ")" ::: "memory")
; #define PG8_BAR __builtin_amdgcn_s_barrier()
; #define PG8_SCHED __builtin_amdgcn_sched_barrier(0)
; template <class Epi, class Sched, bool ALIGN_EPI = false, bool SP2 = false>
; __device__ __forceinline__ void gemm_phase(PG8_LAS unsigned char* lds, const Gemm g, const Sched& S, const Epi& E) {
;     ...
;         const char* nA = has_next ? (const char*)g.A + (size_t)nxt.pm * tstep : cA; const char* nB = has_next ? (const char*)g.Bt + (size_t)nxt.pn * tstep : cB;
;         for (int t = 0; t < nt; t += 2) {
;             const bool last = (t == nt - 2);
;             const char* a1 = cA + (size_t)(t + 1) * kstep;
;             const char* a2 = last ? nA : cA + (size_t)(t + 2) * kstep; const char* b2 = last ? nB : cB + (size_t)(t + 2) * kstep;
;             const char* a3 = a2 + kstep; const char* b3 = b2 + kstep;
;             if (last && has_next) S.a_ready(nxt, ui + 1);
;             if constexpr (SP2) {
;             PG8_LDB(B0, 0, 0); PG8_LDB(B1, 0, 1); PG8_SCHED; PG8_LDA(At, 0, 0); PG8_STAGE(PG8_SA(1, 1), a1 + hstep, voffA);
;             PG8_WAIT_V(8); PG8_WAIT_L(0); PG8_BAR; PG8_MMA(0, 0, At, B0); PG8_MMA(0, 1, At, B1); PG8_BAR; PG8_SCHED;
;             PG8_LDA(At, 0, 1); PG8_STAGE(PG8_SB(0, 0), b2, voffB); PG8_STAGE(PG8_SB(0, 1), b2 + hstep, voffB); PG8_STAGE(PG8_SA(0, 0), a2, voffA);
;             PG8_WAIT_V(8); PG8_WAIT_L(0); PG8_BAR; PG8_MMA(1, 0, At, B0); PG8_MMA(1, 1, At, B1); PG8_BAR; PG8_SCHED;
.LBB0_606:
	s_ashr_i32 s21, s20, 31
	s_lshl_b64 s[22:23], s[20:21], 19
	s_add_u32 s22, s36, s22
	s_addc_u32 s23, s37, s23
	s_and_b64 s[24:25], s[4:5], exec
	s_cselect_b32 s21, s23, s29
	s_cselect_b32 s55, s22, s28
	s_ashr_i32 s19, s18, 31
	s_lshl_b64 s[24:25], s[18:19], 19
	s_add_u32 s24, s48, s24
	s_addc_u32 s25, s49, s25
	s_and_b64 s[34:35], s[4:5], exec
	s_cselect_b32 s19, s25, s31
	s_cselect_b32 s56, s24, s30
	s_add_u32 s28, s28, 0x40080
	s_addc_u32 s29, s29, 0
	s_add_u32 s57, s30, 0x100
	s_addc_u32 s58, s31, 0
	s_mov_b32 s59, -2
	s_add_u32 s30, s28, 0xfffc0080
	s_addc_u32 s31, s29, -1
	s_cmp_eq_u32 s59, 12
	s_cselect_b32 s35, s21, s31
	s_cselect_b32 s34, s55, s30
	s_cselect_b32 s31, s19, s58
	s_cselect_b32 s30, s56, s57
	v_lshl_add_u64 v[160:161], s[28:29], 0, v[152:153]
	s_add_i32 m0, s38, 0xc000
	global_load_lds_dwordx4 v[160:161], off
	v_lshl_add_u64 v[160:161], s[28:29], 0, v[154:155]
	s_add_i32 m0, s38, 0xe000
	s_nop 0
	global_load_lds_dwordx4 v[160:161], off
	s_waitcnt vmcnt(8)
	s_waitcnt lgkmcnt(0)
	s_setprio 1
	s_barrier
	v_mfma_f32_16x16x32_bf16 v[124:127], v[128:131], v[198:201], 0
	v_mfma_f32_16x16x32_bf16 v[120:123], v[174:177], v[198:201], 0
	v_mfma_f32_16x16x32_bf16 v[116:119], v[128:131], v[206:209], 0
	v_mfma_f32_16x16x32_bf16 v[112:115], v[174:177], v[206:209], 0
	v_mfma_f32_16x16x32_bf16 v[108:111], v[128:131], v[214:217], 0
	v_mfma_f32_16x16x32_bf16 v[104:107], v[174:177], v[214:217], 0
	v_mfma_f32_16x16x32_bf16 v[100:103], v[128:131], v[222:225], 0
	v_mfma_f32_16x16x32_bf16 v[96:99], v[174:177], v[222:225], 0
	v_mfma_f32_16x16x32_bf16 v[124:127], v[132:135], v[202:205], v[124:127]
	v_mfma_f32_16x16x32_bf16 v[120:123], v[178:181], v[202:205], v[120:123]
	v_mfma_f32_16x16x32_bf16 v[116:119], v[132:135], v[210:213], v[116:119]
	v_mfma_f32_16x16x32_bf16 v[112:115], v[178:181], v[210:213], v[112:115]
	v_mfma_f32_16x16x32_bf16 v[108:111], v[132:135], v[218:221], v[108:111]
	v_mfma_f32_16x16x32_bf16 v[104:107], v[178:181], v[218:221], v[104:107]
	v_mfma_f32_16x16x32_bf16 v[100:103], v[132:135], v[226:229], v[100:103]
	v_mfma_f32_16x16x32_bf16 v[96:99], v[178:181], v[226:229], v[96:99]
	v_mfma_f32_16x16x32_bf16 v[60:63], v[182:185], v[198:201], 0
	v_mfma_f32_16x16x32_bf16 v[56:59], v[190:193], v[198:201], 0
	v_mfma_f32_16x16x32_bf16 v[52:55], v[182:185], v[206:209], 0
	v_mfma_f32_16x16x32_bf16 v[48:51], v[190:193], v[206:209], 0
	v_mfma_f32_16x16x32_bf16 v[44:47], v[182:185], v[214:217], 0
	v_mfma_f32_16x16x32_bf16 v[40:43], v[190:193], v[214:217], 0
	v_mfma_f32_16x16x32_bf16 v[36:39], v[182:185], v[222:225], 0
	v_mfma_f32_16x16x32_bf16 v[32:35], v[190:193], v[222:225], 0
	v_mfma_f32_16x16x32_bf16 v[60:63], v[186:189], v[202:205], v[60:63]
	v_mfma_f32_16x16x32_bf16 v[56:59], v[194:197], v[202:205], v[56:59]
	v_mfma_f32_16x16x32_bf16 v[52:55], v[186:189], v[210:213], v[52:55]
	v_mfma_f32_16x16x32_bf16 v[48:51], v[194:197], v[210:213], v[48:51]
	v_mfma_f32_16x16x32_bf16 v[44:47], v[186:189], v[218:221], v[44:47]
	v_mfma_f32_16x16x32_bf16 v[40:43], v[194:197], v[218:221], v[40:43]
	v_mfma_f32_16x16x32_bf16 v[36:39], v[186:189], v[226:229], v[36:39]
	v_mfma_f32_16x16x32_bf16 v[32:35], v[194:197], v[226:229], v[32:35]
	s_barrier
	s_setprio 0
	s_add_i32 s60, s45, s33
	v_lshl_add_u64 v[160:161], s[30:31], 0, v[138:139]
	s_mov_b32 m0, s60
	ds_read_b128 v[198:201], v172 offset:16384
	ds_read_b128 v[202:205], v172 offset:17408
	ds_read_b128 v[206:209], v172 offset:18432
	ds_read_b128 v[210:213], v172 offset:19456
	ds_read_b128 v[214:217], v172 offset:20480
	ds_read_b128 v[218:221], v172 offset:21504
	ds_read_b128 v[222:225], v172 offset:22528
	ds_read_b128 v[226:229], v172 offset:23552
	global_load_lds_dwordx4 v[160:161], off
	s_add_i32 m0, s60, 0x2000
	s_add_u32 s60, s30, 0x40000
	v_lshl_add_u64 v[230:231], s[30:31], 0, v[142:143]
	s_addc_u32 s61, s31, 0
	s_add_i32 s62, s50, s33
	global_load_lds_dwordx4 v[230:231], off
	v_lshl_add_u64 v[232:233], s[60:61], 0, v[138:139]
	s_mov_b32 m0, s62
	v_lshl_add_u64 v[234:235], s[34:35], 0, v[140:141]
	global_load_lds_dwordx4 v[232:233], off
	v_lshl_add_u64 v[232:233], s[60:61], 0, v[142:143]
	s_add_i32 m0, s62, 0x2000
	s_nop 0
	global_load_lds_dwordx4 v[232:233], off
	v_lshl_add_u64 v[232:233], s[34:35], 0, v[136:137]
	s_mov_b32 m0, s38
	s_nop 0
	global_load_lds_dwordx4 v[232:233], off
	s_mov_b32 m0, s39
	s_nop 0
	global_load_lds_dwordx4 v[234:235], off
	s_waitcnt vmcnt(8)
	s_waitcnt lgkmcnt(0)
	s_setprio 1
	s_barrier
	v_mfma_f32_16x16x32_bf16 v[92:95], v[128:131], v[198:201], 0
	v_mfma_f32_16x16x32_bf16 v[88:91], v[174:177], v[198:201], 0
	v_mfma_f32_16x16x32_bf16 v[84:87], v[128:131], v[206:209], 0
	v_mfma_f32_16x16x32_bf16 v[80:83], v[174:177], v[206:209], 0
	v_mfma_f32_16x16x32_bf16 v[76:79], v[128:131], v[214:217], 0
	v_mfma_f32_16x16x32_bf16 v[72:75], v[174:177], v[214:217], 0
	v_mfma_f32_16x16x32_bf16 v[68:71], v[128:131], v[222:225], 0
	v_mfma_f32_16x16x32_bf16 v[64:67], v[174:177], v[222:225], 0
	v_mfma_f32_16x16x32_bf16 v[92:95], v[132:135], v[202:205], v[92:95]
	v_mfma_f32_16x16x32_bf16 v[88:91], v[178:181], v[202:205], v[88:91]
	v_mfma_f32_16x16x32_bf16 v[84:87], v[132:135], v[210:213], v[84:87]
	v_mfma_f32_16x16x32_bf16 v[80:83], v[178:181], v[210:213], v[80:83]
	v_mfma_f32_16x16x32_bf16 v[76:79], v[132:135], v[218:221], v[76:79]
	v_mfma_f32_16x16x32_bf16 v[72:75], v[178:181], v[218:221], v[72:75]
	v_mfma_f32_16x16x32_bf16 v[68:71], v[132:135], v[226:229], v[68:71]
	v_mfma_f32_16x16x32_bf16 v[64:67], v[178:181], v[226:229], v[64:67]
	v_mfma_f32_16x16x32_bf16 v[28:31], v[182:185], v[198:201], 0
	v_mfma_f32_16x16x32_bf16 v[24:27], v[190:193], v[198:201], 0
	v_mfma_f32_16x16x32_bf16 v[20:23], v[182:185], v[206:209], 0
	v_mfma_f32_16x16x32_bf16 v[16:19], v[190:193], v[206:209], 0
	v_mfma_f32_16x16x32_bf16 v[12:15], v[182:185], v[214:217], 0
	v_mfma_f32_16x16x32_bf16 v[8:11], v[190:193], v[214:217], 0
	v_mfma_f32_16x16x32_bf16 v[4:7], v[182:185], v[222:225], 0
	v_mfma_f32_16x16x32_bf16 v[0:3], v[190:193], v[222:225], 0
	v_mfma_f32_16x16x32_bf16 v[28:31], v[186:189], v[202:205], v[28:31]
	v_mfma_f32_16x16x32_bf16 v[24:27], v[194:197], v[202:205], v[24:27]
	v_mfma_f32_16x16x32_bf16 v[20:23], v[186:189], v[210:213], v[20:23]
	v_mfma_f32_16x16x32_bf16 v[16:19], v[194:197], v[210:213], v[16:19]
	v_mfma_f32_16x16x32_bf16 v[12:15], v[186:189], v[218:221], v[12:15]
	v_mfma_f32_16x16x32_bf16 v[8:11], v[194:197], v[218:221], v[8:11]
	v_mfma_f32_16x16x32_bf16 v[4:7], v[186:189], v[226:229], v[4:7]
	v_mfma_f32_16x16x32_bf16 v[0:3], v[194:197], v[226:229], v[0:3]
	s_barrier
; #define PG8_STAGE(bufoff, gbase, voff) do { _Pragma("unroll") for (int _i = 0; _i < 2; ++_i) \
;         __builtin_amdgcn_global_load_lds((const unsigned*)((const char*)(gbase) + (voff)[_i]), (PG8_LAS unsigned*)(lds + (bufoff) + ldsw + _i * 8192), 16, 0, 0); } while (0)
; #define PG8_LDA(dst, b, h) do { _Pragma("unroll") for (int m = 0; m < 4; ++m) _Pragma("unroll") for (int k = 0; k < 2; ++k) dst[m][k] = *(const PG8_LAS bf16x8*)(lds + PG8_SA(b, h) + aoff + m * 2048 + k * 1024); } while (0)
; #define PG8_LDB(dst, b, h) do { _Pragma("unroll") for (int n = 0; n < 2; ++n) _Pragma("unroll") for (int k = 0; k < 2; ++k) dst[n][k] = *(const PG8_LAS bf16x8*)(lds + PG8_SB(b, h) + boff + n * 2048 + k * 1024); } while (0)
; #define PG8_MMA(ai, bj, At, Bt) do { __builtin_amdgcn_s_setprio(1); _Pragma("unroll") for (int m = 0; m < 4; ++m) _Pragma("unroll") for (int n = 0; n < 2; ++n) _Pragma("unroll") for (int k = 0; k < 2; ++k) \
;         acc[ai][bj][m][n] = __builtin_amdgcn_mfma_f32_16x16x32_bf16(Bt[n][k], At[m][k], acc[ai][bj][m][n], 0, 0, 0); __builtin_amdgcn_s_setprio(0); } while (0)
; #define PG8_WAIT_V(n) asm volatile("s_waitcnt vmcnt(" #n ")" ::: "memory")
; #define PG8_WAIT_L(n) asm volatile("s_waitcnt lgkmcnt(" #n ")" ::: "memory")
; #define PG8_BAR __builtin_amdgcn_s_barrier()
; #define PG8_SCHED __builtin_amdgcn_sched_barrier(0)
; template <class Epi, class Sched, bool ALIGN_EPI = false, bool SP2 = false>
; __device__ __forceinline__ void gemm_phase(PG8_LAS unsigned char* lds, const Gemm g, const Sched& S, const Epi& E) {
;     ...
;             PG8_LDB(B0, 1, 0); PG8_LDB(B1, 1, 1); PG8_SCHED; PG8_LDA(At, 1, 0); PG8_STAGE(PG8_SA(0, 1), a2 + hstep, voffA);
;             PG8_WAIT_V(8); PG8_WAIT_L(0); PG8_BAR; PG8_MMA(0, 0, At, B0); PG8_MMA(0, 1, At, B1); PG8_BAR; PG8_SCHED;
;             PG8_LDA(At, 1, 1); PG8_STAGE(PG8_SB(1, 0), b3, voffB); PG8_STAGE(PG8_SB(1, 1), b3 + hstep, voffB); PG8_STAGE(PG8_SA(1, 0), a3, voffA);
;             PG8_WAIT_V(8); PG8_WAIT_L(0); PG8_BAR; PG8_MMA(1, 0, At, B0); PG8_MMA(1, 1, At, B1); PG8_BAR; PG8_SCHED;
	s_setprio 0
	s_add_i32 s60, 0, 0x18000
	s_add_i32 s61, 0, 0x1c000
	v_add_u32_e32 v178, s60, v163
	v_add_u32_e32 v194, s61, v163
	ds_read_b128 v[128:131], v178
	ds_read_b128 v[132:135], v178 offset:1024
	ds_read_b128 v[174:177], v178 offset:2048
	ds_read_b128 v[178:181], v178 offset:3072
	ds_read_b128 v[182:185], v194
	ds_read_b128 v[186:189], v194 offset:1024
	ds_read_b128 v[190:193], v194 offset:2048
	ds_read_b128 v[194:197], v194 offset:3072
	s_add_u32 s34, s34, 0x40000
	s_addc_u32 s35, s35, 0
	s_mov_b32 m0, s40
	v_lshl_add_u64 v[236:237], s[34:35], 0, v[136:137]
	ds_read_b128 v[198:201], v172 offset:32768
	ds_read_b128 v[202:205], v172 offset:33792
	ds_read_b128 v[206:209], v172 offset:34816
	ds_read_b128 v[210:213], v172 offset:35840
	ds_read_b128 v[214:217], v172 offset:36864
	ds_read_b128 v[218:221], v172 offset:37888
	ds_read_b128 v[222:225], v172 offset:38912
	ds_read_b128 v[226:229], v172 offset:39936
	global_load_lds_dwordx4 v[236:237], off
	v_lshl_add_u64 v[236:237], s[34:35], 0, v[140:141]
	s_mov_b32 m0, s41
	s_nop 0
	global_load_lds_dwordx4 v[236:237], off
	s_waitcnt vmcnt(8)
	s_waitcnt lgkmcnt(0)
	s_setprio 1
	s_barrier
	v_mfma_f32_16x16x32_bf16 v[124:127], v[128:131], v[198:201], v[124:127]
	v_mfma_f32_16x16x32_bf16 v[120:123], v[174:177], v[198:201], v[120:123]
	v_mfma_f32_16x16x32_bf16 v[116:119], v[128:131], v[206:209], v[116:119]
	v_mfma_f32_16x16x32_bf16 v[112:115], v[174:177], v[206:209], v[112:115]
	v_mfma_f32_16x16x32_bf16 v[108:111], v[128:131], v[214:217], v[108:111]
	v_mfma_f32_16x16x32_bf16 v[104:107], v[174:177], v[214:217], v[104:107]
	v_mfma_f32_16x16x32_bf16 v[100:103], v[128:131], v[222:225], v[100:103]
	v_mfma_f32_16x16x32_bf16 v[96:99], v[174:177], v[222:225], v[96:99]
	v_mfma_f32_16x16x32_bf16 v[124:127], v[132:135], v[202:205], v[124:127]
	v_mfma_f32_16x16x32_bf16 v[120:123], v[178:181], v[202:205], v[120:123]
	v_mfma_f32_16x16x32_bf16 v[116:119], v[132:135], v[210:213], v[116:119]
	v_mfma_f32_16x16x32_bf16 v[112:115], v[178:181], v[210:213], v[112:115]
	v_mfma_f32_16x16x32_bf16 v[108:111], v[132:135], v[218:221], v[108:111]
	v_mfma_f32_16x16x32_bf16 v[104:107], v[178:181], v[218:221], v[104:107]
	v_mfma_f32_16x16x32_bf16 v[100:103], v[132:135], v[226:229], v[100:103]
	v_mfma_f32_16x16x32_bf16 v[96:99], v[178:181], v[226:229], v[96:99]
	v_mfma_f32_16x16x32_bf16 v[60:63], v[182:185], v[198:201], v[60:63]
	v_mfma_f32_16x16x32_bf16 v[56:59], v[190:193], v[198:201], v[56:59]
	v_mfma_f32_16x16x32_bf16 v[52:55], v[182:185], v[206:209], v[52:55]
	v_mfma_f32_16x16x32_bf16 v[48:51], v[190:193], v[206:209], v[48:51]
	v_mfma_f32_16x16x32_bf16 v[44:47], v[182:185], v[214:217], v[44:47]
	v_mfma_f32_16x16x32_bf16 v[40:43], v[190:193], v[214:217], v[40:43]
	v_mfma_f32_16x16x32_bf16 v[36:39], v[182:185], v[222:225], v[36:39]
	v_mfma_f32_16x16x32_bf16 v[32:35], v[190:193], v[222:225], v[32:35]
	v_mfma_f32_16x16x32_bf16 v[60:63], v[186:189], v[202:205], v[60:63]
	v_mfma_f32_16x16x32_bf16 v[56:59], v[194:197], v[202:205], v[56:59]
	v_mfma_f32_16x16x32_bf16 v[52:55], v[186:189], v[210:213], v[52:55]
	v_mfma_f32_16x16x32_bf16 v[48:51], v[194:197], v[210:213], v[48:51]
	v_mfma_f32_16x16x32_bf16 v[44:47], v[186:189], v[218:221], v[44:47]
	v_mfma_f32_16x16x32_bf16 v[40:43], v[194:197], v[218:221], v[40:43]
	v_mfma_f32_16x16x32_bf16 v[36:39], v[186:189], v[226:229], v[36:39]
	v_mfma_f32_16x16x32_bf16 v[32:35], v[194:197], v[226:229], v[32:35]
	s_barrier
	s_setprio 0
	s_add_i32 s34, s60, s33
	v_lshl_add_u64 v[160:161], v[160:161], 0, s[16:17]
	s_mov_b32 m0, s34
	ds_read_b128 v[198:201], v172 offset:49152
	ds_read_b128 v[202:205], v172 offset:50176
	ds_read_b128 v[206:209], v172 offset:51200
	ds_read_b128 v[210:213], v172 offset:52224
	ds_read_b128 v[214:217], v172 offset:53248
	ds_read_b128 v[218:221], v172 offset:54272
	ds_read_b128 v[222:225], v172 offset:55296
	ds_read_b128 v[226:229], v172 offset:56320
	global_load_lds_dwordx4 v[160:161], off
	s_add_i32 m0, s34, 0x2000
	s_add_u32 s30, s30, 0x40080
	v_lshl_add_u64 v[160:161], v[230:231], 0, s[16:17]
	s_addc_u32 s31, s31, 0
	s_add_i32 s34, s61, s33
	global_load_lds_dwordx4 v[160:161], off
	v_lshl_add_u64 v[160:161], s[30:31], 0, v[138:139]
	s_mov_b32 m0, s34
	s_nop 0
	global_load_lds_dwordx4 v[160:161], off
	v_lshl_add_u64 v[160:161], s[30:31], 0, v[142:143]
	s_add_i32 m0, s34, 0x2000
	s_nop 0
	global_load_lds_dwordx4 v[160:161], off
	v_lshl_add_u64 v[160:161], v[232:233], 0, s[16:17]
	s_mov_b32 m0, s42
	s_nop 0
	global_load_lds_dwordx4 v[160:161], off
	v_lshl_add_u64 v[160:161], v[234:235], 0, s[16:17]
	s_mov_b32 m0, s43
	s_nop 0
	global_load_lds_dwordx4 v[160:161], off
	s_waitcnt vmcnt(8)
	s_waitcnt lgkmcnt(0)
	s_setprio 1
	s_barrier
	v_mfma_f32_16x16x32_bf16 v[92:95], v[128:131], v[198:201], v[92:95]
	v_mfma_f32_16x16x32_bf16 v[88:91], v[174:177], v[198:201], v[88:91]
	v_mfma_f32_16x16x32_bf16 v[84:87], v[128:131], v[206:209], v[84:87]
	v_mfma_f32_16x16x32_bf16 v[80:83], v[174:177], v[206:209], v[80:83]
	v_mfma_f32_16x16x32_bf16 v[76:79], v[128:131], v[214:217], v[76:79]
	v_mfma_f32_16x16x32_bf16 v[72:75], v[174:177], v[214:217], v[72:75]
	v_mfma_f32_16x16x32_bf16 v[68:71], v[128:131], v[222:225], v[68:71]
	v_mfma_f32_16x16x32_bf16 v[64:67], v[174:177], v[222:225], v[64:67]
	v_mfma_f32_16x16x32_bf16 v[92:95], v[132:135], v[202:205], v[92:95]
	v_mfma_f32_16x16x32_bf16 v[88:91], v[178:181], v[202:205], v[88:91]
	v_mfma_f32_16x16x32_bf16 v[84:87], v[132:135], v[210:213], v[84:87]
	v_mfma_f32_16x16x32_bf16 v[80:83], v[178:181], v[210:213], v[80:83]
	v_mfma_f32_16x16x32_bf16 v[76:79], v[132:135], v[218:221], v[76:79]
	v_mfma_f32_16x16x32_bf16 v[72:75], v[178:181], v[218:221], v[72:75]
	v_mfma_f32_16x16x32_bf16 v[68:71], v[132:135], v[226:229], v[68:71]
	v_mfma_f32_16x16x32_bf16 v[64:67], v[178:181], v[226:229], v[64:67]
	v_mfma_f32_16x16x32_bf16 v[28:31], v[182:185], v[198:201], v[28:31]
	v_mfma_f32_16x16x32_bf16 v[24:27], v[190:193], v[198:201], v[24:27]
	v_mfma_f32_16x16x32_bf16 v[20:23], v[182:185], v[206:209], v[20:23]
	v_mfma_f32_16x16x32_bf16 v[16:19], v[190:193], v[206:209], v[16:19]
	v_mfma_f32_16x16x32_bf16 v[12:15], v[182:185], v[214:217], v[12:15]
	v_mfma_f32_16x16x32_bf16 v[8:11], v[190:193], v[214:217], v[8:11]
	v_mfma_f32_16x16x32_bf16 v[4:7], v[182:185], v[222:225], v[4:7]
	v_mfma_f32_16x16x32_bf16 v[0:3], v[190:193], v[222:225], v[0:3]
	v_mfma_f32_16x16x32_bf16 v[28:31], v[186:189], v[202:205], v[28:31]
	v_mfma_f32_16x16x32_bf16 v[24:27], v[194:197], v[202:205], v[24:27]
	v_mfma_f32_16x16x32_bf16 v[20:23], v[186:189], v[210:213], v[20:23]
	v_mfma_f32_16x16x32_bf16 v[16:19], v[194:197], v[210:213], v[16:19]
	v_mfma_f32_16x16x32_bf16 v[12:15], v[186:189], v[218:221], v[12:15]
	v_mfma_f32_16x16x32_bf16 v[8:11], v[194:197], v[218:221], v[8:11]
	v_mfma_f32_16x16x32_bf16 v[4:7], v[186:189], v[226:229], v[4:7]
	v_mfma_f32_16x16x32_bf16 v[0:3], v[194:197], v[226:229], v[0:3]
	s_barrier
	s_setprio 0
	s_add_i32 s59, s59, 2
	s_add_u32 s28, s28, 0x100
	s_addc_u32 s29, s29, 0
	s_add_u32 s57, s57, 0x100
	s_addc_u32 s58, s58, 0
	s_cmp_gt_u32 s59, 13
; #define PG8_STAGE(bufoff, gbase, voff) do { _Pragma("unroll") for (int _i = 0; _i < 2; ++_i) \
;         __builtin_amdgcn_global_load_lds((const unsigned*)((const char*)(gbase) + (voff)[_i]), (PG8_LAS unsigned*)(lds + (bufoff) + ldsw + _i * 8192), 16, 0, 0); } while (0)
; #define PG8_LDA(dst, b, h) do { _Pragma("unroll") for (int m = 0; m < 4; ++m) _Pragma("unroll") for (int k = 0; k < 2; ++k) dst[m][k] = *(const PG8_LAS bf16x8*)(lds + PG8_SA(b, h) + aoff + m * 2048 + k * 1024); } while (0)
; #define PG8_LDB(dst, b, h) do { _Pragma("unroll") for (int n = 0; n < 2; ++n) _Pragma("unroll") for (int k = 0; k < 2; ++k) dst[n][k] = *(const PG8_LAS bf16x8*)(lds + PG8_SB(b, h) + boff + n * 2048 + k * 1024); } while (0)
; #define PG8_MMA(ai, bj, At, Bt) do { __builtin_amdgcn_s_setprio(1); _Pragma("unroll") for (int m = 0; m < 4; ++m) _Pragma("unroll") for (int n = 0; n < 2; ++n) _Pragma("unroll") for (int k = 0; k < 2; ++k) \
;         acc[ai][bj][m][n] = __builtin_amdgcn_mfma_f32_16x16x32_bf16(Bt[n][k], At[m][k], acc[ai][bj][m][n], 0, 0, 0); __builtin_amdgcn_s_setprio(0); } while (0)
; #define PG8_WAIT_V(n) asm volatile("s_waitcnt vmcnt(" #n ")" ::: "memory")
; #define PG8_WAIT_L(n) asm volatile("s_waitcnt lgkmcnt(" #n ")" ::: "memory")
; #define PG8_BAR __builtin_amdgcn_s_barrier()
; #define PG8_SCHED __builtin_amdgcn_sched_barrier(0)
; template <class Epi, class Sched, bool ALIGN_EPI = false, bool SP2 = false>
; __device__ __forceinline__ void gemm_phase(PG8_LAS unsigned char* lds, const Gemm g, const Sched& S, const Epi& E) {
;     ...
;             PG8_LDB(B0, 0, 0); PG8_LDB(B1, 0, 1); PG8_SCHED; PG8_LDA(At, 0, 0); PG8_STAGE(PG8_SA(1, 1), a1 + hstep, voffA);
;             PG8_WAIT_V(8); PG8_WAIT_L(0); PG8_BAR; PG8_MMA(0, 0, At, B0); PG8_MMA(0, 1, At, B1); PG8_BAR; PG8_SCHED;
;             PG8_LDA(At, 0, 1); PG8_STAGE(PG8_SB(0, 0), b2, voffB); PG8_STAGE(PG8_SB(0, 1), b2 + hstep, voffB); PG8_STAGE(PG8_SA(0, 0), a2, voffA);
;             PG8_WAIT_V(8); PG8_WAIT_L(0); PG8_BAR; PG8_MMA(1, 0, At, B0); PG8_MMA(1, 1, At, B1); PG8_BAR; PG8_SCHED;
.LBB0_607:
	ds_read_b128 v[128:131], v170
	ds_read_b128 v[132:135], v170 offset:1024
	ds_read_b128 v[174:177], v170 offset:2048
	ds_read_b128 v[178:181], v170 offset:3072
	ds_read_b128 v[182:185], v171
	ds_read_b128 v[186:189], v171 offset:1024
	ds_read_b128 v[190:193], v171 offset:2048
	ds_read_b128 v[194:197], v171 offset:3072
	s_add_u32 s30, s28, 0xfffc0080
	s_addc_u32 s31, s29, -1
	s_cmp_eq_u32 s59, 12
	s_cselect_b32 s35, s21, s31
	s_cselect_b32 s34, s55, s30
	s_cselect_b32 s31, s19, s58
	s_cselect_b32 s30, s56, s57
	v_lshl_add_u64 v[160:161], s[28:29], 0, v[152:153]
	s_add_i32 m0, s38, 0xc000
	ds_read_b128 v[198:201], v172
	ds_read_b128 v[202:205], v172 offset:1024
	ds_read_b128 v[206:209], v172 offset:2048
	ds_read_b128 v[210:213], v172 offset:3072
	ds_read_b128 v[214:217], v172 offset:4096
	ds_read_b128 v[218:221], v172 offset:5120
	ds_read_b128 v[222:225], v172 offset:6144
	ds_read_b128 v[226:229], v172 offset:7168
	global_load_lds_dwordx4 v[160:161], off
	v_lshl_add_u64 v[160:161], s[28:29], 0, v[154:155]
	s_add_i32 m0, s38, 0xe000
	s_nop 0
	global_load_lds_dwordx4 v[160:161], off
	s_waitcnt vmcnt(8)
	s_waitcnt lgkmcnt(0)
	s_setprio 1
	s_barrier
	v_mfma_f32_16x16x32_bf16 v[124:127], v[128:131], v[198:201], v[124:127]
	v_mfma_f32_16x16x32_bf16 v[120:123], v[174:177], v[198:201], v[120:123]
	v_mfma_f32_16x16x32_bf16 v[116:119], v[128:131], v[206:209], v[116:119]
	v_mfma_f32_16x16x32_bf16 v[112:115], v[174:177], v[206:209], v[112:115]
	v_mfma_f32_16x16x32_bf16 v[108:111], v[128:131], v[214:217], v[108:111]
	v_mfma_f32_16x16x32_bf16 v[104:107], v[174:177], v[214:217], v[104:107]
	v_mfma_f32_16x16x32_bf16 v[100:103], v[128:131], v[222:225], v[100:103]
	v_mfma_f32_16x16x32_bf16 v[96:99], v[174:177], v[222:225], v[96:99]
	v_mfma_f32_16x16x32_bf16 v[124:127], v[132:135], v[202:205], v[124:127]
	v_mfma_f32_16x16x32_bf16 v[120:123], v[178:181], v[202:205], v[120:123]
	v_mfma_f32_16x16x32_bf16 v[116:119], v[132:135], v[210:213], v[116:119]
	v_mfma_f32_16x16x32_bf16 v[112:115], v[178:181], v[210:213], v[112:115]
	v_mfma_f32_16x16x32_bf16 v[108:111], v[132:135], v[218:221], v[108:111]
	v_mfma_f32_16x16x32_bf16 v[104:107], v[178:181], v[218:221], v[104:107]
	v_mfma_f32_16x16x32_bf16 v[100:103], v[132:135], v[226:229], v[100:103]
	v_mfma_f32_16x16x32_bf16 v[96:99], v[178:181], v[226:229], v[96:99]
	v_mfma_f32_16x16x32_bf16 v[60:63], v[182:185], v[198:201], v[60:63]
	v_mfma_f32_16x16x32_bf16 v[56:59], v[190:193], v[198:201], v[56:59]
	v_mfma_f32_16x16x32_bf16 v[52:55], v[182:185], v[206:209], v[52:55]
	v_mfma_f32_16x16x32_bf16 v[48:51], v[190:193], v[206:209], v[48:51]
	v_mfma_f32_16x16x32_bf16 v[44:47], v[182:185], v[214:217], v[44:47]
	v_mfma_f32_16x16x32_bf16 v[40:43], v[190:193], v[214:217], v[40:43]
	v_mfma_f32_16x16x32_bf16 v[36:39], v[182:185], v[222:225], v[36:39]
	v_mfma_f32_16x16x32_bf16 v[32:35], v[190:193], v[222:225], v[32:35]
	v_mfma_f32_16x16x32_bf16 v[60:63], v[186:189], v[202:205], v[60:63]
	v_mfma_f32_16x16x32_bf16 v[56:59], v[194:197], v[202:205], v[56:59]
	v_mfma_f32_16x16x32_bf16 v[52:55], v[186:189], v[210:213], v[52:55]
	v_mfma_f32_16x16x32_bf16 v[48:51], v[194:197], v[210:213], v[48:51]
	v_mfma_f32_16x16x32_bf16 v[44:47], v[186:189], v[218:221], v[44:47]
	v_mfma_f32_16x16x32_bf16 v[40:43], v[194:197], v[218:221], v[40:43]
	v_mfma_f32_16x16x32_bf16 v[36:39], v[186:189], v[226:229], v[36:39]
	v_mfma_f32_16x16x32_bf16 v[32:35], v[194:197], v[226:229], v[32:35]
	s_barrier
	s_setprio 0
	s_add_i32 s60, s45, s33
	v_lshl_add_u64 v[160:161], s[30:31], 0, v[138:139]
	s_mov_b32 m0, s60
	ds_read_b128 v[198:201], v172 offset:16384
	ds_read_b128 v[202:205], v172 offset:17408
	ds_read_b128 v[206:209], v172 offset:18432
	ds_read_b128 v[210:213], v172 offset:19456
	ds_read_b128 v[214:217], v172 offset:20480
	ds_read_b128 v[218:221], v172 offset:21504
	ds_read_b128 v[222:225], v172 offset:22528
	ds_read_b128 v[226:229], v172 offset:23552
	global_load_lds_dwordx4 v[160:161], off
	s_add_i32 m0, s60, 0x2000
	s_add_u32 s60, s30, 0x40000
	v_lshl_add_u64 v[230:231], s[30:31], 0, v[142:143]
	s_addc_u32 s61, s31, 0
	s_add_i32 s62, s50, s33
	global_load_lds_dwordx4 v[230:231], off
	v_lshl_add_u64 v[232:233], s[60:61], 0, v[138:139]
	s_mov_b32 m0, s62
	v_lshl_add_u64 v[234:235], s[34:35], 0, v[140:141]
	global_load_lds_dwordx4 v[232:233], off
	v_lshl_add_u64 v[232:233], s[60:61], 0, v[142:143]
	s_add_i32 m0, s62, 0x2000
	s_nop 0
	global_load_lds_dwordx4 v[232:233], off
	v_lshl_add_u64 v[232:233], s[34:35], 0, v[136:137]
	s_mov_b32 m0, s38
	s_nop 0
	global_load_lds_dwordx4 v[232:233], off
	s_mov_b32 m0, s39
	s_nop 0
	global_load_lds_dwordx4 v[234:235], off
	s_waitcnt vmcnt(8)
	s_waitcnt lgkmcnt(0)
	s_setprio 1
	s_barrier
; #define PG8_STAGE(bufoff, gbase, voff) do { _Pragma("unroll") for (int _i = 0; _i < 2; ++_i) \
;         __builtin_amdgcn_global_load_lds((const unsigned*)((const char*)(gbase) + (voff)[_i]), (PG8_LAS unsigned*)(lds + (bufoff) + ldsw + _i * 8192), 16, 0, 0); } while (0)
; #define PG8_LDA(dst, b, h) do { _Pragma("unroll") for (int m = 0; m < 4; ++m) _Pragma("unroll") for (int k = 0; k < 2; ++k) dst[m][k] = *(const PG8_LAS bf16x8*)(lds + PG8_SA(b, h) + aoff + m * 2048 + k * 1024); } while (0)
; #define PG8_LDB(dst, b, h) do { _Pragma("unroll") for (int n = 0; n < 2; ++n) _Pragma("unroll") for (int k = 0; k < 2; ++k) dst[n][k] = *(const PG8_LAS bf16x8*)(lds + PG8_SB(b, h) + boff + n * 2048 + k * 1024); } while (0)
; #define PG8_MMA(ai, bj, At, Bt) do { __builtin_amdgcn_s_setprio(1); _Pragma("unroll") for (int m = 0; m < 4; ++m) _Pragma("unroll") for (int n = 0; n < 2; ++n) _Pragma("unroll") for (int k = 0; k < 2; ++k) \
;         acc[ai][bj][m][n] = __builtin_amdgcn_mfma_f32_16x16x32_bf16(Bt[n][k], At[m][k], acc[ai][bj][m][n], 0, 0, 0); __builtin_amdgcn_s_setprio(0); } while (0)
; #define PG8_WAIT_V(n) asm volatile("s_waitcnt vmcnt(" #n ")" ::: "memory")
; #define PG8_WAIT_L(n) asm volatile("s_waitcnt lgkmcnt(" #n ")" ::: "memory")
; #define PG8_BAR __builtin_amdgcn_s_barrier()
; #define PG8_SCHED __builtin_amdgcn_sched_barrier(0)
; template <class Epi, class Sched, bool ALIGN_EPI = false, bool SP2 = false>
; __device__ __forceinline__ void gemm_phase(PG8_LAS unsigned char* lds, const Gemm g, const Sched& S, const Epi& E) {
;     ...
;             PG8_WAIT_V(8); PG8_WAIT_L(0); PG8_BAR; PG8_MMA(1, 0, At, B0); PG8_MMA(1, 1, At, B1); PG8_BAR; PG8_SCHED;
;             PG8_LDB(B0, 1, 0); PG8_LDB(B1, 1, 1); PG8_SCHED; PG8_LDA(At, 1, 0); PG8_STAGE(PG8_SA(0, 1), a2 + hstep, voffA);
;             PG8_WAIT_V(8); PG8_WAIT_L(0); PG8_BAR; PG8_MMA(0, 0, At, B0); PG8_MMA(0, 1, At, B1); PG8_BAR; PG8_SCHED;
	v_mfma_f32_16x16x32_bf16 v[92:95], v[128:131], v[198:201], v[92:95]
	v_mfma_f32_16x16x32_bf16 v[88:91], v[174:177], v[198:201], v[88:91]
	v_mfma_f32_16x16x32_bf16 v[84:87], v[128:131], v[206:209], v[84:87]
	v_mfma_f32_16x16x32_bf16 v[80:83], v[174:177], v[206:209], v[80:83]
	v_mfma_f32_16x16x32_bf16 v[76:79], v[128:131], v[214:217], v[76:79]
	v_mfma_f32_16x16x32_bf16 v[72:75], v[174:177], v[214:217], v[72:75]
	v_mfma_f32_16x16x32_bf16 v[68:71], v[128:131], v[222:225], v[68:71]
	v_mfma_f32_16x16x32_bf16 v[64:67], v[174:177], v[222:225], v[64:67]
	v_mfma_f32_16x16x32_bf16 v[92:95], v[132:135], v[202:205], v[92:95]
	v_mfma_f32_16x16x32_bf16 v[88:91], v[178:181], v[202:205], v[88:91]
	v_mfma_f32_16x16x32_bf16 v[84:87], v[132:135], v[210:213], v[84:87]
	v_mfma_f32_16x16x32_bf16 v[80:83], v[178:181], v[210:213], v[80:83]
	v_mfma_f32_16x16x32_bf16 v[76:79], v[132:135], v[218:221], v[76:79]
	v_mfma_f32_16x16x32_bf16 v[72:75], v[178:181], v[218:221], v[72:75]
	v_mfma_f32_16x16x32_bf16 v[68:71], v[132:135], v[226:229], v[68:71]
	v_mfma_f32_16x16x32_bf16 v[64:67], v[178:181], v[226:229], v[64:67]
	v_mfma_f32_16x16x32_bf16 v[28:31], v[182:185], v[198:201], v[28:31]
	v_mfma_f32_16x16x32_bf16 v[24:27], v[190:193], v[198:201], v[24:27]
	v_mfma_f32_16x16x32_bf16 v[20:23], v[182:185], v[206:209], v[20:23]
	v_mfma_f32_16x16x32_bf16 v[16:19], v[190:193], v[206:209], v[16:19]
	v_mfma_f32_16x16x32_bf16 v[12:15], v[182:185], v[214:217], v[12:15]
	v_mfma_f32_16x16x32_bf16 v[8:11], v[190:193], v[214:217], v[8:11]
	v_mfma_f32_16x16x32_bf16 v[4:7], v[182:185], v[222:225], v[4:7]
	v_mfma_f32_16x16x32_bf16 v[0:3], v[190:193], v[222:225], v[0:3]
	v_mfma_f32_16x16x32_bf16 v[28:31], v[186:189], v[202:205], v[28:31]
	v_mfma_f32_16x16x32_bf16 v[24:27], v[194:197], v[202:205], v[24:27]
	v_mfma_f32_16x16x32_bf16 v[20:23], v[186:189], v[210:213], v[20:23]
	v_mfma_f32_16x16x32_bf16 v[16:19], v[194:197], v[210:213], v[16:19]
	v_mfma_f32_16x16x32_bf16 v[12:15], v[186:189], v[218:221], v[12:15]
	v_mfma_f32_16x16x32_bf16 v[8:11], v[194:197], v[218:221], v[8:11]
	v_mfma_f32_16x16x32_bf16 v[4:7], v[186:189], v[226:229], v[4:7]
	v_mfma_f32_16x16x32_bf16 v[0:3], v[194:197], v[226:229], v[0:3]
	s_barrier
	s_setprio 0
	s_add_i32 s60, 0, 0x18000
	s_add_i32 s61, 0, 0x1c000
	v_add_u32_e32 v178, s60, v163
	v_add_u32_e32 v194, s61, v163
	ds_read_b128 v[128:131], v178
	ds_read_b128 v[132:135], v178 offset:1024
	ds_read_b128 v[174:177], v178 offset:2048
	ds_read_b128 v[178:181], v178 offset:3072
	ds_read_b128 v[182:185], v194
	ds_read_b128 v[186:189], v194 offset:1024
	ds_read_b128 v[190:193], v194 offset:2048
	ds_read_b128 v[194:197], v194 offset:3072
	s_add_u32 s34, s34, 0x40000
	s_addc_u32 s35, s35, 0
	s_mov_b32 m0, s40
	v_lshl_add_u64 v[236:237], s[34:35], 0, v[136:137]
	ds_read_b128 v[198:201], v172 offset:32768
	ds_read_b128 v[202:205], v172 offset:33792
	ds_read_b128 v[206:209], v172 offset:34816
	ds_read_b128 v[210:213], v172 offset:35840
	ds_read_b128 v[214:217], v172 offset:36864
	ds_read_b128 v[218:221], v172 offset:37888
	ds_read_b128 v[222:225], v172 offset:38912
	ds_read_b128 v[226:229], v172 offset:39936
	global_load_lds_dwordx4 v[236:237], off
	v_lshl_add_u64 v[236:237], s[34:35], 0, v[140:141]
	s_mov_b32 m0, s41
	s_nop 0
	global_load_lds_dwordx4 v[236:237], off
	s_waitcnt vmcnt(8)
	s_waitcnt lgkmcnt(0)
	s_setprio 1
	s_barrier
	v_mfma_f32_16x16x32_bf16 v[124:127], v[128:131], v[198:201], v[124:127]
	v_mfma_f32_16x16x32_bf16 v[120:123], v[174:177], v[198:201], v[120:123]
	v_mfma_f32_16x16x32_bf16 v[116:119], v[128:131], v[206:209], v[116:119]
	v_mfma_f32_16x16x32_bf16 v[112:115], v[174:177], v[206:209], v[112:115]
	v_mfma_f32_16x16x32_bf16 v[108:111], v[128:131], v[214:217], v[108:111]
	v_mfma_f32_16x16x32_bf16 v[104:107], v[174:177], v[214:217], v[104:107]
	v_mfma_f32_16x16x32_bf16 v[100:103], v[128:131], v[222:225], v[100:103]
	v_mfma_f32_16x16x32_bf16 v[96:99], v[174:177], v[222:225], v[96:99]
	v_mfma_f32_16x16x32_bf16 v[124:127], v[132:135], v[202:205], v[124:127]
	v_mfma_f32_16x16x32_bf16 v[120:123], v[178:181], v[202:205], v[120:123]
	v_mfma_f32_16x16x32_bf16 v[116:119], v[132:135], v[210:213], v[116:119]
	v_mfma_f32_16x16x32_bf16 v[112:115], v[178:181], v[210:213], v[112:115]
	v_mfma_f32_16x16x32_bf16 v[108:111], v[132:135], v[218:221], v[108:111]
	v_mfma_f32_16x16x32_bf16 v[104:107], v[178:181], v[218:221], v[104:107]
	v_mfma_f32_16x16x32_bf16 v[100:103], v[132:135], v[226:229], v[100:103]
	v_mfma_f32_16x16x32_bf16 v[96:99], v[178:181], v[226:229], v[96:99]
	v_mfma_f32_16x16x32_bf16 v[60:63], v[182:185], v[198:201], v[60:63]
	v_mfma_f32_16x16x32_bf16 v[56:59], v[190:193], v[198:201], v[56:59]
	v_mfma_f32_16x16x32_bf16 v[52:55], v[182:185], v[206:209], v[52:55]
	v_mfma_f32_16x16x32_bf16 v[48:51], v[190:193], v[206:209], v[48:51]
	v_mfma_f32_16x16x32_bf16 v[44:47], v[182:185], v[214:217], v[44:47]
	v_mfma_f32_16x16x32_bf16 v[40:43], v[190:193], v[214:217], v[40:43]
	v_mfma_f32_16x16x32_bf16 v[36:39], v[182:185], v[222:225], v[36:39]
	v_mfma_f32_16x16x32_bf16 v[32:35], v[190:193], v[222:225], v[32:35]
	v_mfma_f32_16x16x32_bf16 v[60:63], v[186:189], v[202:205], v[60:63]
	v_mfma_f32_16x16x32_bf16 v[56:59], v[194:197], v[202:205], v[56:59]
	v_mfma_f32_16x16x32_bf16 v[52:55], v[186:189], v[210:213], v[52:55]
	v_mfma_f32_16x16x32_bf16 v[48:51], v[194:197], v[210:213], v[48:51]
	v_mfma_f32_16x16x32_bf16 v[44:47], v[186:189], v[218:221], v[44:47]
	v_mfma_f32_16x16x32_bf16 v[40:43], v[194:197], v[218:221], v[40:43]
	v_mfma_f32_16x16x32_bf16 v[36:39], v[186:189], v[226:229], v[36:39]
	v_mfma_f32_16x16x32_bf16 v[32:35], v[194:197], v[226:229], v[32:35]
	s_barrier
; #define PG8_STAGE(bufoff, gbase, voff) do { _Pragma("unroll") for (int _i = 0; _i < 2; ++_i) \
;         __builtin_amdgcn_global_load_lds((const unsigned*)((const char*)(gbase) + (voff)[_i]), (PG8_LAS unsigned*)(lds + (bufoff) + ldsw + _i * 8192), 16, 0, 0); } while (0)
; #define PG8_LDA(dst, b, h) do { _Pragma("unroll") for (int m = 0; m < 4; ++m) _Pragma("unroll") for (int k = 0; k < 2; ++k) dst[m][k] = *(const PG8_LAS bf16x8*)(lds + PG8_SA(b, h) + aoff + m * 2048 + k * 1024); } while (0)
; #define PG8_MMA(ai, bj, At, Bt) do { __builtin_amdgcn_s_setprio(1); _Pragma("unroll") for (int m = 0; m < 4; ++m) _Pragma("unroll") for (int n = 0; n < 2; ++n) _Pragma("unroll") for (int k = 0; k < 2; ++k) \
;         acc[ai][bj][m][n] = __builtin_amdgcn_mfma_f32_16x16x32_bf16(Bt[n][k], At[m][k], acc[ai][bj][m][n], 0, 0, 0); __builtin_amdgcn_s_setprio(0); } while (0)
; #define PG8_WAIT_V(n) asm volatile("s_waitcnt vmcnt(" #n ")" ::: "memory")
; #define PG8_WAIT_L(n) asm volatile("s_waitcnt lgkmcnt(" #n ")" ::: "memory")
; #define PG8_BAR __builtin_amdgcn_s_barrier()
; #define PG8_SCHED __builtin_amdgcn_sched_barrier(0)
; template <class Epi, class Sched, bool ALIGN_EPI = false, bool SP2 = false>
; __device__ __forceinline__ void gemm_phase(PG8_LAS unsigned char* lds, const Gemm g, const Sched& S, const Epi& E) {
;     ...
;             PG8_LDA(At, 1, 1); PG8_STAGE(PG8_SB(1, 0), b3, voffB); PG8_STAGE(PG8_SB(1, 1), b3 + hstep, voffB); PG8_STAGE(PG8_SA(1, 0), a3, voffA);
;             PG8_WAIT_V(8); PG8_WAIT_L(0); PG8_BAR; PG8_MMA(1, 0, At, B0); PG8_MMA(1, 1, At, B1); PG8_BAR; PG8_SCHED;
;     ...
;         if constexpr (ALIGN_EPI) { if (wr == 0) PG8_BAR; }
	s_setprio 0
	s_add_i32 s34, s60, s33
	v_lshl_add_u64 v[160:161], v[160:161], 0, s[16:17]
	s_mov_b32 m0, s34
	ds_read_b128 v[198:201], v172 offset:49152
	ds_read_b128 v[202:205], v172 offset:50176
	ds_read_b128 v[206:209], v172 offset:51200
	ds_read_b128 v[210:213], v172 offset:52224
	ds_read_b128 v[214:217], v172 offset:53248
	ds_read_b128 v[218:221], v172 offset:54272
	ds_read_b128 v[222:225], v172 offset:55296
	ds_read_b128 v[226:229], v172 offset:56320
	global_load_lds_dwordx4 v[160:161], off
	s_add_i32 m0, s34, 0x2000
	s_add_u32 s30, s30, 0x40080
	v_lshl_add_u64 v[160:161], v[230:231], 0, s[16:17]
	s_addc_u32 s31, s31, 0
	s_add_i32 s34, s61, s33
	global_load_lds_dwordx4 v[160:161], off
	v_lshl_add_u64 v[160:161], s[30:31], 0, v[138:139]
	s_mov_b32 m0, s34
	s_nop 0
	global_load_lds_dwordx4 v[160:161], off
	v_lshl_add_u64 v[160:161], s[30:31], 0, v[142:143]
	s_add_i32 m0, s34, 0x2000
	s_nop 0
	global_load_lds_dwordx4 v[160:161], off
	v_lshl_add_u64 v[160:161], v[232:233], 0, s[16:17]
	s_mov_b32 m0, s42
	s_nop 0
	global_load_lds_dwordx4 v[160:161], off
	v_lshl_add_u64 v[160:161], v[234:235], 0, s[16:17]
	s_mov_b32 m0, s43
	s_nop 0
	global_load_lds_dwordx4 v[160:161], off
	s_waitcnt vmcnt(8)
	s_waitcnt lgkmcnt(0)
	s_setprio 1
	s_barrier
	v_mfma_f32_16x16x32_bf16 v[92:95], v[128:131], v[198:201], v[92:95]
	v_mfma_f32_16x16x32_bf16 v[88:91], v[174:177], v[198:201], v[88:91]
	v_mfma_f32_16x16x32_bf16 v[84:87], v[128:131], v[206:209], v[84:87]
	v_mfma_f32_16x16x32_bf16 v[80:83], v[174:177], v[206:209], v[80:83]
	v_mfma_f32_16x16x32_bf16 v[76:79], v[128:131], v[214:217], v[76:79]
	v_mfma_f32_16x16x32_bf16 v[72:75], v[174:177], v[214:217], v[72:75]
	v_mfma_f32_16x16x32_bf16 v[68:71], v[128:131], v[222:225], v[68:71]
	v_mfma_f32_16x16x32_bf16 v[64:67], v[174:177], v[222:225], v[64:67]
	v_mfma_f32_16x16x32_bf16 v[92:95], v[132:135], v[202:205], v[92:95]
	v_mfma_f32_16x16x32_bf16 v[88:91], v[178:181], v[202:205], v[88:91]
	v_mfma_f32_16x16x32_bf16 v[84:87], v[132:135], v[210:213], v[84:87]
	v_mfma_f32_16x16x32_bf16 v[80:83], v[178:181], v[210:213], v[80:83]
	v_mfma_f32_16x16x32_bf16 v[76:79], v[132:135], v[218:221], v[76:79]
	v_mfma_f32_16x16x32_bf16 v[72:75], v[178:181], v[218:221], v[72:75]
	v_mfma_f32_16x16x32_bf16 v[68:71], v[132:135], v[226:229], v[68:71]
	v_mfma_f32_16x16x32_bf16 v[64:67], v[178:181], v[226:229], v[64:67]
	v_mfma_f32_16x16x32_bf16 v[28:31], v[182:185], v[198:201], v[28:31]
	v_mfma_f32_16x16x32_bf16 v[24:27], v[190:193], v[198:201], v[24:27]
	v_mfma_f32_16x16x32_bf16 v[20:23], v[182:185], v[206:209], v[20:23]
	v_mfma_f32_16x16x32_bf16 v[16:19], v[190:193], v[206:209], v[16:19]
	v_mfma_f32_16x16x32_bf16 v[12:15], v[182:185], v[214:217], v[12:15]
	v_mfma_f32_16x16x32_bf16 v[8:11], v[190:193], v[214:217], v[8:11]
	v_mfma_f32_16x16x32_bf16 v[4:7], v[182:185], v[222:225], v[4:7]
	v_mfma_f32_16x16x32_bf16 v[0:3], v[190:193], v[222:225], v[0:3]
	v_mfma_f32_16x16x32_bf16 v[28:31], v[186:189], v[202:205], v[28:31]
	v_mfma_f32_16x16x32_bf16 v[24:27], v[194:197], v[202:205], v[24:27]
	v_mfma_f32_16x16x32_bf16 v[20:23], v[186:189], v[210:213], v[20:23]
	v_mfma_f32_16x16x32_bf16 v[16:19], v[194:197], v[210:213], v[16:19]
	v_mfma_f32_16x16x32_bf16 v[12:15], v[186:189], v[218:221], v[12:15]
	v_mfma_f32_16x16x32_bf16 v[8:11], v[194:197], v[218:221], v[8:11]
	v_mfma_f32_16x16x32_bf16 v[4:7], v[186:189], v[226:229], v[4:7]
	v_mfma_f32_16x16x32_bf16 v[0:3], v[194:197], v[226:229], v[0:3]
	s_barrier
	s_setprio 0
	s_add_i32 s59, s59, 2
	s_add_u32 s28, s28, 0x100
	s_addc_u32 s29, s29, 0
	s_add_u32 s57, s57, 0x100
	s_addc_u32 s58, s58, 0
	s_cmp_gt_u32 s59, 13
	s_cbranch_scc0 .LBB0_607
	s_and_b64 vcc, exec, s[0:1]
	s_cbranch_vccz .LBB0_610
	s_barrier

; #define PG8_STAGE(bufoff, gbase, voff) do { _Pragma("unroll") for (int _i = 0; _i < 2; ++_i) \
;         __builtin_amdgcn_global_load_lds((const unsigned*)((const char*)(gbase) + (voff)[_i]), (PG8_LAS unsigned*)(lds + (bufoff) + ldsw + _i * 8192), 16, 0, 0); } while (0)
; #define PG8_LDA(dst, b, h) do { _Pragma("unroll") for (int m = 0; m < 4; ++m) _Pragma("unroll") for (int k = 0; k < 2; ++k) dst[m][k] = *(const PG8_LAS bf16x8*)(lds + PG8_SA(b, h) + aoff + m * 2048 + k * 1024); } while (0)
; #define PG8_LDB(dst, b, h) do { _Pragma("unroll") for (int n = 0; n < 2; ++n) _Pragma("unroll") for (int k = 0; k < 2; ++k) dst[n][k] = *(const PG8_LAS bf16x8*)(lds + PG8_SB(b, h) + boff + n * 2048 + k * 1024); } while (0)
; #define PG8_WAIT_V(n) asm volatile("s_waitcnt vmcnt(" #n ")" ::: "memory")
; #define PG8_WAIT_L(n) asm volatile("s_waitcnt lgkmcnt(" #n ")" ::: "memory")
; #define PG8_BAR __builtin_amdgcn_s_barrier()
; #define PG8_SCHED __builtin_amdgcn_sched_barrier(0)
; template <class Epi, class Sched, bool ALIGN_EPI = false, bool SP2 = false>
; __device__ __forceinline__ void gemm_phase(PG8_LAS unsigned char* lds, const Gemm g, const Sched& S, const Epi& E) {
;     ...
;         const char* nA = has_next ? (const char*)g.A + (size_t)nxt.pm * tstep : cA; const char* nB = has_next ? (const char*)g.Bt + (size_t)nxt.pn * tstep : cB;
;         for (int t = 0; t < nt; t += 2) {
;             const bool last = (t == nt - 2);
;             const char* a1 = cA + (size_t)(t + 1) * kstep;
;             const char* a2 = last ? nA : cA + (size_t)(t + 2) * kstep; const char* b2 = last ? nB : cB + (size_t)(t + 2) * kstep;
;             const char* a3 = a2 + kstep; const char* b3 = b2 + kstep;
;             if (last && has_next) S.a_ready(nxt, ui + 1);
;             if constexpr (SP2) {
;             PG8_LDB(B0, 0, 0); PG8_LDB(B1, 0, 1); PG8_SCHED; PG8_LDA(At, 0, 0); PG8_STAGE(PG8_SA(1, 1), a1 + hstep, voffA);
;             PG8_WAIT_V(8); PG8_WAIT_L(0); PG8_BAR; PG8_MMA(0, 0, At, B0); PG8_MMA(0, 1, At, B1); PG8_BAR; PG8_SCHED;
;             PG8_LDA(At, 0, 1); PG8_STAGE(PG8_SB(0, 0), b2, voffB); PG8_STAGE(PG8_SB(0, 1), b2 + hstep, voffB); PG8_STAGE(PG8_SA(0, 0), a2, voffA);
;             PG8_WAIT_V(8); PG8_WAIT_L(0); PG8_BAR; PG8_MMA(1, 0, At, B0); PG8_MMA(1, 1, At, B1); PG8_BAR; PG8_SCHED;
.LBB0_959:
	s_ashr_i32 s23, s22, 31
	s_lshl_b64 s[24:25], s[22:23], 19
	s_add_u32 s24, s3, s24
	s_addc_u32 s25, s33, s25
	s_and_b64 s[26:27], s[4:5], exec
	s_cselect_b32 s23, s25, s31
	s_cselect_b32 s29, s24, s30
	s_ashr_i32 s21, s20, 31
	s_lshl_b64 s[26:27], s[20:21], 19
	s_add_u32 s26, s38, s26
	s_addc_u32 s27, s39, s27
	s_and_b64 s[36:37], s[4:5], exec
	s_cselect_b32 s21, s27, s35
	s_cselect_b32 s54, s26, s34
	s_add_u32 s30, s30, 0x40080
	s_addc_u32 s31, s31, 0
	s_add_u32 s55, s34, 0x100
	s_addc_u32 s56, s35, 0
	s_mov_b32 s57, -2
	s_add_u32 s34, s30, 0xfffc0080
	s_addc_u32 s35, s31, -1
	s_cmp_eq_u32 s57, 12
	s_cselect_b32 s37, s23, s35
	s_cselect_b32 s36, s29, s34
	s_cselect_b32 s35, s21, s56
	s_cselect_b32 s34, s54, s55
	v_lshl_add_u64 v[204:205], s[30:31], 0, v[200:201]
	s_add_i32 m0, s41, 0xc000
	global_load_lds_dwordx4 v[204:205], off
	v_lshl_add_u64 v[204:205], s[30:31], 0, v[202:203]
	s_add_i32 m0, s41, 0xe000
	s_nop 0
	global_load_lds_dwordx4 v[204:205], off
	s_waitcnt vmcnt(8)
	s_waitcnt lgkmcnt(0)
	s_setprio 1
	s_barrier
	v_mfma_f32_16x16x32_bf16 v[132:135], v[120:123], v[160:163], 0
	v_mfma_f32_16x16x32_bf16 v[124:127], v[136:139], v[160:163], 0
	v_mfma_f32_16x16x32_bf16 v[108:111], v[120:123], v[168:171], 0
	v_mfma_f32_16x16x32_bf16 v[104:107], v[136:139], v[168:171], 0
	v_mfma_f32_16x16x32_bf16 v[92:95], v[120:123], v[176:179], 0
	v_mfma_f32_16x16x32_bf16 v[88:91], v[136:139], v[176:179], 0
	v_mfma_f32_16x16x32_bf16 v[76:79], v[120:123], v[184:187], 0
	v_mfma_f32_16x16x32_bf16 v[72:75], v[136:139], v[184:187], 0
	v_mfma_f32_16x16x32_bf16 v[132:135], v[128:131], v[164:167], v[132:135]
	v_mfma_f32_16x16x32_bf16 v[124:127], v[140:143], v[164:167], v[124:127]
	v_mfma_f32_16x16x32_bf16 v[108:111], v[128:131], v[172:175], v[108:111]
	v_mfma_f32_16x16x32_bf16 v[104:107], v[140:143], v[172:175], v[104:107]
	v_mfma_f32_16x16x32_bf16 v[92:95], v[128:131], v[180:183], v[92:95]
	v_mfma_f32_16x16x32_bf16 v[88:91], v[140:143], v[180:183], v[88:91]
	v_mfma_f32_16x16x32_bf16 v[76:79], v[128:131], v[188:191], v[76:79]
	v_mfma_f32_16x16x32_bf16 v[72:75], v[140:143], v[188:191], v[72:75]
	v_mfma_f32_16x16x32_bf16 v[116:119], v[144:147], v[160:163], 0
	v_mfma_f32_16x16x32_bf16 v[112:115], v[152:155], v[160:163], 0
	v_mfma_f32_16x16x32_bf16 v[100:103], v[144:147], v[168:171], 0
	v_mfma_f32_16x16x32_bf16 v[96:99], v[152:155], v[168:171], 0
	v_mfma_f32_16x16x32_bf16 v[84:87], v[144:147], v[176:179], 0
	v_mfma_f32_16x16x32_bf16 v[80:83], v[152:155], v[176:179], 0
	v_mfma_f32_16x16x32_bf16 v[68:71], v[144:147], v[184:187], 0
	v_mfma_f32_16x16x32_bf16 v[64:67], v[152:155], v[184:187], 0
	v_mfma_f32_16x16x32_bf16 v[116:119], v[148:151], v[164:167], v[116:119]
	v_mfma_f32_16x16x32_bf16 v[112:115], v[156:159], v[164:167], v[112:115]
	v_mfma_f32_16x16x32_bf16 v[100:103], v[148:151], v[172:175], v[100:103]
	v_mfma_f32_16x16x32_bf16 v[96:99], v[156:159], v[172:175], v[96:99]
	v_mfma_f32_16x16x32_bf16 v[84:87], v[148:151], v[180:183], v[84:87]
	v_mfma_f32_16x16x32_bf16 v[80:83], v[156:159], v[180:183], v[80:83]
	v_mfma_f32_16x16x32_bf16 v[68:71], v[148:151], v[188:191], v[68:71]
	v_mfma_f32_16x16x32_bf16 v[64:67], v[156:159], v[188:191], v[64:67]
	s_barrier
	s_setprio 0
	s_add_i32 s58, s51, s40
	v_lshl_add_u64 v[204:205], s[34:35], 0, v[194:195]
	s_mov_b32 m0, s58
	ds_read_b128 v[160:163], v247 offset:16384
	ds_read_b128 v[164:167], v247 offset:17408
	ds_read_b128 v[168:171], v247 offset:18432
	ds_read_b128 v[172:175], v247 offset:19456
	ds_read_b128 v[176:179], v247 offset:20480
	ds_read_b128 v[180:183], v247 offset:21504
	ds_read_b128 v[184:187], v247 offset:22528
	ds_read_b128 v[188:191], v247 offset:23552
	global_load_lds_dwordx4 v[204:205], off
	s_add_i32 m0, s58, 0x2000
	s_add_u32 s58, s34, 0x40000
	v_lshl_add_u64 v[206:207], s[34:35], 0, v[198:199]
	s_addc_u32 s59, s35, 0
	s_add_i32 s60, s52, s40
	global_load_lds_dwordx4 v[206:207], off
	v_lshl_add_u64 v[208:209], s[58:59], 0, v[194:195]
	s_mov_b32 m0, s60
	v_lshl_add_u64 v[210:211], s[36:37], 0, v[196:197]
	global_load_lds_dwordx4 v[208:209], off
	v_lshl_add_u64 v[208:209], s[58:59], 0, v[198:199]
	s_add_i32 m0, s60, 0x2000
	s_nop 0
	global_load_lds_dwordx4 v[208:209], off
	v_lshl_add_u64 v[208:209], s[36:37], 0, v[192:193]
	s_mov_b32 m0, s41
	s_nop 0
	global_load_lds_dwordx4 v[208:209], off
	s_mov_b32 m0, s42
	s_nop 0
	global_load_lds_dwordx4 v[210:211], off
	s_waitcnt vmcnt(8)
	s_waitcnt lgkmcnt(0)
	s_setprio 1
	s_barrier
	v_mfma_f32_16x16x32_bf16 v[60:63], v[120:123], v[160:163], 0
	v_mfma_f32_16x16x32_bf16 v[56:59], v[136:139], v[160:163], 0
	v_mfma_f32_16x16x32_bf16 v[44:47], v[120:123], v[168:171], 0
	v_mfma_f32_16x16x32_bf16 v[40:43], v[136:139], v[168:171], 0
	v_mfma_f32_16x16x32_bf16 v[28:31], v[120:123], v[176:179], 0
	v_mfma_f32_16x16x32_bf16 v[24:27], v[136:139], v[176:179], 0
	v_mfma_f32_16x16x32_bf16 v[12:15], v[120:123], v[184:187], 0
	v_mfma_f32_16x16x32_bf16 v[8:11], v[136:139], v[184:187], 0
	v_mfma_f32_16x16x32_bf16 v[60:63], v[128:131], v[164:167], v[60:63]
	v_mfma_f32_16x16x32_bf16 v[56:59], v[140:143], v[164:167], v[56:59]
	v_mfma_f32_16x16x32_bf16 v[44:47], v[128:131], v[172:175], v[44:47]
	v_mfma_f32_16x16x32_bf16 v[40:43], v[140:143], v[172:175], v[40:43]
	v_mfma_f32_16x16x32_bf16 v[28:31], v[128:131], v[180:183], v[28:31]
	v_mfma_f32_16x16x32_bf16 v[24:27], v[140:143], v[180:183], v[24:27]
	v_mfma_f32_16x16x32_bf16 v[12:15], v[128:131], v[188:191], v[12:15]
	v_mfma_f32_16x16x32_bf16 v[8:11], v[140:143], v[188:191], v[8:11]
	v_mfma_f32_16x16x32_bf16 v[52:55], v[144:147], v[160:163], 0
	v_mfma_f32_16x16x32_bf16 v[48:51], v[152:155], v[160:163], 0
	v_mfma_f32_16x16x32_bf16 v[36:39], v[144:147], v[168:171], 0
	v_mfma_f32_16x16x32_bf16 v[32:35], v[152:155], v[168:171], 0
	v_mfma_f32_16x16x32_bf16 v[20:23], v[144:147], v[176:179], 0
	v_mfma_f32_16x16x32_bf16 v[16:19], v[152:155], v[176:179], 0
	v_mfma_f32_16x16x32_bf16 v[4:7], v[144:147], v[184:187], 0
	v_mfma_f32_16x16x32_bf16 v[0:3], v[152:155], v[184:187], 0
	v_mfma_f32_16x16x32_bf16 v[52:55], v[148:151], v[164:167], v[52:55]
	v_mfma_f32_16x16x32_bf16 v[48:51], v[156:159], v[164:167], v[48:51]
	v_mfma_f32_16x16x32_bf16 v[36:39], v[148:151], v[172:175], v[36:39]
	v_mfma_f32_16x16x32_bf16 v[32:35], v[156:159], v[172:175], v[32:35]
	v_mfma_f32_16x16x32_bf16 v[20:23], v[148:151], v[180:183], v[20:23]
	v_mfma_f32_16x16x32_bf16 v[16:19], v[156:159], v[180:183], v[16:19]
	v_mfma_f32_16x16x32_bf16 v[4:7], v[148:151], v[188:191], v[4:7]
	v_mfma_f32_16x16x32_bf16 v[0:3], v[156:159], v[188:191], v[0:3]
	s_barrier
; #define PG8_STAGE(bufoff, gbase, voff) do { _Pragma("unroll") for (int _i = 0; _i < 2; ++_i) \
;         __builtin_amdgcn_global_load_lds((const unsigned*)((const char*)(gbase) + (voff)[_i]), (PG8_LAS unsigned*)(lds + (bufoff) + ldsw + _i * 8192), 16, 0, 0); } while (0)
; #define PG8_LDA(dst, b, h) do { _Pragma("unroll") for (int m = 0; m < 4; ++m) _Pragma("unroll") for (int k = 0; k < 2; ++k) dst[m][k] = *(const PG8_LAS bf16x8*)(lds + PG8_SA(b, h) + aoff + m * 2048 + k * 1024); } while (0)
; #define PG8_LDB(dst, b, h) do { _Pragma("unroll") for (int n = 0; n < 2; ++n) _Pragma("unroll") for (int k = 0; k < 2; ++k) dst[n][k] = *(const PG8_LAS bf16x8*)(lds + PG8_SB(b, h) + boff + n * 2048 + k * 1024); } while (0)
; #define PG8_MMA(ai, bj, At, Bt) do { __builtin_amdgcn_s_setprio(1); _Pragma("unroll") for (int m = 0; m < 4; ++m) _Pragma("unroll") for (int n = 0; n < 2; ++n) _Pragma("unroll") for (int k = 0; k < 2; ++k) \
;         acc[ai][bj][m][n] = __builtin_amdgcn_mfma_f32_16x16x32_bf16(Bt[n][k], At[m][k], acc[ai][bj][m][n], 0, 0, 0); __builtin_amdgcn_s_setprio(0); } while (0)
; #define PG8_WAIT_V(n) asm volatile("s_waitcnt vmcnt(" #n ")" ::: "memory")
; #define PG8_WAIT_L(n) asm volatile("s_waitcnt lgkmcnt(" #n ")" ::: "memory")
; #define PG8_BAR __builtin_amdgcn_s_barrier()
; #define PG8_SCHED __builtin_amdgcn_sched_barrier(0)
; template <class Epi, class Sched, bool ALIGN_EPI = false, bool SP2 = false>
; __device__ __forceinline__ void gemm_phase(PG8_LAS unsigned char* lds, const Gemm g, const Sched& S, const Epi& E) {
;     ...
;             PG8_LDB(B0, 1, 0); PG8_LDB(B1, 1, 1); PG8_SCHED; PG8_LDA(At, 1, 0); PG8_STAGE(PG8_SA(0, 1), a2 + hstep, voffA);
;             PG8_WAIT_V(8); PG8_WAIT_L(0); PG8_BAR; PG8_MMA(0, 0, At, B0); PG8_MMA(0, 1, At, B1); PG8_BAR; PG8_SCHED;
;             PG8_LDA(At, 1, 1); PG8_STAGE(PG8_SB(1, 0), b3, voffB); PG8_STAGE(PG8_SB(1, 1), b3 + hstep, voffB); PG8_STAGE(PG8_SA(1, 0), a3, voffA);
;             PG8_WAIT_V(8); PG8_WAIT_L(0); PG8_BAR; PG8_MMA(1, 0, At, B0); PG8_MMA(1, 1, At, B1); PG8_BAR; PG8_SCHED;
	s_setprio 0
	s_add_i32 s58, 0, 0x18000
	s_add_i32 s59, 0, 0x1c000
	v_add_u32_e32 v140, s58, v243
	v_add_u32_e32 v156, s59, v243
	ds_read_b128 v[120:123], v140
	ds_read_b128 v[128:131], v140 offset:1024
	ds_read_b128 v[136:139], v140 offset:2048
	ds_read_b128 v[140:143], v140 offset:3072
	ds_read_b128 v[144:147], v156
	ds_read_b128 v[148:151], v156 offset:1024
	ds_read_b128 v[152:155], v156 offset:2048
	ds_read_b128 v[156:159], v156 offset:3072
	s_add_u32 s36, s36, 0x40000
	s_addc_u32 s37, s37, 0
	s_mov_b32 m0, s43
	v_lshl_add_u64 v[212:213], s[36:37], 0, v[192:193]
	ds_read_b128 v[160:163], v247 offset:32768
	ds_read_b128 v[164:167], v247 offset:33792
	ds_read_b128 v[168:171], v247 offset:34816
	ds_read_b128 v[172:175], v247 offset:35840
	ds_read_b128 v[176:179], v247 offset:36864
	ds_read_b128 v[180:183], v247 offset:37888
	ds_read_b128 v[184:187], v247 offset:38912
	ds_read_b128 v[188:191], v247 offset:39936
	global_load_lds_dwordx4 v[212:213], off
	v_lshl_add_u64 v[212:213], s[36:37], 0, v[196:197]
	s_mov_b32 m0, s44
	s_nop 0
	global_load_lds_dwordx4 v[212:213], off
	s_waitcnt vmcnt(8)
	s_waitcnt lgkmcnt(0)
	s_setprio 1
	s_barrier
	v_mfma_f32_16x16x32_bf16 v[132:135], v[120:123], v[160:163], v[132:135]
	v_mfma_f32_16x16x32_bf16 v[124:127], v[136:139], v[160:163], v[124:127]
	v_mfma_f32_16x16x32_bf16 v[108:111], v[120:123], v[168:171], v[108:111]
	v_mfma_f32_16x16x32_bf16 v[104:107], v[136:139], v[168:171], v[104:107]
	v_mfma_f32_16x16x32_bf16 v[92:95], v[120:123], v[176:179], v[92:95]
	v_mfma_f32_16x16x32_bf16 v[88:91], v[136:139], v[176:179], v[88:91]
	v_mfma_f32_16x16x32_bf16 v[76:79], v[120:123], v[184:187], v[76:79]
	v_mfma_f32_16x16x32_bf16 v[72:75], v[136:139], v[184:187], v[72:75]
	v_mfma_f32_16x16x32_bf16 v[132:135], v[128:131], v[164:167], v[132:135]
	v_mfma_f32_16x16x32_bf16 v[124:127], v[140:143], v[164:167], v[124:127]
	v_mfma_f32_16x16x32_bf16 v[108:111], v[128:131], v[172:175], v[108:111]
	v_mfma_f32_16x16x32_bf16 v[104:107], v[140:143], v[172:175], v[104:107]
	v_mfma_f32_16x16x32_bf16 v[92:95], v[128:131], v[180:183], v[92:95]
	v_mfma_f32_16x16x32_bf16 v[88:91], v[140:143], v[180:183], v[88:91]
	v_mfma_f32_16x16x32_bf16 v[76:79], v[128:131], v[188:191], v[76:79]
	v_mfma_f32_16x16x32_bf16 v[72:75], v[140:143], v[188:191], v[72:75]
	v_mfma_f32_16x16x32_bf16 v[116:119], v[144:147], v[160:163], v[116:119]
	v_mfma_f32_16x16x32_bf16 v[112:115], v[152:155], v[160:163], v[112:115]
	v_mfma_f32_16x16x32_bf16 v[100:103], v[144:147], v[168:171], v[100:103]
	v_mfma_f32_16x16x32_bf16 v[96:99], v[152:155], v[168:171], v[96:99]
	v_mfma_f32_16x16x32_bf16 v[84:87], v[144:147], v[176:179], v[84:87]
	v_mfma_f32_16x16x32_bf16 v[80:83], v[152:155], v[176:179], v[80:83]
	v_mfma_f32_16x16x32_bf16 v[68:71], v[144:147], v[184:187], v[68:71]
	v_mfma_f32_16x16x32_bf16 v[64:67], v[152:155], v[184:187], v[64:67]
	v_mfma_f32_16x16x32_bf16 v[116:119], v[148:151], v[164:167], v[116:119]
	v_mfma_f32_16x16x32_bf16 v[112:115], v[156:159], v[164:167], v[112:115]
	v_mfma_f32_16x16x32_bf16 v[100:103], v[148:151], v[172:175], v[100:103]
	v_mfma_f32_16x16x32_bf16 v[96:99], v[156:159], v[172:175], v[96:99]
	v_mfma_f32_16x16x32_bf16 v[84:87], v[148:151], v[180:183], v[84:87]
	v_mfma_f32_16x16x32_bf16 v[80:83], v[156:159], v[180:183], v[80:83]
	v_mfma_f32_16x16x32_bf16 v[68:71], v[148:151], v[188:191], v[68:71]
	v_mfma_f32_16x16x32_bf16 v[64:67], v[156:159], v[188:191], v[64:67]
	s_barrier
	s_setprio 0
	s_add_i32 s36, s58, s40
	v_lshl_add_u64 v[204:205], v[204:205], 0, s[16:17]
	s_mov_b32 m0, s36
	ds_read_b128 v[160:163], v247 offset:49152
	ds_read_b128 v[164:167], v247 offset:50176
	ds_read_b128 v[168:171], v247 offset:51200
	ds_read_b128 v[172:175], v247 offset:52224
	ds_read_b128 v[176:179], v247 offset:53248
	ds_read_b128 v[180:183], v247 offset:54272
	ds_read_b128 v[184:187], v247 offset:55296
	ds_read_b128 v[188:191], v247 offset:56320
	global_load_lds_dwordx4 v[204:205], off
	s_add_i32 m0, s36, 0x2000
	s_add_u32 s34, s34, 0x40080
	v_lshl_add_u64 v[204:205], v[206:207], 0, s[16:17]
	s_addc_u32 s35, s35, 0
	s_add_i32 s36, s59, s40
	global_load_lds_dwordx4 v[204:205], off
	v_lshl_add_u64 v[204:205], s[34:35], 0, v[194:195]
	s_mov_b32 m0, s36
	s_nop 0
	global_load_lds_dwordx4 v[204:205], off
	v_lshl_add_u64 v[204:205], s[34:35], 0, v[198:199]
	s_add_i32 m0, s36, 0x2000
	s_nop 0
	global_load_lds_dwordx4 v[204:205], off
	v_lshl_add_u64 v[204:205], v[208:209], 0, s[16:17]
	s_mov_b32 m0, s46
	s_nop 0
	global_load_lds_dwordx4 v[204:205], off
	v_lshl_add_u64 v[204:205], v[210:211], 0, s[16:17]
	s_mov_b32 m0, s47
	s_nop 0
	global_load_lds_dwordx4 v[204:205], off
	s_waitcnt vmcnt(8)
	s_waitcnt lgkmcnt(0)
	s_setprio 1
	s_barrier
	v_mfma_f32_16x16x32_bf16 v[60:63], v[120:123], v[160:163], v[60:63]
	v_mfma_f32_16x16x32_bf16 v[56:59], v[136:139], v[160:163], v[56:59]
	v_mfma_f32_16x16x32_bf16 v[44:47], v[120:123], v[168:171], v[44:47]
	v_mfma_f32_16x16x32_bf16 v[40:43], v[136:139], v[168:171], v[40:43]
	v_mfma_f32_16x16x32_bf16 v[28:31], v[120:123], v[176:179], v[28:31]
	v_mfma_f32_16x16x32_bf16 v[24:27], v[136:139], v[176:179], v[24:27]
	v_mfma_f32_16x16x32_bf16 v[12:15], v[120:123], v[184:187], v[12:15]
	v_mfma_f32_16x16x32_bf16 v[8:11], v[136:139], v[184:187], v[8:11]
	v_mfma_f32_16x16x32_bf16 v[60:63], v[128:131], v[164:167], v[60:63]
	v_mfma_f32_16x16x32_bf16 v[56:59], v[140:143], v[164:167], v[56:59]
	v_mfma_f32_16x16x32_bf16 v[44:47], v[128:131], v[172:175], v[44:47]
	v_mfma_f32_16x16x32_bf16 v[40:43], v[140:143], v[172:175], v[40:43]
	v_mfma_f32_16x16x32_bf16 v[28:31], v[128:131], v[180:183], v[28:31]
	v_mfma_f32_16x16x32_bf16 v[24:27], v[140:143], v[180:183], v[24:27]
	v_mfma_f32_16x16x32_bf16 v[12:15], v[128:131], v[188:191], v[12:15]
	v_mfma_f32_16x16x32_bf16 v[8:11], v[140:143], v[188:191], v[8:11]
	v_mfma_f32_16x16x32_bf16 v[52:55], v[144:147], v[160:163], v[52:55]
	v_mfma_f32_16x16x32_bf16 v[48:51], v[152:155], v[160:163], v[48:51]
	v_mfma_f32_16x16x32_bf16 v[36:39], v[144:147], v[168:171], v[36:39]
	v_mfma_f32_16x16x32_bf16 v[32:35], v[152:155], v[168:171], v[32:35]
	v_mfma_f32_16x16x32_bf16 v[20:23], v[144:147], v[176:179], v[20:23]
	v_mfma_f32_16x16x32_bf16 v[16:19], v[152:155], v[176:179], v[16:19]
	v_mfma_f32_16x16x32_bf16 v[4:7], v[144:147], v[184:187], v[4:7]
	v_mfma_f32_16x16x32_bf16 v[0:3], v[152:155], v[184:187], v[0:3]
	v_mfma_f32_16x16x32_bf16 v[52:55], v[148:151], v[164:167], v[52:55]
	v_mfma_f32_16x16x32_bf16 v[48:51], v[156:159], v[164:167], v[48:51]
	v_mfma_f32_16x16x32_bf16 v[36:39], v[148:151], v[172:175], v[36:39]
	v_mfma_f32_16x16x32_bf16 v[32:35], v[156:159], v[172:175], v[32:35]
	v_mfma_f32_16x16x32_bf16 v[20:23], v[148:151], v[180:183], v[20:23]
	v_mfma_f32_16x16x32_bf16 v[16:19], v[156:159], v[180:183], v[16:19]
	v_mfma_f32_16x16x32_bf16 v[4:7], v[148:151], v[188:191], v[4:7]
	v_mfma_f32_16x16x32_bf16 v[0:3], v[156:159], v[188:191], v[0:3]
	s_barrier
	s_setprio 0
	s_add_i32 s57, s57, 2
	s_add_u32 s30, s30, 0x100
	s_addc_u32 s31, s31, 0
	s_add_u32 s55, s55, 0x100
	s_addc_u32 s56, s56, 0
	s_cmp_gt_u32 s57, 13
; #define PG8_STAGE(bufoff, gbase, voff) do { _Pragma("unroll") for (int _i = 0; _i < 2; ++_i) \
;         __builtin_amdgcn_global_load_lds((const unsigned*)((const char*)(gbase) + (voff)[_i]), (PG8_LAS unsigned*)(lds + (bufoff) + ldsw + _i * 8192), 16, 0, 0); } while (0)
; #define PG8_LDA(dst, b, h) do { _Pragma("unroll") for (int m = 0; m < 4; ++m) _Pragma("unroll") for (int k = 0; k < 2; ++k) dst[m][k] = *(const PG8_LAS bf16x8*)(lds + PG8_SA(b, h) + aoff + m * 2048 + k * 1024); } while (0)
; #define PG8_LDB(dst, b, h) do { _Pragma("unroll") for (int n = 0; n < 2; ++n) _Pragma("unroll") for (int k = 0; k < 2; ++k) dst[n][k] = *(const PG8_LAS bf16x8*)(lds + PG8_SB(b, h) + boff + n * 2048 + k * 1024); } while (0)
; #define PG8_MMA(ai, bj, At, Bt) do { __builtin_amdgcn_s_setprio(1); _Pragma("unroll") for (int m = 0; m < 4; ++m) _Pragma("unroll") for (int n = 0; n < 2; ++n) _Pragma("unroll") for (int k = 0; k < 2; ++k) \
;         acc[ai][bj][m][n] = __builtin_amdgcn_mfma_f32_16x16x32_bf16(Bt[n][k], At[m][k], acc[ai][bj][m][n], 0, 0, 0); __builtin_amdgcn_s_setprio(0); } while (0)
; #define PG8_WAIT_V(n) asm volatile("s_waitcnt vmcnt(" #n ")" ::: "memory")
; #define PG8_WAIT_L(n) asm volatile("s_waitcnt lgkmcnt(" #n ")" ::: "memory")
; #define PG8_BAR __builtin_amdgcn_s_barrier()
; #define PG8_SCHED __builtin_amdgcn_sched_barrier(0)
; template <class Epi, class Sched, bool ALIGN_EPI = false, bool SP2 = false>
; __device__ __forceinline__ void gemm_phase(PG8_LAS unsigned char* lds, const Gemm g, const Sched& S, const Epi& E) {
;     ...
;             PG8_LDB(B0, 0, 0); PG8_LDB(B1, 0, 1); PG8_SCHED; PG8_LDA(At, 0, 0); PG8_STAGE(PG8_SA(1, 1), a1 + hstep, voffA);
;             PG8_WAIT_V(8); PG8_WAIT_L(0); PG8_BAR; PG8_MMA(0, 0, At, B0); PG8_MMA(0, 1, At, B1); PG8_BAR; PG8_SCHED;
;             PG8_LDA(At, 0, 1); PG8_STAGE(PG8_SB(0, 0), b2, voffB); PG8_STAGE(PG8_SB(0, 1), b2 + hstep, voffB); PG8_STAGE(PG8_SA(0, 0), a2, voffA);
;             PG8_WAIT_V(8); PG8_WAIT_L(0); PG8_BAR; PG8_MMA(1, 0, At, B0); PG8_MMA(1, 1, At, B1); PG8_BAR; PG8_SCHED;
.LBB0_960:
	ds_read_b128 v[120:123], v245
	ds_read_b128 v[128:131], v245 offset:1024
	ds_read_b128 v[136:139], v245 offset:2048
	ds_read_b128 v[140:143], v245 offset:3072
	ds_read_b128 v[144:147], v246
	ds_read_b128 v[148:151], v246 offset:1024
	ds_read_b128 v[152:155], v246 offset:2048
	ds_read_b128 v[156:159], v246 offset:3072
	s_add_u32 s34, s30, 0xfffc0080
	s_addc_u32 s35, s31, -1
	s_cmp_eq_u32 s57, 12
	s_cselect_b32 s37, s23, s35
	s_cselect_b32 s36, s29, s34
	s_cselect_b32 s35, s21, s56
	s_cselect_b32 s34, s54, s55
	v_lshl_add_u64 v[204:205], s[30:31], 0, v[200:201]
	s_add_i32 m0, s41, 0xc000
	ds_read_b128 v[160:163], v247
	ds_read_b128 v[164:167], v247 offset:1024
	ds_read_b128 v[168:171], v247 offset:2048
	ds_read_b128 v[172:175], v247 offset:3072
	ds_read_b128 v[176:179], v247 offset:4096
	ds_read_b128 v[180:183], v247 offset:5120
	ds_read_b128 v[184:187], v247 offset:6144
	ds_read_b128 v[188:191], v247 offset:7168
	global_load_lds_dwordx4 v[204:205], off
	v_lshl_add_u64 v[204:205], s[30:31], 0, v[202:203]
	s_add_i32 m0, s41, 0xe000
	s_nop 0
	global_load_lds_dwordx4 v[204:205], off
	s_waitcnt vmcnt(8)
	s_waitcnt lgkmcnt(0)
	s_setprio 1
	s_barrier
	v_mfma_f32_16x16x32_bf16 v[132:135], v[120:123], v[160:163], v[132:135]
	v_mfma_f32_16x16x32_bf16 v[124:127], v[136:139], v[160:163], v[124:127]
	v_mfma_f32_16x16x32_bf16 v[108:111], v[120:123], v[168:171], v[108:111]
	v_mfma_f32_16x16x32_bf16 v[104:107], v[136:139], v[168:171], v[104:107]
	v_mfma_f32_16x16x32_bf16 v[92:95], v[120:123], v[176:179], v[92:95]
	v_mfma_f32_16x16x32_bf16 v[88:91], v[136:139], v[176:179], v[88:91]
	v_mfma_f32_16x16x32_bf16 v[76:79], v[120:123], v[184:187], v[76:79]
	v_mfma_f32_16x16x32_bf16 v[72:75], v[136:139], v[184:187], v[72:75]
	v_mfma_f32_16x16x32_bf16 v[132:135], v[128:131], v[164:167], v[132:135]
	v_mfma_f32_16x16x32_bf16 v[124:127], v[140:143], v[164:167], v[124:127]
	v_mfma_f32_16x16x32_bf16 v[108:111], v[128:131], v[172:175], v[108:111]
	v_mfma_f32_16x16x32_bf16 v[104:107], v[140:143], v[172:175], v[104:107]
	v_mfma_f32_16x16x32_bf16 v[92:95], v[128:131], v[180:183], v[92:95]
	v_mfma_f32_16x16x32_bf16 v[88:91], v[140:143], v[180:183], v[88:91]
	v_mfma_f32_16x16x32_bf16 v[76:79], v[128:131], v[188:191], v[76:79]
	v_mfma_f32_16x16x32_bf16 v[72:75], v[140:143], v[188:191], v[72:75]
	v_mfma_f32_16x16x32_bf16 v[116:119], v[144:147], v[160:163], v[116:119]
	v_mfma_f32_16x16x32_bf16 v[112:115], v[152:155], v[160:163], v[112:115]
	v_mfma_f32_16x16x32_bf16 v[100:103], v[144:147], v[168:171], v[100:103]
	v_mfma_f32_16x16x32_bf16 v[96:99], v[152:155], v[168:171], v[96:99]
	v_mfma_f32_16x16x32_bf16 v[84:87], v[144:147], v[176:179], v[84:87]
	v_mfma_f32_16x16x32_bf16 v[80:83], v[152:155], v[176:179], v[80:83]
	v_mfma_f32_16x16x32_bf16 v[68:71], v[144:147], v[184:187], v[68:71]
	v_mfma_f32_16x16x32_bf16 v[64:67], v[152:155], v[184:187], v[64:67]
	v_mfma_f32_16x16x32_bf16 v[116:119], v[148:151], v[164:167], v[116:119]
	v_mfma_f32_16x16x32_bf16 v[112:115], v[156:159], v[164:167], v[112:115]
	v_mfma_f32_16x16x32_bf16 v[100:103], v[148:151], v[172:175], v[100:103]
	v_mfma_f32_16x16x32_bf16 v[96:99], v[156:159], v[172:175], v[96:99]
	v_mfma_f32_16x16x32_bf16 v[84:87], v[148:151], v[180:183], v[84:87]
	v_mfma_f32_16x16x32_bf16 v[80:83], v[156:159], v[180:183], v[80:83]
	v_mfma_f32_16x16x32_bf16 v[68:71], v[148:151], v[188:191], v[68:71]
	v_mfma_f32_16x16x32_bf16 v[64:67], v[156:159], v[188:191], v[64:67]
	s_barrier
	s_setprio 0
	s_add_i32 s58, s51, s40
	v_lshl_add_u64 v[204:205], s[34:35], 0, v[194:195]
	s_mov_b32 m0, s58
	ds_read_b128 v[160:163], v247 offset:16384
	ds_read_b128 v[164:167], v247 offset:17408
	ds_read_b128 v[168:171], v247 offset:18432
	ds_read_b128 v[172:175], v247 offset:19456
	ds_read_b128 v[176:179], v247 offset:20480
	ds_read_b128 v[180:183], v247 offset:21504
	ds_read_b128 v[184:187], v247 offset:22528
	ds_read_b128 v[188:191], v247 offset:23552
	global_load_lds_dwordx4 v[204:205], off
	s_add_i32 m0, s58, 0x2000
	s_add_u32 s58, s34, 0x40000
	v_lshl_add_u64 v[206:207], s[34:35], 0, v[198:199]
	s_addc_u32 s59, s35, 0
	s_add_i32 s60, s52, s40
	global_load_lds_dwordx4 v[206:207], off
	v_lshl_add_u64 v[208:209], s[58:59], 0, v[194:195]
	s_mov_b32 m0, s60
	v_lshl_add_u64 v[210:211], s[36:37], 0, v[196:197]
	global_load_lds_dwordx4 v[208:209], off
	v_lshl_add_u64 v[208:209], s[58:59], 0, v[198:199]
	s_add_i32 m0, s60, 0x2000
	s_nop 0
	global_load_lds_dwordx4 v[208:209], off
	v_lshl_add_u64 v[208:209], s[36:37], 0, v[192:193]
	s_mov_b32 m0, s41
	s_nop 0
	global_load_lds_dwordx4 v[208:209], off
	s_mov_b32 m0, s42
	s_nop 0
	global_load_lds_dwordx4 v[210:211], off
	s_waitcnt vmcnt(8)
	s_waitcnt lgkmcnt(0)
	s_setprio 1
	s_barrier
; #define PG8_STAGE(bufoff, gbase, voff) do { _Pragma("unroll") for (int _i = 0; _i < 2; ++_i) \
;         __builtin_amdgcn_global_load_lds((const unsigned*)((const char*)(gbase) + (voff)[_i]), (PG8_LAS unsigned*)(lds + (bufoff) + ldsw + _i * 8192), 16, 0, 0); } while (0)
; #define PG8_LDA(dst, b, h) do { _Pragma("unroll") for (int m = 0; m < 4; ++m) _Pragma("unroll") for (int k = 0; k < 2; ++k) dst[m][k] = *(const PG8_LAS bf16x8*)(lds + PG8_SA(b, h) + aoff + m * 2048 + k * 1024); } while (0)
; #define PG8_LDB(dst, b, h) do { _Pragma("unroll") for (int n = 0; n < 2; ++n) _Pragma("unroll") for (int k = 0; k < 2; ++k) dst[n][k] = *(const PG8_LAS bf16x8*)(lds + PG8_SB(b, h) + boff + n * 2048 + k * 1024); } while (0)
; #define PG8_MMA(ai, bj, At, Bt) do { __builtin_amdgcn_s_setprio(1); _Pragma("unroll") for (int m = 0; m < 4; ++m) _Pragma("unroll") for (int n = 0; n < 2; ++n) _Pragma("unroll") for (int k = 0; k < 2; ++k) \
;         acc[ai][bj][m][n] = __builtin_amdgcn_mfma_f32_16x16x32_bf16(Bt[n][k], At[m][k], acc[ai][bj][m][n], 0, 0, 0); __builtin_amdgcn_s_setprio(0); } while (0)
; #define PG8_WAIT_V(n) asm volatile("s_waitcnt vmcnt(" #n ")" ::: "memory")
; #define PG8_WAIT_L(n) asm volatile("s_waitcnt lgkmcnt(" #n ")" ::: "memory")
; #define PG8_BAR __builtin_amdgcn_s_barrier()
; #define PG8_SCHED __builtin_amdgcn_sched_barrier(0)
; template <class Epi, class Sched, bool ALIGN_EPI = false, bool SP2 = false>
; __device__ __forceinline__ void gemm_phase(PG8_LAS unsigned char* lds, const Gemm g, const Sched& S, const Epi& E) {
;     ...
;             PG8_WAIT_V(8); PG8_WAIT_L(0); PG8_BAR; PG8_MMA(1, 0, At, B0); PG8_MMA(1, 1, At, B1); PG8_BAR; PG8_SCHED;
;             PG8_LDB(B0, 1, 0); PG8_LDB(B1, 1, 1); PG8_SCHED; PG8_LDA(At, 1, 0); PG8_STAGE(PG8_SA(0, 1), a2 + hstep, voffA);
;             PG8_WAIT_V(8); PG8_WAIT_L(0); PG8_BAR; PG8_MMA(0, 0, At, B0); PG8_MMA(0, 1, At, B1); PG8_BAR; PG8_SCHED;
	v_mfma_f32_16x16x32_bf16 v[60:63], v[120:123], v[160:163], v[60:63]
	v_mfma_f32_16x16x32_bf16 v[56:59], v[136:139], v[160:163], v[56:59]
	v_mfma_f32_16x16x32_bf16 v[44:47], v[120:123], v[168:171], v[44:47]
	v_mfma_f32_16x16x32_bf16 v[40:43], v[136:139], v[168:171], v[40:43]
	v_mfma_f32_16x16x32_bf16 v[28:31], v[120:123], v[176:179], v[28:31]
	v_mfma_f32_16x16x32_bf16 v[24:27], v[136:139], v[176:179], v[24:27]
	v_mfma_f32_16x16x32_bf16 v[12:15], v[120:123], v[184:187], v[12:15]
	v_mfma_f32_16x16x32_bf16 v[8:11], v[136:139], v[184:187], v[8:11]
	v_mfma_f32_16x16x32_bf16 v[60:63], v[128:131], v[164:167], v[60:63]
	v_mfma_f32_16x16x32_bf16 v[56:59], v[140:143], v[164:167], v[56:59]
	v_mfma_f32_16x16x32_bf16 v[44:47], v[128:131], v[172:175], v[44:47]
	v_mfma_f32_16x16x32_bf16 v[40:43], v[140:143], v[172:175], v[40:43]
	v_mfma_f32_16x16x32_bf16 v[28:31], v[128:131], v[180:183], v[28:31]
	v_mfma_f32_16x16x32_bf16 v[24:27], v[140:143], v[180:183], v[24:27]
	v_mfma_f32_16x16x32_bf16 v[12:15], v[128:131], v[188:191], v[12:15]
	v_mfma_f32_16x16x32_bf16 v[8:11], v[140:143], v[188:191], v[8:11]
	v_mfma_f32_16x16x32_bf16 v[52:55], v[144:147], v[160:163], v[52:55]
	v_mfma_f32_16x16x32_bf16 v[48:51], v[152:155], v[160:163], v[48:51]
	v_mfma_f32_16x16x32_bf16 v[36:39], v[144:147], v[168:171], v[36:39]
	v_mfma_f32_16x16x32_bf16 v[32:35], v[152:155], v[168:171], v[32:35]
	v_mfma_f32_16x16x32_bf16 v[20:23], v[144:147], v[176:179], v[20:23]
	v_mfma_f32_16x16x32_bf16 v[16:19], v[152:155], v[176:179], v[16:19]
	v_mfma_f32_16x16x32_bf16 v[4:7], v[144:147], v[184:187], v[4:7]
	v_mfma_f32_16x16x32_bf16 v[0:3], v[152:155], v[184:187], v[0:3]
	v_mfma_f32_16x16x32_bf16 v[52:55], v[148:151], v[164:167], v[52:55]
	v_mfma_f32_16x16x32_bf16 v[48:51], v[156:159], v[164:167], v[48:51]
	v_mfma_f32_16x16x32_bf16 v[36:39], v[148:151], v[172:175], v[36:39]
	v_mfma_f32_16x16x32_bf16 v[32:35], v[156:159], v[172:175], v[32:35]
	v_mfma_f32_16x16x32_bf16 v[20:23], v[148:151], v[180:183], v[20:23]
	v_mfma_f32_16x16x32_bf16 v[16:19], v[156:159], v[180:183], v[16:19]
	v_mfma_f32_16x16x32_bf16 v[4:7], v[148:151], v[188:191], v[4:7]
	v_mfma_f32_16x16x32_bf16 v[0:3], v[156:159], v[188:191], v[0:3]
	s_barrier
	s_setprio 0
	s_add_i32 s58, 0, 0x18000
	s_add_i32 s59, 0, 0x1c000
	v_add_u32_e32 v140, s58, v243
	v_add_u32_e32 v156, s59, v243
	ds_read_b128 v[120:123], v140
	ds_read_b128 v[128:131], v140 offset:1024
	ds_read_b128 v[136:139], v140 offset:2048
	ds_read_b128 v[140:143], v140 offset:3072
	ds_read_b128 v[144:147], v156
	ds_read_b128 v[148:151], v156 offset:1024
	ds_read_b128 v[152:155], v156 offset:2048
	ds_read_b128 v[156:159], v156 offset:3072
	s_add_u32 s36, s36, 0x40000
	s_addc_u32 s37, s37, 0
	s_mov_b32 m0, s43
	v_lshl_add_u64 v[212:213], s[36:37], 0, v[192:193]
	ds_read_b128 v[160:163], v247 offset:32768
	ds_read_b128 v[164:167], v247 offset:33792
	ds_read_b128 v[168:171], v247 offset:34816
	ds_read_b128 v[172:175], v247 offset:35840
	ds_read_b128 v[176:179], v247 offset:36864
	ds_read_b128 v[180:183], v247 offset:37888
	ds_read_b128 v[184:187], v247 offset:38912
	ds_read_b128 v[188:191], v247 offset:39936
	global_load_lds_dwordx4 v[212:213], off
	v_lshl_add_u64 v[212:213], s[36:37], 0, v[196:197]
	s_mov_b32 m0, s44
	s_nop 0
	global_load_lds_dwordx4 v[212:213], off
	s_waitcnt vmcnt(8)
	s_waitcnt lgkmcnt(0)
	s_setprio 1
	s_barrier
	v_mfma_f32_16x16x32_bf16 v[132:135], v[120:123], v[160:163], v[132:135]
	v_mfma_f32_16x16x32_bf16 v[124:127], v[136:139], v[160:163], v[124:127]
	v_mfma_f32_16x16x32_bf16 v[108:111], v[120:123], v[168:171], v[108:111]
	v_mfma_f32_16x16x32_bf16 v[104:107], v[136:139], v[168:171], v[104:107]
	v_mfma_f32_16x16x32_bf16 v[92:95], v[120:123], v[176:179], v[92:95]
	v_mfma_f32_16x16x32_bf16 v[88:91], v[136:139], v[176:179], v[88:91]
	v_mfma_f32_16x16x32_bf16 v[76:79], v[120:123], v[184:187], v[76:79]
	v_mfma_f32_16x16x32_bf16 v[72:75], v[136:139], v[184:187], v[72:75]
	v_mfma_f32_16x16x32_bf16 v[132:135], v[128:131], v[164:167], v[132:135]
	v_mfma_f32_16x16x32_bf16 v[124:127], v[140:143], v[164:167], v[124:127]
	v_mfma_f32_16x16x32_bf16 v[108:111], v[128:131], v[172:175], v[108:111]
	v_mfma_f32_16x16x32_bf16 v[104:107], v[140:143], v[172:175], v[104:107]
	v_mfma_f32_16x16x32_bf16 v[92:95], v[128:131], v[180:183], v[92:95]
	v_mfma_f32_16x16x32_bf16 v[88:91], v[140:143], v[180:183], v[88:91]
	v_mfma_f32_16x16x32_bf16 v[76:79], v[128:131], v[188:191], v[76:79]
	v_mfma_f32_16x16x32_bf16 v[72:75], v[140:143], v[188:191], v[72:75]
	v_mfma_f32_16x16x32_bf16 v[116:119], v[144:147], v[160:163], v[116:119]
	v_mfma_f32_16x16x32_bf16 v[112:115], v[152:155], v[160:163], v[112:115]
	v_mfma_f32_16x16x32_bf16 v[100:103], v[144:147], v[168:171], v[100:103]
	v_mfma_f32_16x16x32_bf16 v[96:99], v[152:155], v[168:171], v[96:99]
	v_mfma_f32_16x16x32_bf16 v[84:87], v[144:147], v[176:179], v[84:87]
	v_mfma_f32_16x16x32_bf16 v[80:83], v[152:155], v[176:179], v[80:83]
	v_mfma_f32_16x16x32_bf16 v[68:71], v[144:147], v[184:187], v[68:71]
	v_mfma_f32_16x16x32_bf16 v[64:67], v[152:155], v[184:187], v[64:67]
	v_mfma_f32_16x16x32_bf16 v[116:119], v[148:151], v[164:167], v[116:119]
	v_mfma_f32_16x16x32_bf16 v[112:115], v[156:159], v[164:167], v[112:115]
	v_mfma_f32_16x16x32_bf16 v[100:103], v[148:151], v[172:175], v[100:103]
	v_mfma_f32_16x16x32_bf16 v[96:99], v[156:159], v[172:175], v[96:99]
	v_mfma_f32_16x16x32_bf16 v[84:87], v[148:151], v[180:183], v[84:87]
	v_mfma_f32_16x16x32_bf16 v[80:83], v[156:159], v[180:183], v[80:83]
	v_mfma_f32_16x16x32_bf16 v[68:71], v[148:151], v[188:191], v[68:71]
	v_mfma_f32_16x16x32_bf16 v[64:67], v[156:159], v[188:191], v[64:67]
	s_barrier
; #define PG8_STAGE(bufoff, gbase, voff) do { _Pragma("unroll") for (int _i = 0; _i < 2; ++_i) \
;         __builtin_amdgcn_global_load_lds((const unsigned*)((const char*)(gbase) + (voff)[_i]), (PG8_LAS unsigned*)(lds + (bufoff) + ldsw + _i * 8192), 16, 0, 0); } while (0)
; #define PG8_LDA(dst, b, h) do { _Pragma("unroll") for (int m = 0; m < 4; ++m) _Pragma("unroll") for (int k = 0; k < 2; ++k) dst[m][k] = *(const PG8_LAS bf16x8*)(lds + PG8_SA(b, h) + aoff + m * 2048 + k * 1024); } while (0)
; #define PG8_MMA(ai, bj, At, Bt) do { __builtin_amdgcn_s_setprio(1); _Pragma("unroll") for (int m = 0; m < 4; ++m) _Pragma("unroll") for (int n = 0; n < 2; ++n) _Pragma("unroll") for (int k = 0; k < 2; ++k) \
;         acc[ai][bj][m][n] = __builtin_amdgcn_mfma_f32_16x16x32_bf16(Bt[n][k], At[m][k], acc[ai][bj][m][n], 0, 0, 0); __builtin_amdgcn_s_setprio(0); } while (0)
; #define PG8_WAIT_V(n) asm volatile("s_waitcnt vmcnt(" #n ")" ::: "memory")
; #define PG8_WAIT_L(n) asm volatile("s_waitcnt lgkmcnt(" #n ")" ::: "memory")
; #define PG8_BAR __builtin_amdgcn_s_barrier()
; #define PG8_SCHED __builtin_amdgcn_sched_barrier(0)
; template <class Epi, class Sched, bool ALIGN_EPI = false, bool SP2 = false>
; __device__ __forceinline__ void gemm_phase(PG8_LAS unsigned char* lds, const Gemm g, const Sched& S, const Epi& E) {
;     ...
;             PG8_LDA(At, 1, 1); PG8_STAGE(PG8_SB(1, 0), b3, voffB); PG8_STAGE(PG8_SB(1, 1), b3 + hstep, voffB); PG8_STAGE(PG8_SA(1, 0), a3, voffA);
;             PG8_WAIT_V(8); PG8_WAIT_L(0); PG8_BAR; PG8_MMA(1, 0, At, B0); PG8_MMA(1, 1, At, B1); PG8_BAR; PG8_SCHED;
;     ...
;         if constexpr (ALIGN_EPI) { if (wr == 0) PG8_BAR; }
	s_setprio 0
	s_add_i32 s36, s58, s40
	v_lshl_add_u64 v[204:205], v[204:205], 0, s[16:17]
	s_mov_b32 m0, s36
	ds_read_b128 v[160:163], v247 offset:49152
	ds_read_b128 v[164:167], v247 offset:50176
	ds_read_b128 v[168:171], v247 offset:51200
	ds_read_b128 v[172:175], v247 offset:52224
	ds_read_b128 v[176:179], v247 offset:53248
	ds_read_b128 v[180:183], v247 offset:54272
	ds_read_b128 v[184:187], v247 offset:55296
	ds_read_b128 v[188:191], v247 offset:56320
	global_load_lds_dwordx4 v[204:205], off
	s_add_i32 m0, s36, 0x2000
	s_add_u32 s34, s34, 0x40080
	v_lshl_add_u64 v[204:205], v[206:207], 0, s[16:17]
	s_addc_u32 s35, s35, 0
	s_add_i32 s36, s59, s40
	global_load_lds_dwordx4 v[204:205], off
	v_lshl_add_u64 v[204:205], s[34:35], 0, v[194:195]
	s_mov_b32 m0, s36
	s_nop 0
	global_load_lds_dwordx4 v[204:205], off
	v_lshl_add_u64 v[204:205], s[34:35], 0, v[198:199]
	s_add_i32 m0, s36, 0x2000
	s_nop 0
	global_load_lds_dwordx4 v[204:205], off
	v_lshl_add_u64 v[204:205], v[208:209], 0, s[16:17]
	s_mov_b32 m0, s46
	s_nop 0
	global_load_lds_dwordx4 v[204:205], off
	v_lshl_add_u64 v[204:205], v[210:211], 0, s[16:17]
	s_mov_b32 m0, s47
	s_nop 0
	global_load_lds_dwordx4 v[204:205], off
	s_waitcnt vmcnt(8)
	s_waitcnt lgkmcnt(0)
	s_setprio 1
	s_barrier
	v_mfma_f32_16x16x32_bf16 v[60:63], v[120:123], v[160:163], v[60:63]
	v_mfma_f32_16x16x32_bf16 v[56:59], v[136:139], v[160:163], v[56:59]
	v_mfma_f32_16x16x32_bf16 v[44:47], v[120:123], v[168:171], v[44:47]
	v_mfma_f32_16x16x32_bf16 v[40:43], v[136:139], v[168:171], v[40:43]
	v_mfma_f32_16x16x32_bf16 v[28:31], v[120:123], v[176:179], v[28:31]
	v_mfma_f32_16x16x32_bf16 v[24:27], v[136:139], v[176:179], v[24:27]
	v_mfma_f32_16x16x32_bf16 v[12:15], v[120:123], v[184:187], v[12:15]
	v_mfma_f32_16x16x32_bf16 v[8:11], v[136:139], v[184:187], v[8:11]
	v_mfma_f32_16x16x32_bf16 v[60:63], v[128:131], v[164:167], v[60:63]
	v_mfma_f32_16x16x32_bf16 v[56:59], v[140:143], v[164:167], v[56:59]
	v_mfma_f32_16x16x32_bf16 v[44:47], v[128:131], v[172:175], v[44:47]
	v_mfma_f32_16x16x32_bf16 v[40:43], v[140:143], v[172:175], v[40:43]
	v_mfma_f32_16x16x32_bf16 v[28:31], v[128:131], v[180:183], v[28:31]
	v_mfma_f32_16x16x32_bf16 v[24:27], v[140:143], v[180:183], v[24:27]
	v_mfma_f32_16x16x32_bf16 v[12:15], v[128:131], v[188:191], v[12:15]
	v_mfma_f32_16x16x32_bf16 v[8:11], v[140:143], v[188:191], v[8:11]
	v_mfma_f32_16x16x32_bf16 v[52:55], v[144:147], v[160:163], v[52:55]
	v_mfma_f32_16x16x32_bf16 v[48:51], v[152:155], v[160:163], v[48:51]
	v_mfma_f32_16x16x32_bf16 v[36:39], v[144:147], v[168:171], v[36:39]
	v_mfma_f32_16x16x32_bf16 v[32:35], v[152:155], v[168:171], v[32:35]
	v_mfma_f32_16x16x32_bf16 v[20:23], v[144:147], v[176:179], v[20:23]
	v_mfma_f32_16x16x32_bf16 v[16:19], v[152:155], v[176:179], v[16:19]
	v_mfma_f32_16x16x32_bf16 v[4:7], v[144:147], v[184:187], v[4:7]
	v_mfma_f32_16x16x32_bf16 v[0:3], v[152:155], v[184:187], v[0:3]
	v_mfma_f32_16x16x32_bf16 v[52:55], v[148:151], v[164:167], v[52:55]
	v_mfma_f32_16x16x32_bf16 v[48:51], v[156:159], v[164:167], v[48:51]
	v_mfma_f32_16x16x32_bf16 v[36:39], v[148:151], v[172:175], v[36:39]
	v_mfma_f32_16x16x32_bf16 v[32:35], v[156:159], v[172:175], v[32:35]
	v_mfma_f32_16x16x32_bf16 v[20:23], v[148:151], v[180:183], v[20:23]
	v_mfma_f32_16x16x32_bf16 v[16:19], v[156:159], v[180:183], v[16:19]
	v_mfma_f32_16x16x32_bf16 v[4:7], v[148:151], v[188:191], v[4:7]
	v_mfma_f32_16x16x32_bf16 v[0:3], v[156:159], v[188:191], v[0:3]
	s_barrier
	s_setprio 0
	s_add_i32 s57, s57, 2
	s_add_u32 s30, s30, 0x100
	s_addc_u32 s31, s31, 0
	s_add_u32 s55, s55, 0x100
	s_addc_u32 s56, s56, 0
	s_cmp_gt_u32 s57, 13
	s_cbranch_scc0 .LBB0_960
	s_and_b64 vcc, exec, s[18:19]
	s_cbranch_vccz .LBB0_963
	s_barrier

; #define PG8_STAGE(bufoff, gbase, voff) do { _Pragma("unroll") for (int _i = 0; _i < 2; ++_i) \
;         __builtin_amdgcn_global_load_lds((const unsigned*)((const char*)(gbase) + (voff)[_i]), (PG8_LAS unsigned*)(lds + (bufoff) + ldsw + _i * 8192), 16, 0, 0); } while (0)
; #define PG8_LDA(dst, b, h) do { _Pragma("unroll") for (int m = 0; m < 4; ++m) _Pragma("unroll") for (int k = 0; k < 2; ++k) dst[m][k] = *(const PG8_LAS bf16x8*)(lds + PG8_SA(b, h) + aoff + m * 2048 + k * 1024); } while (0)
; #define PG8_LDB(dst, b, h) do { _Pragma("unroll") for (int n = 0; n < 2; ++n) _Pragma("unroll") for (int k = 0; k < 2; ++k) dst[n][k] = *(const PG8_LAS bf16x8*)(lds + PG8_SB(b, h) + boff + n * 2048 + k * 1024); } while (0)
; #define PG8_WAIT_V(n) asm volatile("s_waitcnt vmcnt(" #n ")" ::: "memory")
; #define PG8_WAIT_L(n) asm volatile("s_waitcnt lgkmcnt(" #n ")" ::: "memory")
; #define PG8_BAR __builtin_amdgcn_s_barrier()
; #define PG8_SCHED __builtin_amdgcn_sched_barrier(0)
; template <class Epi, class Sched, bool ALIGN_EPI = false, bool SP2 = false>
; __device__ __forceinline__ void gemm_phase(PG8_LAS unsigned char* lds, const Gemm g, const Sched& S, const Epi& E) {
;     ...
;         const char* nA = has_next ? (const char*)g.A + (size_t)nxt.pm * tstep : cA; const char* nB = has_next ? (const char*)g.Bt + (size_t)nxt.pn * tstep : cB;
;         for (int t = 0; t < nt; t += 2) {
;             const bool last = (t == nt - 2);
;             const char* a1 = cA + (size_t)(t + 1) * kstep;
;             const char* a2 = last ? nA : cA + (size_t)(t + 2) * kstep; const char* b2 = last ? nB : cB + (size_t)(t + 2) * kstep;
;             const char* a3 = a2 + kstep; const char* b3 = b2 + kstep;
;             if (last && has_next) S.a_ready(nxt, ui + 1);
;             if constexpr (SP2) {
;             PG8_LDB(B0, 0, 0); PG8_LDB(B1, 0, 1); PG8_SCHED; PG8_LDA(At, 0, 0); PG8_STAGE(PG8_SA(1, 1), a1 + hstep, voffA);
;             PG8_WAIT_V(8); PG8_WAIT_L(0); PG8_BAR; PG8_MMA(0, 0, At, B0); PG8_MMA(0, 1, At, B1); PG8_BAR; PG8_SCHED;
;             PG8_LDA(At, 0, 1); PG8_STAGE(PG8_SB(0, 0), b2, voffB); PG8_STAGE(PG8_SB(0, 1), b2 + hstep, voffB); PG8_STAGE(PG8_SA(0, 0), a2, voffA);
;             PG8_WAIT_V(8); PG8_WAIT_L(0); PG8_BAR; PG8_MMA(1, 0, At, B0); PG8_MMA(1, 1, At, B1); PG8_BAR; PG8_SCHED;
.LBB0_1048:
	s_ashr_i32 s17, s16, 31
	s_lshl_b64 s[18:19], s[16:17], 19
	s_add_u32 s18, s34, s18
	s_addc_u32 s19, s35, s19
	s_and_b64 s[20:21], s[0:1], exec
	s_cselect_b32 s17, s19, s25
	s_cselect_b32 s50, s18, s24
	s_ashr_i32 s15, s14, 31
	s_lshl_b64 s[20:21], s[14:15], 19
	s_add_u32 s20, s36, s20
	s_addc_u32 s21, s37, s21
	s_and_b64 s[28:29], s[0:1], exec
	s_cselect_b32 s15, s21, s27
	s_cselect_b32 s51, s20, s26
	s_add_u32 s24, s24, 0x40080
	s_addc_u32 s25, s25, 0
	s_add_u32 s52, s26, 0x100
	s_addc_u32 s53, s27, 0
	s_mov_b32 s54, -2
	s_add_u32 s26, s24, 0xfffc0080
	s_addc_u32 s27, s25, -1
	s_cmp_eq_u32 s54, 12
	s_cselect_b32 s29, s17, s27
	s_cselect_b32 s28, s50, s26
	s_cselect_b32 s27, s15, s53
	s_cselect_b32 s26, s51, s52
	v_lshl_add_u64 v[216:217], s[24:25], 0, v[136:137]
	s_add_i32 m0, s23, 0xc000
	global_load_lds_dwordx4 v[216:217], off
	v_lshl_add_u64 v[216:217], s[24:25], 0, v[138:139]
	s_add_i32 m0, s23, 0xe000
	s_nop 0
	global_load_lds_dwordx4 v[216:217], off
	s_waitcnt vmcnt(8)
	s_waitcnt lgkmcnt(0)
	s_setprio 1
	s_barrier
	v_mfma_f32_16x16x32_bf16 v[124:127], v[152:155], v[184:187], 0
	v_mfma_f32_16x16x32_bf16 v[120:123], v[160:163], v[184:187], 0
	v_mfma_f32_16x16x32_bf16 v[108:111], v[152:155], v[192:195], 0
	v_mfma_f32_16x16x32_bf16 v[104:107], v[160:163], v[192:195], 0
	v_mfma_f32_16x16x32_bf16 v[92:95], v[152:155], v[200:203], 0
	v_mfma_f32_16x16x32_bf16 v[88:91], v[160:163], v[200:203], 0
	v_mfma_f32_16x16x32_bf16 v[76:79], v[152:155], v[208:211], 0
	v_mfma_f32_16x16x32_bf16 v[72:75], v[160:163], v[208:211], 0
	v_mfma_f32_16x16x32_bf16 v[124:127], v[156:159], v[188:191], v[124:127]
	v_mfma_f32_16x16x32_bf16 v[120:123], v[164:167], v[188:191], v[120:123]
	v_mfma_f32_16x16x32_bf16 v[108:111], v[156:159], v[196:199], v[108:111]
	v_mfma_f32_16x16x32_bf16 v[104:107], v[164:167], v[196:199], v[104:107]
	v_mfma_f32_16x16x32_bf16 v[92:95], v[156:159], v[204:207], v[92:95]
	v_mfma_f32_16x16x32_bf16 v[88:91], v[164:167], v[204:207], v[88:91]
	v_mfma_f32_16x16x32_bf16 v[76:79], v[156:159], v[212:215], v[76:79]
	v_mfma_f32_16x16x32_bf16 v[72:75], v[164:167], v[212:215], v[72:75]
	v_mfma_f32_16x16x32_bf16 v[116:119], v[168:171], v[184:187], 0
	v_mfma_f32_16x16x32_bf16 v[112:115], v[176:179], v[184:187], 0
	v_mfma_f32_16x16x32_bf16 v[100:103], v[168:171], v[192:195], 0
	v_mfma_f32_16x16x32_bf16 v[96:99], v[176:179], v[192:195], 0
	v_mfma_f32_16x16x32_bf16 v[84:87], v[168:171], v[200:203], 0
	v_mfma_f32_16x16x32_bf16 v[80:83], v[176:179], v[200:203], 0
	v_mfma_f32_16x16x32_bf16 v[68:71], v[168:171], v[208:211], 0
	v_mfma_f32_16x16x32_bf16 v[64:67], v[176:179], v[208:211], 0
	v_mfma_f32_16x16x32_bf16 v[116:119], v[172:175], v[188:191], v[116:119]
	v_mfma_f32_16x16x32_bf16 v[112:115], v[180:183], v[188:191], v[112:115]
	v_mfma_f32_16x16x32_bf16 v[100:103], v[172:175], v[196:199], v[100:103]
	v_mfma_f32_16x16x32_bf16 v[96:99], v[180:183], v[196:199], v[96:99]
	v_mfma_f32_16x16x32_bf16 v[84:87], v[172:175], v[204:207], v[84:87]
	v_mfma_f32_16x16x32_bf16 v[80:83], v[180:183], v[204:207], v[80:83]
	v_mfma_f32_16x16x32_bf16 v[68:71], v[172:175], v[212:215], v[68:71]
	v_mfma_f32_16x16x32_bf16 v[64:67], v[180:183], v[212:215], v[64:67]
	s_barrier
	s_setprio 0
	s_add_i32 s55, s44, s33
	v_lshl_add_u64 v[216:217], s[26:27], 0, v[132:133]
	s_mov_b32 m0, s55
	ds_read_b128 v[184:187], v150 offset:16384
	ds_read_b128 v[188:191], v150 offset:17408
	ds_read_b128 v[192:195], v150 offset:18432
	ds_read_b128 v[196:199], v150 offset:19456
	ds_read_b128 v[200:203], v150 offset:20480
	ds_read_b128 v[204:207], v150 offset:21504
	ds_read_b128 v[208:211], v150 offset:22528
	ds_read_b128 v[212:215], v150 offset:23552
	global_load_lds_dwordx4 v[216:217], off
	s_add_i32 m0, s55, 0x2000
	s_add_u32 s56, s26, 0x40000
	v_lshl_add_u64 v[218:219], s[26:27], 0, v[128:129]
	s_addc_u32 s57, s27, 0
	s_add_i32 s55, s45, s33
	global_load_lds_dwordx4 v[218:219], off
	v_lshl_add_u64 v[220:221], s[56:57], 0, v[132:133]
	s_mov_b32 m0, s55
	v_lshl_add_u64 v[222:223], s[28:29], 0, v[130:131]
	global_load_lds_dwordx4 v[220:221], off
	v_lshl_add_u64 v[220:221], s[56:57], 0, v[128:129]
	s_add_i32 m0, s55, 0x2000
	s_nop 0
	global_load_lds_dwordx4 v[220:221], off
	v_lshl_add_u64 v[220:221], s[28:29], 0, v[134:135]
	s_mov_b32 m0, s23
	s_nop 0
	global_load_lds_dwordx4 v[220:221], off
	s_mov_b32 m0, s39
	s_nop 0
	global_load_lds_dwordx4 v[222:223], off
	s_waitcnt vmcnt(8)
	s_waitcnt lgkmcnt(0)
	s_setprio 1
	s_barrier
	v_mfma_f32_16x16x32_bf16 v[60:63], v[152:155], v[184:187], 0
	v_mfma_f32_16x16x32_bf16 v[56:59], v[160:163], v[184:187], 0
	v_mfma_f32_16x16x32_bf16 v[44:47], v[152:155], v[192:195], 0
	v_mfma_f32_16x16x32_bf16 v[40:43], v[160:163], v[192:195], 0
	v_mfma_f32_16x16x32_bf16 v[28:31], v[152:155], v[200:203], 0
	v_mfma_f32_16x16x32_bf16 v[24:27], v[160:163], v[200:203], 0
	v_mfma_f32_16x16x32_bf16 v[12:15], v[152:155], v[208:211], 0
	v_mfma_f32_16x16x32_bf16 v[8:11], v[160:163], v[208:211], 0
	v_mfma_f32_16x16x32_bf16 v[60:63], v[156:159], v[188:191], v[60:63]
	v_mfma_f32_16x16x32_bf16 v[56:59], v[164:167], v[188:191], v[56:59]
	v_mfma_f32_16x16x32_bf16 v[44:47], v[156:159], v[196:199], v[44:47]
	v_mfma_f32_16x16x32_bf16 v[40:43], v[164:167], v[196:199], v[40:43]
	v_mfma_f32_16x16x32_bf16 v[28:31], v[156:159], v[204:207], v[28:31]
	v_mfma_f32_16x16x32_bf16 v[24:27], v[164:167], v[204:207], v[24:27]
	v_mfma_f32_16x16x32_bf16 v[12:15], v[156:159], v[212:215], v[12:15]
	v_mfma_f32_16x16x32_bf16 v[8:11], v[164:167], v[212:215], v[8:11]
	v_mfma_f32_16x16x32_bf16 v[52:55], v[168:171], v[184:187], 0
	v_mfma_f32_16x16x32_bf16 v[48:51], v[176:179], v[184:187], 0
	v_mfma_f32_16x16x32_bf16 v[36:39], v[168:171], v[192:195], 0
	v_mfma_f32_16x16x32_bf16 v[32:35], v[176:179], v[192:195], 0
	v_mfma_f32_16x16x32_bf16 v[20:23], v[168:171], v[200:203], 0
	v_mfma_f32_16x16x32_bf16 v[16:19], v[176:179], v[200:203], 0
	v_mfma_f32_16x16x32_bf16 v[4:7], v[168:171], v[208:211], 0
	v_mfma_f32_16x16x32_bf16 v[0:3], v[176:179], v[208:211], 0
	v_mfma_f32_16x16x32_bf16 v[52:55], v[172:175], v[188:191], v[52:55]
	v_mfma_f32_16x16x32_bf16 v[48:51], v[180:183], v[188:191], v[48:51]
	v_mfma_f32_16x16x32_bf16 v[36:39], v[172:175], v[196:199], v[36:39]
	v_mfma_f32_16x16x32_bf16 v[32:35], v[180:183], v[196:199], v[32:35]
	v_mfma_f32_16x16x32_bf16 v[20:23], v[172:175], v[204:207], v[20:23]
	v_mfma_f32_16x16x32_bf16 v[16:19], v[180:183], v[204:207], v[16:19]
	v_mfma_f32_16x16x32_bf16 v[4:7], v[172:175], v[212:215], v[4:7]
	v_mfma_f32_16x16x32_bf16 v[0:3], v[180:183], v[212:215], v[0:3]
	s_barrier
; #define PG8_STAGE(bufoff, gbase, voff) do { _Pragma("unroll") for (int _i = 0; _i < 2; ++_i) \
;         __builtin_amdgcn_global_load_lds((const unsigned*)((const char*)(gbase) + (voff)[_i]), (PG8_LAS unsigned*)(lds + (bufoff) + ldsw + _i * 8192), 16, 0, 0); } while (0)
; #define PG8_LDA(dst, b, h) do { _Pragma("unroll") for (int m = 0; m < 4; ++m) _Pragma("unroll") for (int k = 0; k < 2; ++k) dst[m][k] = *(const PG8_LAS bf16x8*)(lds + PG8_SA(b, h) + aoff + m * 2048 + k * 1024); } while (0)
; #define PG8_LDB(dst, b, h) do { _Pragma("unroll") for (int n = 0; n < 2; ++n) _Pragma("unroll") for (int k = 0; k < 2; ++k) dst[n][k] = *(const PG8_LAS bf16x8*)(lds + PG8_SB(b, h) + boff + n * 2048 + k * 1024); } while (0)
; #define PG8_MMA(ai, bj, At, Bt) do { __builtin_amdgcn_s_setprio(1); _Pragma("unroll") for (int m = 0; m < 4; ++m) _Pragma("unroll") for (int n = 0; n < 2; ++n) _Pragma("unroll") for (int k = 0; k < 2; ++k) \
;         acc[ai][bj][m][n] = __builtin_amdgcn_mfma_f32_16x16x32_bf16(Bt[n][k], At[m][k], acc[ai][bj][m][n], 0, 0, 0); __builtin_amdgcn_s_setprio(0); } while (0)
; #define PG8_WAIT_V(n) asm volatile("s_waitcnt vmcnt(" #n ")" ::: "memory")
; #define PG8_WAIT_L(n) asm volatile("s_waitcnt lgkmcnt(" #n ")" ::: "memory")
; #define PG8_BAR __builtin_amdgcn_s_barrier()
; #define PG8_SCHED __builtin_amdgcn_sched_barrier(0)
; template <class Epi, class Sched, bool ALIGN_EPI = false, bool SP2 = false>
; __device__ __forceinline__ void gemm_phase(PG8_LAS unsigned char* lds, const Gemm g, const Sched& S, const Epi& E) {
;     ...
;             PG8_LDB(B0, 1, 0); PG8_LDB(B1, 1, 1); PG8_SCHED; PG8_LDA(At, 1, 0); PG8_STAGE(PG8_SA(0, 1), a2 + hstep, voffA);
;             PG8_WAIT_V(8); PG8_WAIT_L(0); PG8_BAR; PG8_MMA(0, 0, At, B0); PG8_MMA(0, 1, At, B1); PG8_BAR; PG8_SCHED;
;             PG8_LDA(At, 1, 1); PG8_STAGE(PG8_SB(1, 0), b3, voffB); PG8_STAGE(PG8_SB(1, 1), b3 + hstep, voffB); PG8_STAGE(PG8_SA(1, 0), a3, voffA);
;             PG8_WAIT_V(8); PG8_WAIT_L(0); PG8_BAR; PG8_MMA(1, 0, At, B0); PG8_MMA(1, 1, At, B1); PG8_BAR; PG8_SCHED;
	s_setprio 0
	s_add_i32 s55, 0, 0x18000
	v_add_u32_e32 v151, s55, v145
	s_add_i32 s56, 0, 0x1c000
	ds_read_b128 v[152:155], v151
	ds_read_b128 v[156:159], v151 offset:1024
	ds_read_b128 v[160:163], v151 offset:2048
	ds_read_b128 v[164:167], v151 offset:3072
	v_add_u32_e32 v151, s56, v145
	ds_read_b128 v[168:171], v151
	ds_read_b128 v[172:175], v151 offset:1024
	ds_read_b128 v[176:179], v151 offset:2048
	ds_read_b128 v[180:183], v151 offset:3072
	s_add_u32 s28, s28, 0x40000
	s_addc_u32 s29, s29, 0
	s_mov_b32 m0, s40
	v_lshl_add_u64 v[224:225], s[28:29], 0, v[134:135]
	ds_read_b128 v[184:187], v150 offset:32768
	ds_read_b128 v[188:191], v150 offset:33792
	ds_read_b128 v[192:195], v150 offset:34816
	ds_read_b128 v[196:199], v150 offset:35840
	ds_read_b128 v[200:203], v150 offset:36864
	ds_read_b128 v[204:207], v150 offset:37888
	ds_read_b128 v[208:211], v150 offset:38912
	ds_read_b128 v[212:215], v150 offset:39936
	global_load_lds_dwordx4 v[224:225], off
	v_lshl_add_u64 v[224:225], s[28:29], 0, v[130:131]
	s_mov_b32 m0, s41
	s_nop 0
	global_load_lds_dwordx4 v[224:225], off
	s_waitcnt vmcnt(8)
	s_waitcnt lgkmcnt(0)
	s_setprio 1
	s_barrier
	v_mfma_f32_16x16x32_bf16 v[124:127], v[152:155], v[184:187], v[124:127]
	v_mfma_f32_16x16x32_bf16 v[120:123], v[160:163], v[184:187], v[120:123]
	v_mfma_f32_16x16x32_bf16 v[108:111], v[152:155], v[192:195], v[108:111]
	v_mfma_f32_16x16x32_bf16 v[104:107], v[160:163], v[192:195], v[104:107]
	v_mfma_f32_16x16x32_bf16 v[92:95], v[152:155], v[200:203], v[92:95]
	v_mfma_f32_16x16x32_bf16 v[88:91], v[160:163], v[200:203], v[88:91]
	v_mfma_f32_16x16x32_bf16 v[76:79], v[152:155], v[208:211], v[76:79]
	v_mfma_f32_16x16x32_bf16 v[72:75], v[160:163], v[208:211], v[72:75]
	v_mfma_f32_16x16x32_bf16 v[124:127], v[156:159], v[188:191], v[124:127]
	v_mfma_f32_16x16x32_bf16 v[120:123], v[164:167], v[188:191], v[120:123]
	v_mfma_f32_16x16x32_bf16 v[108:111], v[156:159], v[196:199], v[108:111]
	v_mfma_f32_16x16x32_bf16 v[104:107], v[164:167], v[196:199], v[104:107]
	v_mfma_f32_16x16x32_bf16 v[92:95], v[156:159], v[204:207], v[92:95]
	v_mfma_f32_16x16x32_bf16 v[88:91], v[164:167], v[204:207], v[88:91]
	v_mfma_f32_16x16x32_bf16 v[76:79], v[156:159], v[212:215], v[76:79]
	v_mfma_f32_16x16x32_bf16 v[72:75], v[164:167], v[212:215], v[72:75]
	v_mfma_f32_16x16x32_bf16 v[116:119], v[168:171], v[184:187], v[116:119]
	v_mfma_f32_16x16x32_bf16 v[112:115], v[176:179], v[184:187], v[112:115]
	v_mfma_f32_16x16x32_bf16 v[100:103], v[168:171], v[192:195], v[100:103]
	v_mfma_f32_16x16x32_bf16 v[96:99], v[176:179], v[192:195], v[96:99]
	v_mfma_f32_16x16x32_bf16 v[84:87], v[168:171], v[200:203], v[84:87]
	v_mfma_f32_16x16x32_bf16 v[80:83], v[176:179], v[200:203], v[80:83]
	v_mfma_f32_16x16x32_bf16 v[68:71], v[168:171], v[208:211], v[68:71]
	v_mfma_f32_16x16x32_bf16 v[64:67], v[176:179], v[208:211], v[64:67]
	v_mfma_f32_16x16x32_bf16 v[116:119], v[172:175], v[188:191], v[116:119]
	v_mfma_f32_16x16x32_bf16 v[112:115], v[180:183], v[188:191], v[112:115]
	v_mfma_f32_16x16x32_bf16 v[100:103], v[172:175], v[196:199], v[100:103]
	v_mfma_f32_16x16x32_bf16 v[96:99], v[180:183], v[196:199], v[96:99]
	v_mfma_f32_16x16x32_bf16 v[84:87], v[172:175], v[204:207], v[84:87]
	v_mfma_f32_16x16x32_bf16 v[80:83], v[180:183], v[204:207], v[80:83]
	v_mfma_f32_16x16x32_bf16 v[68:71], v[172:175], v[212:215], v[68:71]
	v_mfma_f32_16x16x32_bf16 v[64:67], v[180:183], v[212:215], v[64:67]
	s_barrier
	s_setprio 0
	s_add_i32 s28, s55, s33
	v_lshl_add_u64 v[216:217], v[216:217], 0, s[8:9]
	s_mov_b32 m0, s28
	ds_read_b128 v[184:187], v150 offset:49152
	ds_read_b128 v[188:191], v150 offset:50176
	ds_read_b128 v[192:195], v150 offset:51200
	ds_read_b128 v[196:199], v150 offset:52224
	ds_read_b128 v[200:203], v150 offset:53248
	ds_read_b128 v[204:207], v150 offset:54272
	ds_read_b128 v[208:211], v150 offset:55296
	ds_read_b128 v[212:215], v150 offset:56320
	global_load_lds_dwordx4 v[216:217], off
	s_add_i32 m0, s28, 0x2000
	s_add_u32 s26, s26, 0x40080
	v_lshl_add_u64 v[216:217], v[218:219], 0, s[8:9]
	s_addc_u32 s27, s27, 0
	s_add_i32 s28, s56, s33
	global_load_lds_dwordx4 v[216:217], off
	v_lshl_add_u64 v[216:217], s[26:27], 0, v[132:133]
	s_mov_b32 m0, s28
	s_nop 0
	global_load_lds_dwordx4 v[216:217], off
	v_lshl_add_u64 v[216:217], s[26:27], 0, v[128:129]
	s_add_i32 m0, s28, 0x2000
	s_nop 0
	global_load_lds_dwordx4 v[216:217], off
	v_lshl_add_u64 v[216:217], v[220:221], 0, s[8:9]
	s_mov_b32 m0, s42
	s_nop 0
	global_load_lds_dwordx4 v[216:217], off
	v_lshl_add_u64 v[216:217], v[222:223], 0, s[8:9]
	s_mov_b32 m0, s43
	s_nop 0
	global_load_lds_dwordx4 v[216:217], off
	s_waitcnt vmcnt(8)
	s_waitcnt lgkmcnt(0)
	s_setprio 1
	s_barrier
	v_mfma_f32_16x16x32_bf16 v[60:63], v[152:155], v[184:187], v[60:63]
	v_mfma_f32_16x16x32_bf16 v[56:59], v[160:163], v[184:187], v[56:59]
	v_mfma_f32_16x16x32_bf16 v[44:47], v[152:155], v[192:195], v[44:47]
	v_mfma_f32_16x16x32_bf16 v[40:43], v[160:163], v[192:195], v[40:43]
	v_mfma_f32_16x16x32_bf16 v[28:31], v[152:155], v[200:203], v[28:31]
	v_mfma_f32_16x16x32_bf16 v[24:27], v[160:163], v[200:203], v[24:27]
	v_mfma_f32_16x16x32_bf16 v[12:15], v[152:155], v[208:211], v[12:15]
	v_mfma_f32_16x16x32_bf16 v[8:11], v[160:163], v[208:211], v[8:11]
	v_mfma_f32_16x16x32_bf16 v[60:63], v[156:159], v[188:191], v[60:63]
	v_mfma_f32_16x16x32_bf16 v[56:59], v[164:167], v[188:191], v[56:59]
	v_mfma_f32_16x16x32_bf16 v[44:47], v[156:159], v[196:199], v[44:47]
	v_mfma_f32_16x16x32_bf16 v[40:43], v[164:167], v[196:199], v[40:43]
	v_mfma_f32_16x16x32_bf16 v[28:31], v[156:159], v[204:207], v[28:31]
	v_mfma_f32_16x16x32_bf16 v[24:27], v[164:167], v[204:207], v[24:27]
	v_mfma_f32_16x16x32_bf16 v[12:15], v[156:159], v[212:215], v[12:15]
	v_mfma_f32_16x16x32_bf16 v[8:11], v[164:167], v[212:215], v[8:11]
	v_mfma_f32_16x16x32_bf16 v[52:55], v[168:171], v[184:187], v[52:55]
	v_mfma_f32_16x16x32_bf16 v[48:51], v[176:179], v[184:187], v[48:51]
	v_mfma_f32_16x16x32_bf16 v[36:39], v[168:171], v[192:195], v[36:39]
	v_mfma_f32_16x16x32_bf16 v[32:35], v[176:179], v[192:195], v[32:35]
	v_mfma_f32_16x16x32_bf16 v[20:23], v[168:171], v[200:203], v[20:23]
	v_mfma_f32_16x16x32_bf16 v[16:19], v[176:179], v[200:203], v[16:19]
	v_mfma_f32_16x16x32_bf16 v[4:7], v[168:171], v[208:211], v[4:7]
	v_mfma_f32_16x16x32_bf16 v[0:3], v[176:179], v[208:211], v[0:3]
	v_mfma_f32_16x16x32_bf16 v[52:55], v[172:175], v[188:191], v[52:55]
	v_mfma_f32_16x16x32_bf16 v[48:51], v[180:183], v[188:191], v[48:51]
	v_mfma_f32_16x16x32_bf16 v[36:39], v[172:175], v[196:199], v[36:39]
	v_mfma_f32_16x16x32_bf16 v[32:35], v[180:183], v[196:199], v[32:35]
	v_mfma_f32_16x16x32_bf16 v[20:23], v[172:175], v[204:207], v[20:23]
	v_mfma_f32_16x16x32_bf16 v[16:19], v[180:183], v[204:207], v[16:19]
	v_mfma_f32_16x16x32_bf16 v[4:7], v[172:175], v[212:215], v[4:7]
	v_mfma_f32_16x16x32_bf16 v[0:3], v[180:183], v[212:215], v[0:3]
	s_barrier
	s_setprio 0
	s_add_i32 s54, s54, 2
	s_add_u32 s24, s24, 0x100
	s_addc_u32 s25, s25, 0
	s_add_u32 s52, s52, 0x100
	s_addc_u32 s53, s53, 0
	s_cmp_gt_u32 s54, 13

; #define PG8_STAGE(bufoff, gbase, voff) do { _Pragma("unroll") for (int _i = 0; _i < 2; ++_i) \
;         __builtin_amdgcn_global_load_lds((const unsigned*)((const char*)(gbase) + (voff)[_i]), (PG8_LAS unsigned*)(lds + (bufoff) + ldsw + _i * 8192), 16, 0, 0); } while (0)
; #define PG8_LDA(dst, b, h) do { _Pragma("unroll") for (int m = 0; m < 4; ++m) _Pragma("unroll") for (int k = 0; k < 2; ++k) dst[m][k] = *(const PG8_LAS bf16x8*)(lds + PG8_SA(b, h) + aoff + m * 2048 + k * 1024); } while (0)
; #define PG8_LDB(dst, b, h) do { _Pragma("unroll") for (int n = 0; n < 2; ++n) _Pragma("unroll") for (int k = 0; k < 2; ++k) dst[n][k] = *(const PG8_LAS bf16x8*)(lds + PG8_SB(b, h) + boff + n * 2048 + k * 1024); } while (0)
; #define PG8_WAIT_V(n) asm volatile("s_waitcnt vmcnt(" #n ")" ::: "memory")
; #define PG8_WAIT_L(n) asm volatile("s_waitcnt lgkmcnt(" #n ")" ::: "memory")
; #define PG8_BAR __builtin_amdgcn_s_barrier()
; #define PG8_SCHED __builtin_amdgcn_sched_barrier(0)
; template <class Epi, class Sched, bool ALIGN_EPI = false, bool SP2 = false>
; __device__ __forceinline__ void gemm_phase(PG8_LAS unsigned char* lds, const Gemm g, const Sched& S, const Epi& E) {
;     ...
;         const char* nA = has_next ? (const char*)g.A + (size_t)nxt.pm * tstep : cA; const char* nB = has_next ? (const char*)g.Bt + (size_t)nxt.pn * tstep : cB;
;         for (int t = 0; t < nt; t += 2) {
;             const bool last = (t == nt - 2);
;             const char* a1 = cA + (size_t)(t + 1) * kstep;
;             const char* a2 = last ? nA : cA + (size_t)(t + 2) * kstep; const char* b2 = last ? nB : cB + (size_t)(t + 2) * kstep;
;             const char* a3 = a2 + kstep; const char* b3 = b2 + kstep;
;             if (last && has_next) S.a_ready(nxt, ui + 1);
;             if constexpr (SP2) {
;             PG8_LDB(B0, 0, 0); PG8_LDB(B1, 0, 1); PG8_SCHED; PG8_LDA(At, 0, 0); PG8_STAGE(PG8_SA(1, 1), a1 + hstep, voffA);
;             PG8_WAIT_V(8); PG8_WAIT_L(0); PG8_BAR; PG8_MMA(0, 0, At, B0); PG8_MMA(0, 1, At, B1); PG8_BAR; PG8_SCHED;
;             PG8_LDA(At, 0, 1); PG8_STAGE(PG8_SB(0, 0), b2, voffB); PG8_STAGE(PG8_SB(0, 1), b2 + hstep, voffB); PG8_STAGE(PG8_SA(0, 0), a2, voffA);
;             PG8_WAIT_V(8); PG8_WAIT_L(0); PG8_BAR; PG8_MMA(1, 0, At, B0); PG8_MMA(1, 1, At, B1); PG8_BAR; PG8_SCHED;
.LBB0_1129:
	s_add_u32 s24, s24, 0xb0080
	s_addc_u32 s25, s25, 0
	s_add_u32 s51, s26, 0x100
	s_addc_u32 s52, s27, 0
	s_mov_b32 s53, -2
	s_add_u32 s26, s24, 0xfff50080
	s_addc_u32 s27, s25, -1
	s_cmp_eq_u32 s53, 40
	s_cselect_b32 s29, s7, s27
	s_cselect_b32 s28, s6, s26
	s_cselect_b32 s27, s23, s52
	s_cselect_b32 s26, s22, s51
	v_lshl_add_u64 v[204:205], s[24:25], 0, v[200:201]
	s_add_i32 m0, s35, 0xc000
	global_load_lds_dwordx4 v[204:205], off
	v_lshl_add_u64 v[204:205], s[24:25], 0, v[202:203]
	s_add_i32 m0, s35, 0xe000
	s_nop 0
	global_load_lds_dwordx4 v[204:205], off
	s_waitcnt vmcnt(8)
	s_waitcnt lgkmcnt(0)
	s_setprio 1
	s_barrier
	v_mfma_f32_16x16x32_bf16 v[132:135], v[120:123], v[160:163], 0
	v_mfma_f32_16x16x32_bf16 v[124:127], v[136:139], v[160:163], 0
	v_mfma_f32_16x16x32_bf16 v[108:111], v[120:123], v[168:171], 0
	v_mfma_f32_16x16x32_bf16 v[104:107], v[136:139], v[168:171], 0
	v_mfma_f32_16x16x32_bf16 v[92:95], v[120:123], v[176:179], 0
	v_mfma_f32_16x16x32_bf16 v[88:91], v[136:139], v[176:179], 0
	v_mfma_f32_16x16x32_bf16 v[76:79], v[120:123], v[184:187], 0
	v_mfma_f32_16x16x32_bf16 v[72:75], v[136:139], v[184:187], 0
	v_mfma_f32_16x16x32_bf16 v[132:135], v[128:131], v[164:167], v[132:135]
	v_mfma_f32_16x16x32_bf16 v[124:127], v[140:143], v[164:167], v[124:127]
	v_mfma_f32_16x16x32_bf16 v[108:111], v[128:131], v[172:175], v[108:111]
	v_mfma_f32_16x16x32_bf16 v[104:107], v[140:143], v[172:175], v[104:107]
	v_mfma_f32_16x16x32_bf16 v[92:95], v[128:131], v[180:183], v[92:95]
	v_mfma_f32_16x16x32_bf16 v[88:91], v[140:143], v[180:183], v[88:91]
	v_mfma_f32_16x16x32_bf16 v[76:79], v[128:131], v[188:191], v[76:79]
	v_mfma_f32_16x16x32_bf16 v[72:75], v[140:143], v[188:191], v[72:75]
	v_mfma_f32_16x16x32_bf16 v[116:119], v[144:147], v[160:163], 0
	v_mfma_f32_16x16x32_bf16 v[112:115], v[152:155], v[160:163], 0
	v_mfma_f32_16x16x32_bf16 v[100:103], v[144:147], v[168:171], 0
	v_mfma_f32_16x16x32_bf16 v[96:99], v[152:155], v[168:171], 0
	v_mfma_f32_16x16x32_bf16 v[84:87], v[144:147], v[176:179], 0
	v_mfma_f32_16x16x32_bf16 v[80:83], v[152:155], v[176:179], 0
	v_mfma_f32_16x16x32_bf16 v[68:71], v[144:147], v[184:187], 0
	v_mfma_f32_16x16x32_bf16 v[64:67], v[152:155], v[184:187], 0
	v_mfma_f32_16x16x32_bf16 v[116:119], v[148:151], v[164:167], v[116:119]
	v_mfma_f32_16x16x32_bf16 v[112:115], v[156:159], v[164:167], v[112:115]
	v_mfma_f32_16x16x32_bf16 v[100:103], v[148:151], v[172:175], v[100:103]
	v_mfma_f32_16x16x32_bf16 v[96:99], v[156:159], v[172:175], v[96:99]
	v_mfma_f32_16x16x32_bf16 v[84:87], v[148:151], v[180:183], v[84:87]
	v_mfma_f32_16x16x32_bf16 v[80:83], v[156:159], v[180:183], v[80:83]
	v_mfma_f32_16x16x32_bf16 v[68:71], v[148:151], v[188:191], v[68:71]
	v_mfma_f32_16x16x32_bf16 v[64:67], v[156:159], v[188:191], v[64:67]
	s_barrier
	s_setprio 0
	s_add_i32 s54, s45, s34
	v_lshl_add_u64 v[204:205], s[26:27], 0, v[194:195]
	s_mov_b32 m0, s54
	ds_read_b128 v[160:163], v247 offset:16384
	ds_read_b128 v[164:167], v247 offset:17408
	ds_read_b128 v[168:171], v247 offset:18432
	ds_read_b128 v[172:175], v247 offset:19456
	ds_read_b128 v[176:179], v247 offset:20480
	ds_read_b128 v[180:183], v247 offset:21504
	ds_read_b128 v[184:187], v247 offset:22528
	ds_read_b128 v[188:191], v247 offset:23552
	global_load_lds_dwordx4 v[204:205], off
	s_add_i32 m0, s54, 0x2000
	s_add_u32 s54, s26, 0xb0000
	v_lshl_add_u64 v[206:207], s[26:27], 0, v[198:199]
	s_addc_u32 s55, s27, 0
	s_add_i32 s56, s46, s34
	global_load_lds_dwordx4 v[206:207], off
	v_lshl_add_u64 v[208:209], s[54:55], 0, v[194:195]
	s_mov_b32 m0, s56
	v_lshl_add_u64 v[210:211], s[28:29], 0, v[196:197]
	global_load_lds_dwordx4 v[208:209], off
	v_lshl_add_u64 v[208:209], s[54:55], 0, v[198:199]
	s_add_i32 m0, s56, 0x2000
	s_nop 0
	global_load_lds_dwordx4 v[208:209], off
	v_lshl_add_u64 v[208:209], s[28:29], 0, v[192:193]
	s_mov_b32 m0, s35
	s_nop 0
	global_load_lds_dwordx4 v[208:209], off
	s_mov_b32 m0, s36
	s_nop 0
	global_load_lds_dwordx4 v[210:211], off
	s_waitcnt vmcnt(8)
	s_waitcnt lgkmcnt(0)
	s_setprio 1
	s_barrier
	v_mfma_f32_16x16x32_bf16 v[60:63], v[120:123], v[160:163], 0
	v_mfma_f32_16x16x32_bf16 v[56:59], v[136:139], v[160:163], 0
	v_mfma_f32_16x16x32_bf16 v[44:47], v[120:123], v[168:171], 0
	v_mfma_f32_16x16x32_bf16 v[40:43], v[136:139], v[168:171], 0
	v_mfma_f32_16x16x32_bf16 v[28:31], v[120:123], v[176:179], 0
	v_mfma_f32_16x16x32_bf16 v[24:27], v[136:139], v[176:179], 0
	v_mfma_f32_16x16x32_bf16 v[12:15], v[120:123], v[184:187], 0
	v_mfma_f32_16x16x32_bf16 v[8:11], v[136:139], v[184:187], 0
	v_mfma_f32_16x16x32_bf16 v[60:63], v[128:131], v[164:167], v[60:63]
	v_mfma_f32_16x16x32_bf16 v[56:59], v[140:143], v[164:167], v[56:59]
	v_mfma_f32_16x16x32_bf16 v[44:47], v[128:131], v[172:175], v[44:47]
	v_mfma_f32_16x16x32_bf16 v[40:43], v[140:143], v[172:175], v[40:43]
	v_mfma_f32_16x16x32_bf16 v[28:31], v[128:131], v[180:183], v[28:31]
	v_mfma_f32_16x16x32_bf16 v[24:27], v[140:143], v[180:183], v[24:27]
	v_mfma_f32_16x16x32_bf16 v[12:15], v[128:131], v[188:191], v[12:15]
	v_mfma_f32_16x16x32_bf16 v[8:11], v[140:143], v[188:191], v[8:11]
	v_mfma_f32_16x16x32_bf16 v[52:55], v[144:147], v[160:163], 0
	v_mfma_f32_16x16x32_bf16 v[48:51], v[152:155], v[160:163], 0
	v_mfma_f32_16x16x32_bf16 v[36:39], v[144:147], v[168:171], 0
	v_mfma_f32_16x16x32_bf16 v[32:35], v[152:155], v[168:171], 0
	v_mfma_f32_16x16x32_bf16 v[20:23], v[144:147], v[176:179], 0
	v_mfma_f32_16x16x32_bf16 v[16:19], v[152:155], v[176:179], 0
	v_mfma_f32_16x16x32_bf16 v[4:7], v[144:147], v[184:187], 0
	v_mfma_f32_16x16x32_bf16 v[0:3], v[152:155], v[184:187], 0
	v_mfma_f32_16x16x32_bf16 v[52:55], v[148:151], v[164:167], v[52:55]
	v_mfma_f32_16x16x32_bf16 v[48:51], v[156:159], v[164:167], v[48:51]
	v_mfma_f32_16x16x32_bf16 v[36:39], v[148:151], v[172:175], v[36:39]
	v_mfma_f32_16x16x32_bf16 v[32:35], v[156:159], v[172:175], v[32:35]
	v_mfma_f32_16x16x32_bf16 v[20:23], v[148:151], v[180:183], v[20:23]
	v_mfma_f32_16x16x32_bf16 v[16:19], v[156:159], v[180:183], v[16:19]
	v_mfma_f32_16x16x32_bf16 v[4:7], v[148:151], v[188:191], v[4:7]
	v_mfma_f32_16x16x32_bf16 v[0:3], v[156:159], v[188:191], v[0:3]
	s_barrier
; #define PG8_STAGE(bufoff, gbase, voff) do { _Pragma("unroll") for (int _i = 0; _i < 2; ++_i) \
;         __builtin_amdgcn_global_load_lds((const unsigned*)((const char*)(gbase) + (voff)[_i]), (PG8_LAS unsigned*)(lds + (bufoff) + ldsw + _i * 8192), 16, 0, 0); } while (0)
; #define PG8_LDA(dst, b, h) do { _Pragma("unroll") for (int m = 0; m < 4; ++m) _Pragma("unroll") for (int k = 0; k < 2; ++k) dst[m][k] = *(const PG8_LAS bf16x8*)(lds + PG8_SA(b, h) + aoff + m * 2048 + k * 1024); } while (0)
; #define PG8_LDB(dst, b, h) do { _Pragma("unroll") for (int n = 0; n < 2; ++n) _Pragma("unroll") for (int k = 0; k < 2; ++k) dst[n][k] = *(const PG8_LAS bf16x8*)(lds + PG8_SB(b, h) + boff + n * 2048 + k * 1024); } while (0)
; #define PG8_MMA(ai, bj, At, Bt) do { __builtin_amdgcn_s_setprio(1); _Pragma("unroll") for (int m = 0; m < 4; ++m) _Pragma("unroll") for (int n = 0; n < 2; ++n) _Pragma("unroll") for (int k = 0; k < 2; ++k) \
;         acc[ai][bj][m][n] = __builtin_amdgcn_mfma_f32_16x16x32_bf16(Bt[n][k], At[m][k], acc[ai][bj][m][n], 0, 0, 0); __builtin_amdgcn_s_setprio(0); } while (0)
; #define PG8_WAIT_V(n) asm volatile("s_waitcnt vmcnt(" #n ")" ::: "memory")
; #define PG8_WAIT_L(n) asm volatile("s_waitcnt lgkmcnt(" #n ")" ::: "memory")
; #define PG8_BAR __builtin_amdgcn_s_barrier()
; #define PG8_SCHED __builtin_amdgcn_sched_barrier(0)
; template <class Epi, class Sched, bool ALIGN_EPI = false, bool SP2 = false>
; __device__ __forceinline__ void gemm_phase(PG8_LAS unsigned char* lds, const Gemm g, const Sched& S, const Epi& E) {
;     ...
;             PG8_LDB(B0, 1, 0); PG8_LDB(B1, 1, 1); PG8_SCHED; PG8_LDA(At, 1, 0); PG8_STAGE(PG8_SA(0, 1), a2 + hstep, voffA);
;             PG8_WAIT_V(8); PG8_WAIT_L(0); PG8_BAR; PG8_MMA(0, 0, At, B0); PG8_MMA(0, 1, At, B1); PG8_BAR; PG8_SCHED;
;             PG8_LDA(At, 1, 1); PG8_STAGE(PG8_SB(1, 0), b3, voffB); PG8_STAGE(PG8_SB(1, 1), b3 + hstep, voffB); PG8_STAGE(PG8_SA(1, 0), a3, voffA);
;             PG8_WAIT_V(8); PG8_WAIT_L(0); PG8_BAR; PG8_MMA(1, 0, At, B0); PG8_MMA(1, 1, At, B1); PG8_BAR; PG8_SCHED;
	s_setprio 0
	s_add_i32 s54, 0, 0x18000
	s_add_i32 s55, 0, 0x1c000
	v_add_u32_e32 v140, s54, v243
	v_add_u32_e32 v156, s55, v243
	ds_read_b128 v[120:123], v140
	ds_read_b128 v[128:131], v140 offset:1024
	ds_read_b128 v[136:139], v140 offset:2048
	ds_read_b128 v[140:143], v140 offset:3072
	ds_read_b128 v[144:147], v156
	ds_read_b128 v[148:151], v156 offset:1024
	ds_read_b128 v[152:155], v156 offset:2048
	ds_read_b128 v[156:159], v156 offset:3072
	s_add_u32 s28, s28, 0xb0000
	s_addc_u32 s29, s29, 0
	s_mov_b32 m0, s37
	v_lshl_add_u64 v[212:213], s[28:29], 0, v[192:193]
	ds_read_b128 v[160:163], v247 offset:32768
	ds_read_b128 v[164:167], v247 offset:33792
	ds_read_b128 v[168:171], v247 offset:34816
	ds_read_b128 v[172:175], v247 offset:35840
	ds_read_b128 v[176:179], v247 offset:36864
	ds_read_b128 v[180:183], v247 offset:37888
	ds_read_b128 v[184:187], v247 offset:38912
	ds_read_b128 v[188:191], v247 offset:39936
	global_load_lds_dwordx4 v[212:213], off
	v_lshl_add_u64 v[212:213], s[28:29], 0, v[196:197]
	s_mov_b32 m0, s38
	s_nop 0
	global_load_lds_dwordx4 v[212:213], off
	s_waitcnt vmcnt(8)
	s_waitcnt lgkmcnt(0)
	s_setprio 1
	s_barrier
	v_mfma_f32_16x16x32_bf16 v[132:135], v[120:123], v[160:163], v[132:135]
	v_mfma_f32_16x16x32_bf16 v[124:127], v[136:139], v[160:163], v[124:127]
	v_mfma_f32_16x16x32_bf16 v[108:111], v[120:123], v[168:171], v[108:111]
	v_mfma_f32_16x16x32_bf16 v[104:107], v[136:139], v[168:171], v[104:107]
	v_mfma_f32_16x16x32_bf16 v[92:95], v[120:123], v[176:179], v[92:95]
	v_mfma_f32_16x16x32_bf16 v[88:91], v[136:139], v[176:179], v[88:91]
	v_mfma_f32_16x16x32_bf16 v[76:79], v[120:123], v[184:187], v[76:79]
	v_mfma_f32_16x16x32_bf16 v[72:75], v[136:139], v[184:187], v[72:75]
	v_mfma_f32_16x16x32_bf16 v[132:135], v[128:131], v[164:167], v[132:135]
	v_mfma_f32_16x16x32_bf16 v[124:127], v[140:143], v[164:167], v[124:127]
	v_mfma_f32_16x16x32_bf16 v[108:111], v[128:131], v[172:175], v[108:111]
	v_mfma_f32_16x16x32_bf16 v[104:107], v[140:143], v[172:175], v[104:107]
	v_mfma_f32_16x16x32_bf16 v[92:95], v[128:131], v[180:183], v[92:95]
	v_mfma_f32_16x16x32_bf16 v[88:91], v[140:143], v[180:183], v[88:91]
	v_mfma_f32_16x16x32_bf16 v[76:79], v[128:131], v[188:191], v[76:79]
	v_mfma_f32_16x16x32_bf16 v[72:75], v[140:143], v[188:191], v[72:75]
	v_mfma_f32_16x16x32_bf16 v[116:119], v[144:147], v[160:163], v[116:119]
	v_mfma_f32_16x16x32_bf16 v[112:115], v[152:155], v[160:163], v[112:115]
	v_mfma_f32_16x16x32_bf16 v[100:103], v[144:147], v[168:171], v[100:103]
	v_mfma_f32_16x16x32_bf16 v[96:99], v[152:155], v[168:171], v[96:99]
	v_mfma_f32_16x16x32_bf16 v[84:87], v[144:147], v[176:179], v[84:87]
	v_mfma_f32_16x16x32_bf16 v[80:83], v[152:155], v[176:179], v[80:83]
	v_mfma_f32_16x16x32_bf16 v[68:71], v[144:147], v[184:187], v[68:71]
	v_mfma_f32_16x16x32_bf16 v[64:67], v[152:155], v[184:187], v[64:67]
	v_mfma_f32_16x16x32_bf16 v[116:119], v[148:151], v[164:167], v[116:119]
	v_mfma_f32_16x16x32_bf16 v[112:115], v[156:159], v[164:167], v[112:115]
	v_mfma_f32_16x16x32_bf16 v[100:103], v[148:151], v[172:175], v[100:103]
	v_mfma_f32_16x16x32_bf16 v[96:99], v[156:159], v[172:175], v[96:99]
	v_mfma_f32_16x16x32_bf16 v[84:87], v[148:151], v[180:183], v[84:87]
	v_mfma_f32_16x16x32_bf16 v[80:83], v[156:159], v[180:183], v[80:83]
	v_mfma_f32_16x16x32_bf16 v[68:71], v[148:151], v[188:191], v[68:71]
	v_mfma_f32_16x16x32_bf16 v[64:67], v[156:159], v[188:191], v[64:67]
	s_barrier
	s_setprio 0
	s_add_i32 s28, s54, s34
	v_lshl_add_u64 v[204:205], v[204:205], 0, s[18:19]
	s_mov_b32 m0, s28
	ds_read_b128 v[160:163], v247 offset:49152
	ds_read_b128 v[164:167], v247 offset:50176
	ds_read_b128 v[168:171], v247 offset:51200
	ds_read_b128 v[172:175], v247 offset:52224
	ds_read_b128 v[176:179], v247 offset:53248
	ds_read_b128 v[180:183], v247 offset:54272
	ds_read_b128 v[184:187], v247 offset:55296
	ds_read_b128 v[188:191], v247 offset:56320
	global_load_lds_dwordx4 v[204:205], off
	s_add_i32 m0, s28, 0x2000
	s_add_u32 s26, s26, 0xb0080
	v_lshl_add_u64 v[204:205], v[206:207], 0, s[18:19]
	s_addc_u32 s27, s27, 0
	s_add_i32 s28, s55, s34
	global_load_lds_dwordx4 v[204:205], off
	v_lshl_add_u64 v[204:205], s[26:27], 0, v[194:195]
	s_mov_b32 m0, s28
	s_nop 0
	global_load_lds_dwordx4 v[204:205], off
	v_lshl_add_u64 v[204:205], s[26:27], 0, v[198:199]
	s_add_i32 m0, s28, 0x2000
	s_nop 0
	global_load_lds_dwordx4 v[204:205], off
	v_lshl_add_u64 v[204:205], v[208:209], 0, s[18:19]
	s_mov_b32 m0, s40
	s_nop 0
	global_load_lds_dwordx4 v[204:205], off
	v_lshl_add_u64 v[204:205], v[210:211], 0, s[18:19]
	s_mov_b32 m0, s41
	s_nop 0
	global_load_lds_dwordx4 v[204:205], off
	s_waitcnt vmcnt(8)
	s_waitcnt lgkmcnt(0)
	s_setprio 1
	s_barrier
	v_mfma_f32_16x16x32_bf16 v[60:63], v[120:123], v[160:163], v[60:63]
	v_mfma_f32_16x16x32_bf16 v[56:59], v[136:139], v[160:163], v[56:59]
	v_mfma_f32_16x16x32_bf16 v[44:47], v[120:123], v[168:171], v[44:47]
	v_mfma_f32_16x16x32_bf16 v[40:43], v[136:139], v[168:171], v[40:43]
	v_mfma_f32_16x16x32_bf16 v[28:31], v[120:123], v[176:179], v[28:31]
	v_mfma_f32_16x16x32_bf16 v[24:27], v[136:139], v[176:179], v[24:27]
	v_mfma_f32_16x16x32_bf16 v[12:15], v[120:123], v[184:187], v[12:15]
	v_mfma_f32_16x16x32_bf16 v[8:11], v[136:139], v[184:187], v[8:11]
	v_mfma_f32_16x16x32_bf16 v[60:63], v[128:131], v[164:167], v[60:63]
	v_mfma_f32_16x16x32_bf16 v[56:59], v[140:143], v[164:167], v[56:59]
	v_mfma_f32_16x16x32_bf16 v[44:47], v[128:131], v[172:175], v[44:47]
	v_mfma_f32_16x16x32_bf16 v[40:43], v[140:143], v[172:175], v[40:43]
	v_mfma_f32_16x16x32_bf16 v[28:31], v[128:131], v[180:183], v[28:31]
	v_mfma_f32_16x16x32_bf16 v[24:27], v[140:143], v[180:183], v[24:27]
	v_mfma_f32_16x16x32_bf16 v[12:15], v[128:131], v[188:191], v[12:15]
	v_mfma_f32_16x16x32_bf16 v[8:11], v[140:143], v[188:191], v[8:11]
	v_mfma_f32_16x16x32_bf16 v[52:55], v[144:147], v[160:163], v[52:55]
	v_mfma_f32_16x16x32_bf16 v[48:51], v[152:155], v[160:163], v[48:51]
	v_mfma_f32_16x16x32_bf16 v[36:39], v[144:147], v[168:171], v[36:39]
	v_mfma_f32_16x16x32_bf16 v[32:35], v[152:155], v[168:171], v[32:35]
	v_mfma_f32_16x16x32_bf16 v[20:23], v[144:147], v[176:179], v[20:23]
	v_mfma_f32_16x16x32_bf16 v[16:19], v[152:155], v[176:179], v[16:19]
	v_mfma_f32_16x16x32_bf16 v[4:7], v[144:147], v[184:187], v[4:7]
	v_mfma_f32_16x16x32_bf16 v[0:3], v[152:155], v[184:187], v[0:3]
	v_mfma_f32_16x16x32_bf16 v[52:55], v[148:151], v[164:167], v[52:55]
	v_mfma_f32_16x16x32_bf16 v[48:51], v[156:159], v[164:167], v[48:51]
	v_mfma_f32_16x16x32_bf16 v[36:39], v[148:151], v[172:175], v[36:39]
	v_mfma_f32_16x16x32_bf16 v[32:35], v[156:159], v[172:175], v[32:35]
	v_mfma_f32_16x16x32_bf16 v[20:23], v[148:151], v[180:183], v[20:23]
	v_mfma_f32_16x16x32_bf16 v[16:19], v[156:159], v[180:183], v[16:19]
	v_mfma_f32_16x16x32_bf16 v[4:7], v[148:151], v[188:191], v[4:7]
	v_mfma_f32_16x16x32_bf16 v[0:3], v[156:159], v[188:191], v[0:3]
	s_barrier
	s_setprio 0
	s_add_i32 s53, s53, 2
	s_add_u32 s24, s24, 0x100
	s_addc_u32 s25, s25, 0
	s_add_u32 s51, s51, 0x100
	s_addc_u32 s52, s52, 0
	s_cmp_gt_u32 s53, 41

; #define PG8_STAGE(bufoff, gbase, voff) do { _Pragma("unroll") for (int _i = 0; _i < 2; ++_i) \
;         __builtin_amdgcn_global_load_lds((const unsigned*)((const char*)(gbase) + (voff)[_i]), (PG8_LAS unsigned*)(lds + (bufoff) + ldsw + _i * 8192), 16, 0, 0); } while (0)
; #define PG8_LDA(dst, b, h) do { _Pragma("unroll") for (int m = 0; m < 4; ++m) _Pragma("unroll") for (int k = 0; k < 2; ++k) dst[m][k] = *(const PG8_LAS bf16x8*)(lds + PG8_SA(b, h) + aoff + m * 2048 + k * 1024); } while (0)
; #define PG8_LDB(dst, b, h) do { _Pragma("unroll") for (int n = 0; n < 2; ++n) _Pragma("unroll") for (int k = 0; k < 2; ++k) dst[n][k] = *(const PG8_LAS bf16x8*)(lds + PG8_SB(b, h) + boff + n * 2048 + k * 1024); } while (0)
; #define PG8_WAIT_V(n) asm volatile("s_waitcnt vmcnt(" #n ")" ::: "memory")
; #define PG8_WAIT_L(n) asm volatile("s_waitcnt lgkmcnt(" #n ")" ::: "memory")
; #define PG8_BAR __builtin_amdgcn_s_barrier()
; #define PG8_SCHED __builtin_amdgcn_sched_barrier(0)
; template <class Epi, class Sched, bool ALIGN_EPI = false, bool SP2 = false>
; __device__ __forceinline__ void gemm_phase(PG8_LAS unsigned char* lds, const Gemm g, const Sched& S, const Epi& E) {
;     ...
;         const char* nA = has_next ? (const char*)g.A + (size_t)nxt.pm * tstep : cA; const char* nB = has_next ? (const char*)g.Bt + (size_t)nxt.pn * tstep : cB;
;         for (int t = 0; t < nt; t += 2) {
;             const bool last = (t == nt - 2);
;             const char* a1 = cA + (size_t)(t + 1) * kstep;
;             const char* a2 = last ? nA : cA + (size_t)(t + 2) * kstep; const char* b2 = last ? nB : cB + (size_t)(t + 2) * kstep;
;             const char* a3 = a2 + kstep; const char* b3 = b2 + kstep;
;             if (last && has_next) S.a_ready(nxt, ui + 1);
;             if constexpr (SP2) {
;             PG8_LDB(B0, 0, 0); PG8_LDB(B1, 0, 1); PG8_SCHED; PG8_LDA(At, 0, 0); PG8_STAGE(PG8_SA(1, 1), a1 + hstep, voffA);
;             PG8_WAIT_V(8); PG8_WAIT_L(0); PG8_BAR; PG8_MMA(0, 0, At, B0); PG8_MMA(0, 1, At, B1); PG8_BAR; PG8_SCHED;
;             PG8_LDA(At, 0, 1); PG8_STAGE(PG8_SB(0, 0), b2, voffB); PG8_STAGE(PG8_SB(0, 1), b2 + hstep, voffB); PG8_STAGE(PG8_SA(0, 0), a2, voffA);
;             PG8_WAIT_V(8); PG8_WAIT_L(0); PG8_BAR; PG8_MMA(1, 0, At, B0); PG8_MMA(1, 1, At, B1); PG8_BAR; PG8_SCHED;
.LBB0_1218:
	s_ashr_i32 s17, s16, 31
	s_lshl_b64 s[18:19], s[16:17], 19
	s_add_u32 s18, s36, s18
	s_addc_u32 s19, s37, s19
	s_and_b64 s[20:21], s[0:1], exec
	s_cselect_b32 s17, s19, s25
	s_cselect_b32 s50, s18, s24
	s_ashr_i32 s15, s14, 31
	s_lshl_b64 s[20:21], s[14:15], 19
	s_add_u32 s20, s34, s20
	s_addc_u32 s21, s35, s21
	s_and_b64 s[28:29], s[0:1], exec
	s_cselect_b32 s15, s21, s27
	s_cselect_b32 s51, s20, s26
	s_add_u32 s24, s24, 0x40080
	s_addc_u32 s25, s25, 0
	s_add_u32 s52, s26, 0x100
	s_addc_u32 s53, s27, 0
	s_mov_b32 s54, -2
	s_add_u32 s26, s24, 0xfffc0080
	s_addc_u32 s27, s25, -1
	s_cmp_eq_u32 s54, 12
	s_cselect_b32 s29, s17, s27
	s_cselect_b32 s28, s50, s26
	s_cselect_b32 s27, s15, s53
	s_cselect_b32 s26, s51, s52
	v_lshl_add_u64 v[216:217], s[24:25], 0, v[136:137]
	s_add_i32 m0, s23, 0xc000
	global_load_lds_dwordx4 v[216:217], off
	v_lshl_add_u64 v[216:217], s[24:25], 0, v[138:139]
	s_add_i32 m0, s23, 0xe000
	s_nop 0
	global_load_lds_dwordx4 v[216:217], off
	s_waitcnt vmcnt(8)
	s_waitcnt lgkmcnt(0)
	s_setprio 1
	s_barrier
	v_mfma_f32_16x16x32_bf16 v[124:127], v[152:155], v[184:187], 0
	v_mfma_f32_16x16x32_bf16 v[120:123], v[160:163], v[184:187], 0
	v_mfma_f32_16x16x32_bf16 v[108:111], v[152:155], v[192:195], 0
	v_mfma_f32_16x16x32_bf16 v[104:107], v[160:163], v[192:195], 0
	v_mfma_f32_16x16x32_bf16 v[92:95], v[152:155], v[200:203], 0
	v_mfma_f32_16x16x32_bf16 v[88:91], v[160:163], v[200:203], 0
	v_mfma_f32_16x16x32_bf16 v[76:79], v[152:155], v[208:211], 0
	v_mfma_f32_16x16x32_bf16 v[72:75], v[160:163], v[208:211], 0
	v_mfma_f32_16x16x32_bf16 v[124:127], v[156:159], v[188:191], v[124:127]
	v_mfma_f32_16x16x32_bf16 v[120:123], v[164:167], v[188:191], v[120:123]
	v_mfma_f32_16x16x32_bf16 v[108:111], v[156:159], v[196:199], v[108:111]
	v_mfma_f32_16x16x32_bf16 v[104:107], v[164:167], v[196:199], v[104:107]
	v_mfma_f32_16x16x32_bf16 v[92:95], v[156:159], v[204:207], v[92:95]
	v_mfma_f32_16x16x32_bf16 v[88:91], v[164:167], v[204:207], v[88:91]
	v_mfma_f32_16x16x32_bf16 v[76:79], v[156:159], v[212:215], v[76:79]
	v_mfma_f32_16x16x32_bf16 v[72:75], v[164:167], v[212:215], v[72:75]
	v_mfma_f32_16x16x32_bf16 v[116:119], v[168:171], v[184:187], 0
	v_mfma_f32_16x16x32_bf16 v[112:115], v[176:179], v[184:187], 0
	v_mfma_f32_16x16x32_bf16 v[100:103], v[168:171], v[192:195], 0
	v_mfma_f32_16x16x32_bf16 v[96:99], v[176:179], v[192:195], 0
	v_mfma_f32_16x16x32_bf16 v[84:87], v[168:171], v[200:203], 0
	v_mfma_f32_16x16x32_bf16 v[80:83], v[176:179], v[200:203], 0
	v_mfma_f32_16x16x32_bf16 v[68:71], v[168:171], v[208:211], 0
	v_mfma_f32_16x16x32_bf16 v[64:67], v[176:179], v[208:211], 0
	v_mfma_f32_16x16x32_bf16 v[116:119], v[172:175], v[188:191], v[116:119]
	v_mfma_f32_16x16x32_bf16 v[112:115], v[180:183], v[188:191], v[112:115]
	v_mfma_f32_16x16x32_bf16 v[100:103], v[172:175], v[196:199], v[100:103]
	v_mfma_f32_16x16x32_bf16 v[96:99], v[180:183], v[196:199], v[96:99]
	v_mfma_f32_16x16x32_bf16 v[84:87], v[172:175], v[204:207], v[84:87]
	v_mfma_f32_16x16x32_bf16 v[80:83], v[180:183], v[204:207], v[80:83]
	v_mfma_f32_16x16x32_bf16 v[68:71], v[172:175], v[212:215], v[68:71]
	v_mfma_f32_16x16x32_bf16 v[64:67], v[180:183], v[212:215], v[64:67]
	s_barrier
	s_setprio 0
	s_add_i32 s55, s44, s33
	v_lshl_add_u64 v[216:217], s[26:27], 0, v[132:133]
	s_mov_b32 m0, s55
	ds_read_b128 v[184:187], v150 offset:16384
	ds_read_b128 v[188:191], v150 offset:17408
	ds_read_b128 v[192:195], v150 offset:18432
	ds_read_b128 v[196:199], v150 offset:19456
	ds_read_b128 v[200:203], v150 offset:20480
	ds_read_b128 v[204:207], v150 offset:21504
	ds_read_b128 v[208:211], v150 offset:22528
	ds_read_b128 v[212:215], v150 offset:23552
	global_load_lds_dwordx4 v[216:217], off
	s_add_i32 m0, s55, 0x2000
	s_add_u32 s56, s26, 0x40000
	v_lshl_add_u64 v[218:219], s[26:27], 0, v[128:129]
	s_addc_u32 s57, s27, 0
	s_add_i32 s55, s45, s33
	global_load_lds_dwordx4 v[218:219], off
	v_lshl_add_u64 v[220:221], s[56:57], 0, v[132:133]
	s_mov_b32 m0, s55
	v_lshl_add_u64 v[222:223], s[28:29], 0, v[130:131]
	global_load_lds_dwordx4 v[220:221], off
	v_lshl_add_u64 v[220:221], s[56:57], 0, v[128:129]
	s_add_i32 m0, s55, 0x2000
	s_nop 0
	global_load_lds_dwordx4 v[220:221], off
	v_lshl_add_u64 v[220:221], s[28:29], 0, v[134:135]
	s_mov_b32 m0, s23
	s_nop 0
	global_load_lds_dwordx4 v[220:221], off
	s_mov_b32 m0, s39
	s_nop 0
	global_load_lds_dwordx4 v[222:223], off
	s_waitcnt vmcnt(8)
	s_waitcnt lgkmcnt(0)
	s_setprio 1
	s_barrier
	v_mfma_f32_16x16x32_bf16 v[60:63], v[152:155], v[184:187], 0
	v_mfma_f32_16x16x32_bf16 v[56:59], v[160:163], v[184:187], 0
	v_mfma_f32_16x16x32_bf16 v[44:47], v[152:155], v[192:195], 0
	v_mfma_f32_16x16x32_bf16 v[40:43], v[160:163], v[192:195], 0
	v_mfma_f32_16x16x32_bf16 v[28:31], v[152:155], v[200:203], 0
	v_mfma_f32_16x16x32_bf16 v[24:27], v[160:163], v[200:203], 0
	v_mfma_f32_16x16x32_bf16 v[12:15], v[152:155], v[208:211], 0
	v_mfma_f32_16x16x32_bf16 v[8:11], v[160:163], v[208:211], 0
	v_mfma_f32_16x16x32_bf16 v[60:63], v[156:159], v[188:191], v[60:63]
	v_mfma_f32_16x16x32_bf16 v[56:59], v[164:167], v[188:191], v[56:59]
	v_mfma_f32_16x16x32_bf16 v[44:47], v[156:159], v[196:199], v[44:47]
	v_mfma_f32_16x16x32_bf16 v[40:43], v[164:167], v[196:199], v[40:43]
	v_mfma_f32_16x16x32_bf16 v[28:31], v[156:159], v[204:207], v[28:31]
	v_mfma_f32_16x16x32_bf16 v[24:27], v[164:167], v[204:207], v[24:27]
	v_mfma_f32_16x16x32_bf16 v[12:15], v[156:159], v[212:215], v[12:15]
	v_mfma_f32_16x16x32_bf16 v[8:11], v[164:167], v[212:215], v[8:11]
	v_mfma_f32_16x16x32_bf16 v[52:55], v[168:171], v[184:187], 0
	v_mfma_f32_16x16x32_bf16 v[48:51], v[176:179], v[184:187], 0
	v_mfma_f32_16x16x32_bf16 v[36:39], v[168:171], v[192:195], 0
	v_mfma_f32_16x16x32_bf16 v[32:35], v[176:179], v[192:195], 0
	v_mfma_f32_16x16x32_bf16 v[20:23], v[168:171], v[200:203], 0
	v_mfma_f32_16x16x32_bf16 v[16:19], v[176:179], v[200:203], 0
	v_mfma_f32_16x16x32_bf16 v[4:7], v[168:171], v[208:211], 0
	v_mfma_f32_16x16x32_bf16 v[0:3], v[176:179], v[208:211], 0
	v_mfma_f32_16x16x32_bf16 v[52:55], v[172:175], v[188:191], v[52:55]
	v_mfma_f32_16x16x32_bf16 v[48:51], v[180:183], v[188:191], v[48:51]
	v_mfma_f32_16x16x32_bf16 v[36:39], v[172:175], v[196:199], v[36:39]
	v_mfma_f32_16x16x32_bf16 v[32:35], v[180:183], v[196:199], v[32:35]
	v_mfma_f32_16x16x32_bf16 v[20:23], v[172:175], v[204:207], v[20:23]
	v_mfma_f32_16x16x32_bf16 v[16:19], v[180:183], v[204:207], v[16:19]
	v_mfma_f32_16x16x32_bf16 v[4:7], v[172:175], v[212:215], v[4:7]
	v_mfma_f32_16x16x32_bf16 v[0:3], v[180:183], v[212:215], v[0:3]
	s_barrier
; #define PG8_STAGE(bufoff, gbase, voff) do { _Pragma("unroll") for (int _i = 0; _i < 2; ++_i) \
;         __builtin_amdgcn_global_load_lds((const unsigned*)((const char*)(gbase) + (voff)[_i]), (PG8_LAS unsigned*)(lds + (bufoff) + ldsw + _i * 8192), 16, 0, 0); } while (0)
; #define PG8_LDA(dst, b, h) do { _Pragma("unroll") for (int m = 0; m < 4; ++m) _Pragma("unroll") for (int k = 0; k < 2; ++k) dst[m][k] = *(const PG8_LAS bf16x8*)(lds + PG8_SA(b, h) + aoff + m * 2048 + k * 1024); } while (0)
; #define PG8_LDB(dst, b, h) do { _Pragma("unroll") for (int n = 0; n < 2; ++n) _Pragma("unroll") for (int k = 0; k < 2; ++k) dst[n][k] = *(const PG8_LAS bf16x8*)(lds + PG8_SB(b, h) + boff + n * 2048 + k * 1024); } while (0)
; #define PG8_MMA(ai, bj, At, Bt) do { __builtin_amdgcn_s_setprio(1); _Pragma("unroll") for (int m = 0; m < 4; ++m) _Pragma("unroll") for (int n = 0; n < 2; ++n) _Pragma("unroll") for (int k = 0; k < 2; ++k) \
;         acc[ai][bj][m][n] = __builtin_amdgcn_mfma_f32_16x16x32_bf16(Bt[n][k], At[m][k], acc[ai][bj][m][n], 0, 0, 0); __builtin_amdgcn_s_setprio(0); } while (0)
; #define PG8_WAIT_V(n) asm volatile("s_waitcnt vmcnt(" #n ")" ::: "memory")
; #define PG8_WAIT_L(n) asm volatile("s_waitcnt lgkmcnt(" #n ")" ::: "memory")
; #define PG8_BAR __builtin_amdgcn_s_barrier()
; #define PG8_SCHED __builtin_amdgcn_sched_barrier(0)
; template <class Epi, class Sched, bool ALIGN_EPI = false, bool SP2 = false>
; __device__ __forceinline__ void gemm_phase(PG8_LAS unsigned char* lds, const Gemm g, const Sched& S, const Epi& E) {
;     ...
;             PG8_LDB(B0, 1, 0); PG8_LDB(B1, 1, 1); PG8_SCHED; PG8_LDA(At, 1, 0); PG8_STAGE(PG8_SA(0, 1), a2 + hstep, voffA);
;             PG8_WAIT_V(8); PG8_WAIT_L(0); PG8_BAR; PG8_MMA(0, 0, At, B0); PG8_MMA(0, 1, At, B1); PG8_BAR; PG8_SCHED;
;             PG8_LDA(At, 1, 1); PG8_STAGE(PG8_SB(1, 0), b3, voffB); PG8_STAGE(PG8_SB(1, 1), b3 + hstep, voffB); PG8_STAGE(PG8_SA(1, 0), a3, voffA);
;             PG8_WAIT_V(8); PG8_WAIT_L(0); PG8_BAR; PG8_MMA(1, 0, At, B0); PG8_MMA(1, 1, At, B1); PG8_BAR; PG8_SCHED;
	s_setprio 0
	s_add_i32 s55, 0, 0x18000
	v_add_u32_e32 v151, s55, v145
	s_add_i32 s56, 0, 0x1c000
	ds_read_b128 v[152:155], v151
	ds_read_b128 v[156:159], v151 offset:1024
	ds_read_b128 v[160:163], v151 offset:2048
	ds_read_b128 v[164:167], v151 offset:3072
	v_add_u32_e32 v151, s56, v145
	ds_read_b128 v[168:171], v151
	ds_read_b128 v[172:175], v151 offset:1024
	ds_read_b128 v[176:179], v151 offset:2048
	ds_read_b128 v[180:183], v151 offset:3072
	s_add_u32 s28, s28, 0x40000
	s_addc_u32 s29, s29, 0
	s_mov_b32 m0, s40
	v_lshl_add_u64 v[224:225], s[28:29], 0, v[134:135]
	ds_read_b128 v[184:187], v150 offset:32768
	ds_read_b128 v[188:191], v150 offset:33792
	ds_read_b128 v[192:195], v150 offset:34816
	ds_read_b128 v[196:199], v150 offset:35840
	ds_read_b128 v[200:203], v150 offset:36864
	ds_read_b128 v[204:207], v150 offset:37888
	ds_read_b128 v[208:211], v150 offset:38912
	ds_read_b128 v[212:215], v150 offset:39936
	global_load_lds_dwordx4 v[224:225], off
	v_lshl_add_u64 v[224:225], s[28:29], 0, v[130:131]
	s_mov_b32 m0, s41
	s_nop 0
	global_load_lds_dwordx4 v[224:225], off
	s_waitcnt vmcnt(8)
	s_waitcnt lgkmcnt(0)
	s_setprio 1
	s_barrier
	v_mfma_f32_16x16x32_bf16 v[124:127], v[152:155], v[184:187], v[124:127]
	v_mfma_f32_16x16x32_bf16 v[120:123], v[160:163], v[184:187], v[120:123]
	v_mfma_f32_16x16x32_bf16 v[108:111], v[152:155], v[192:195], v[108:111]
	v_mfma_f32_16x16x32_bf16 v[104:107], v[160:163], v[192:195], v[104:107]
	v_mfma_f32_16x16x32_bf16 v[92:95], v[152:155], v[200:203], v[92:95]
	v_mfma_f32_16x16x32_bf16 v[88:91], v[160:163], v[200:203], v[88:91]
	v_mfma_f32_16x16x32_bf16 v[76:79], v[152:155], v[208:211], v[76:79]
	v_mfma_f32_16x16x32_bf16 v[72:75], v[160:163], v[208:211], v[72:75]
	v_mfma_f32_16x16x32_bf16 v[124:127], v[156:159], v[188:191], v[124:127]
	v_mfma_f32_16x16x32_bf16 v[120:123], v[164:167], v[188:191], v[120:123]
	v_mfma_f32_16x16x32_bf16 v[108:111], v[156:159], v[196:199], v[108:111]
	v_mfma_f32_16x16x32_bf16 v[104:107], v[164:167], v[196:199], v[104:107]
	v_mfma_f32_16x16x32_bf16 v[92:95], v[156:159], v[204:207], v[92:95]
	v_mfma_f32_16x16x32_bf16 v[88:91], v[164:167], v[204:207], v[88:91]
	v_mfma_f32_16x16x32_bf16 v[76:79], v[156:159], v[212:215], v[76:79]
	v_mfma_f32_16x16x32_bf16 v[72:75], v[164:167], v[212:215], v[72:75]
	v_mfma_f32_16x16x32_bf16 v[116:119], v[168:171], v[184:187], v[116:119]
	v_mfma_f32_16x16x32_bf16 v[112:115], v[176:179], v[184:187], v[112:115]
	v_mfma_f32_16x16x32_bf16 v[100:103], v[168:171], v[192:195], v[100:103]
	v_mfma_f32_16x16x32_bf16 v[96:99], v[176:179], v[192:195], v[96:99]
	v_mfma_f32_16x16x32_bf16 v[84:87], v[168:171], v[200:203], v[84:87]
	v_mfma_f32_16x16x32_bf16 v[80:83], v[176:179], v[200:203], v[80:83]
	v_mfma_f32_16x16x32_bf16 v[68:71], v[168:171], v[208:211], v[68:71]
	v_mfma_f32_16x16x32_bf16 v[64:67], v[176:179], v[208:211], v[64:67]
	v_mfma_f32_16x16x32_bf16 v[116:119], v[172:175], v[188:191], v[116:119]
	v_mfma_f32_16x16x32_bf16 v[112:115], v[180:183], v[188:191], v[112:115]
	v_mfma_f32_16x16x32_bf16 v[100:103], v[172:175], v[196:199], v[100:103]
	v_mfma_f32_16x16x32_bf16 v[96:99], v[180:183], v[196:199], v[96:99]
	v_mfma_f32_16x16x32_bf16 v[84:87], v[172:175], v[204:207], v[84:87]
	v_mfma_f32_16x16x32_bf16 v[80:83], v[180:183], v[204:207], v[80:83]
	v_mfma_f32_16x16x32_bf16 v[68:71], v[172:175], v[212:215], v[68:71]
	v_mfma_f32_16x16x32_bf16 v[64:67], v[180:183], v[212:215], v[64:67]
	s_barrier
	s_setprio 0
	s_add_i32 s28, s55, s33
	v_lshl_add_u64 v[216:217], v[216:217], 0, s[10:11]
	s_mov_b32 m0, s28
	ds_read_b128 v[184:187], v150 offset:49152
	ds_read_b128 v[188:191], v150 offset:50176
	ds_read_b128 v[192:195], v150 offset:51200
	ds_read_b128 v[196:199], v150 offset:52224
	ds_read_b128 v[200:203], v150 offset:53248
	ds_read_b128 v[204:207], v150 offset:54272
	ds_read_b128 v[208:211], v150 offset:55296
	ds_read_b128 v[212:215], v150 offset:56320
	global_load_lds_dwordx4 v[216:217], off
	s_add_i32 m0, s28, 0x2000
	s_add_u32 s26, s26, 0x40080
	v_lshl_add_u64 v[216:217], v[218:219], 0, s[10:11]
	s_addc_u32 s27, s27, 0
	s_add_i32 s28, s56, s33
	global_load_lds_dwordx4 v[216:217], off
	v_lshl_add_u64 v[216:217], s[26:27], 0, v[132:133]
	s_mov_b32 m0, s28
	s_nop 0
	global_load_lds_dwordx4 v[216:217], off
	v_lshl_add_u64 v[216:217], s[26:27], 0, v[128:129]
	s_add_i32 m0, s28, 0x2000
	s_nop 0
	global_load_lds_dwordx4 v[216:217], off
	v_lshl_add_u64 v[216:217], v[220:221], 0, s[10:11]
	s_mov_b32 m0, s42
	s_nop 0
	global_load_lds_dwordx4 v[216:217], off
	v_lshl_add_u64 v[216:217], v[222:223], 0, s[10:11]
	s_mov_b32 m0, s43
	s_nop 0
	global_load_lds_dwordx4 v[216:217], off
	s_waitcnt vmcnt(8)
	s_waitcnt lgkmcnt(0)
	s_setprio 1
	s_barrier
	v_mfma_f32_16x16x32_bf16 v[60:63], v[152:155], v[184:187], v[60:63]
	v_mfma_f32_16x16x32_bf16 v[56:59], v[160:163], v[184:187], v[56:59]
	v_mfma_f32_16x16x32_bf16 v[44:47], v[152:155], v[192:195], v[44:47]
	v_mfma_f32_16x16x32_bf16 v[40:43], v[160:163], v[192:195], v[40:43]
	v_mfma_f32_16x16x32_bf16 v[28:31], v[152:155], v[200:203], v[28:31]
	v_mfma_f32_16x16x32_bf16 v[24:27], v[160:163], v[200:203], v[24:27]
	v_mfma_f32_16x16x32_bf16 v[12:15], v[152:155], v[208:211], v[12:15]
	v_mfma_f32_16x16x32_bf16 v[8:11], v[160:163], v[208:211], v[8:11]
	v_mfma_f32_16x16x32_bf16 v[60:63], v[156:159], v[188:191], v[60:63]
	v_mfma_f32_16x16x32_bf16 v[56:59], v[164:167], v[188:191], v[56:59]
	v_mfma_f32_16x16x32_bf16 v[44:47], v[156:159], v[196:199], v[44:47]
	v_mfma_f32_16x16x32_bf16 v[40:43], v[164:167], v[196:199], v[40:43]
	v_mfma_f32_16x16x32_bf16 v[28:31], v[156:159], v[204:207], v[28:31]
	v_mfma_f32_16x16x32_bf16 v[24:27], v[164:167], v[204:207], v[24:27]
	v_mfma_f32_16x16x32_bf16 v[12:15], v[156:159], v[212:215], v[12:15]
	v_mfma_f32_16x16x32_bf16 v[8:11], v[164:167], v[212:215], v[8:11]
	v_mfma_f32_16x16x32_bf16 v[52:55], v[168:171], v[184:187], v[52:55]
	v_mfma_f32_16x16x32_bf16 v[48:51], v[176:179], v[184:187], v[48:51]
	v_mfma_f32_16x16x32_bf16 v[36:39], v[168:171], v[192:195], v[36:39]
	v_mfma_f32_16x16x32_bf16 v[32:35], v[176:179], v[192:195], v[32:35]
	v_mfma_f32_16x16x32_bf16 v[20:23], v[168:171], v[200:203], v[20:23]
	v_mfma_f32_16x16x32_bf16 v[16:19], v[176:179], v[200:203], v[16:19]
	v_mfma_f32_16x16x32_bf16 v[4:7], v[168:171], v[208:211], v[4:7]
	v_mfma_f32_16x16x32_bf16 v[0:3], v[176:179], v[208:211], v[0:3]
	v_mfma_f32_16x16x32_bf16 v[52:55], v[172:175], v[188:191], v[52:55]
	v_mfma_f32_16x16x32_bf16 v[48:51], v[180:183], v[188:191], v[48:51]
	v_mfma_f32_16x16x32_bf16 v[36:39], v[172:175], v[196:199], v[36:39]
	v_mfma_f32_16x16x32_bf16 v[32:35], v[180:183], v[196:199], v[32:35]
	v_mfma_f32_16x16x32_bf16 v[20:23], v[172:175], v[204:207], v[20:23]
	v_mfma_f32_16x16x32_bf16 v[16:19], v[180:183], v[204:207], v[16:19]
	v_mfma_f32_16x16x32_bf16 v[4:7], v[172:175], v[212:215], v[4:7]
	v_mfma_f32_16x16x32_bf16 v[0:3], v[180:183], v[212:215], v[0:3]
	s_barrier
	s_setprio 0
	s_add_i32 s54, s54, 2
	s_add_u32 s24, s24, 0x100
	s_addc_u32 s25, s25, 0
	s_add_u32 s52, s52, 0x100
	s_addc_u32 s53, s53, 0
	s_cmp_gt_u32 s54, 13
; #define PG8_STAGE(bufoff, gbase, voff) do { _Pragma("unroll") for (int _i = 0; _i < 2; ++_i) \
;         __builtin_amdgcn_global_load_lds((const unsigned*)((const char*)(gbase) + (voff)[_i]), (PG8_LAS unsigned*)(lds + (bufoff) + ldsw + _i * 8192), 16, 0, 0); } while (0)
; #define PG8_LDA(dst, b, h) do { _Pragma("unroll") for (int m = 0; m < 4; ++m) _Pragma("unroll") for (int k = 0; k < 2; ++k) dst[m][k] = *(const PG8_LAS bf16x8*)(lds + PG8_SA(b, h) + aoff + m * 2048 + k * 1024); } while (0)
; #define PG8_LDB(dst, b, h) do { _Pragma("unroll") for (int n = 0; n < 2; ++n) _Pragma("unroll") for (int k = 0; k < 2; ++k) dst[n][k] = *(const PG8_LAS bf16x8*)(lds + PG8_SB(b, h) + boff + n * 2048 + k * 1024); } while (0)
; #define PG8_MMA(ai, bj, At, Bt) do { __builtin_amdgcn_s_setprio(1); _Pragma("unroll") for (int m = 0; m < 4; ++m) _Pragma("unroll") for (int n = 0; n < 2; ++n) _Pragma("unroll") for (int k = 0; k < 2; ++k) \
;         acc[ai][bj][m][n] = __builtin_amdgcn_mfma_f32_16x16x32_bf16(Bt[n][k], At[m][k], acc[ai][bj][m][n], 0, 0, 0); __builtin_amdgcn_s_setprio(0); } while (0)
; #define PG8_WAIT_V(n) asm volatile("s_waitcnt vmcnt(" #n ")" ::: "memory")
; #define PG8_WAIT_L(n) asm volatile("s_waitcnt lgkmcnt(" #n ")" ::: "memory")
; #define PG8_BAR __builtin_amdgcn_s_barrier()
; #define PG8_SCHED __builtin_amdgcn_sched_barrier(0)
; template <class Epi, class Sched, bool ALIGN_EPI = false, bool SP2 = false>
; __device__ __forceinline__ void gemm_phase(PG8_LAS unsigned char* lds, const Gemm g, const Sched& S, const Epi& E) {
;     ...
;             PG8_LDB(B0, 0, 0); PG8_LDB(B1, 0, 1); PG8_SCHED; PG8_LDA(At, 0, 0); PG8_STAGE(PG8_SA(1, 1), a1 + hstep, voffA);
;             PG8_WAIT_V(8); PG8_WAIT_L(0); PG8_BAR; PG8_MMA(0, 0, At, B0); PG8_MMA(0, 1, At, B1); PG8_BAR; PG8_SCHED;
;             PG8_LDA(At, 0, 1); PG8_STAGE(PG8_SB(0, 0), b2, voffB); PG8_STAGE(PG8_SB(0, 1), b2 + hstep, voffB); PG8_STAGE(PG8_SA(0, 0), a2, voffA);
;             PG8_WAIT_V(8); PG8_WAIT_L(0); PG8_BAR; PG8_MMA(1, 0, At, B0); PG8_MMA(1, 1, At, B1); PG8_BAR; PG8_SCHED;
.LBB0_1219:
	ds_read_b128 v[152:155], v148
	ds_read_b128 v[156:159], v148 offset:1024
	ds_read_b128 v[160:163], v148 offset:2048
	ds_read_b128 v[164:167], v148 offset:3072
	ds_read_b128 v[168:171], v149
	ds_read_b128 v[172:175], v149 offset:1024
	ds_read_b128 v[176:179], v149 offset:2048
	ds_read_b128 v[180:183], v149 offset:3072
	s_add_u32 s26, s24, 0xfffc0080
	s_addc_u32 s27, s25, -1
	s_cmp_eq_u32 s54, 12
	s_cselect_b32 s29, s17, s27
	s_cselect_b32 s28, s50, s26
	s_cselect_b32 s27, s15, s53
	s_cselect_b32 s26, s51, s52
	v_lshl_add_u64 v[216:217], s[24:25], 0, v[136:137]
	s_add_i32 m0, s23, 0xc000
	ds_read_b128 v[184:187], v150
	ds_read_b128 v[188:191], v150 offset:1024
	ds_read_b128 v[192:195], v150 offset:2048
	ds_read_b128 v[196:199], v150 offset:3072
	ds_read_b128 v[200:203], v150 offset:4096
	ds_read_b128 v[204:207], v150 offset:5120
	ds_read_b128 v[208:211], v150 offset:6144
	ds_read_b128 v[212:215], v150 offset:7168
	global_load_lds_dwordx4 v[216:217], off
	v_lshl_add_u64 v[216:217], s[24:25], 0, v[138:139]
	s_add_i32 m0, s23, 0xe000
	s_nop 0
	global_load_lds_dwordx4 v[216:217], off
	s_waitcnt vmcnt(8)
	s_waitcnt lgkmcnt(0)
	s_setprio 1
	s_barrier
	v_mfma_f32_16x16x32_bf16 v[124:127], v[152:155], v[184:187], v[124:127]
	v_mfma_f32_16x16x32_bf16 v[120:123], v[160:163], v[184:187], v[120:123]
	v_mfma_f32_16x16x32_bf16 v[108:111], v[152:155], v[192:195], v[108:111]
	v_mfma_f32_16x16x32_bf16 v[104:107], v[160:163], v[192:195], v[104:107]
	v_mfma_f32_16x16x32_bf16 v[92:95], v[152:155], v[200:203], v[92:95]
	v_mfma_f32_16x16x32_bf16 v[88:91], v[160:163], v[200:203], v[88:91]
	v_mfma_f32_16x16x32_bf16 v[76:79], v[152:155], v[208:211], v[76:79]
	v_mfma_f32_16x16x32_bf16 v[72:75], v[160:163], v[208:211], v[72:75]
	v_mfma_f32_16x16x32_bf16 v[124:127], v[156:159], v[188:191], v[124:127]
	v_mfma_f32_16x16x32_bf16 v[120:123], v[164:167], v[188:191], v[120:123]
	v_mfma_f32_16x16x32_bf16 v[108:111], v[156:159], v[196:199], v[108:111]
	v_mfma_f32_16x16x32_bf16 v[104:107], v[164:167], v[196:199], v[104:107]
	v_mfma_f32_16x16x32_bf16 v[92:95], v[156:159], v[204:207], v[92:95]
	v_mfma_f32_16x16x32_bf16 v[88:91], v[164:167], v[204:207], v[88:91]
	v_mfma_f32_16x16x32_bf16 v[76:79], v[156:159], v[212:215], v[76:79]
	v_mfma_f32_16x16x32_bf16 v[72:75], v[164:167], v[212:215], v[72:75]
	v_mfma_f32_16x16x32_bf16 v[116:119], v[168:171], v[184:187], v[116:119]
	v_mfma_f32_16x16x32_bf16 v[112:115], v[176:179], v[184:187], v[112:115]
	v_mfma_f32_16x16x32_bf16 v[100:103], v[168:171], v[192:195], v[100:103]
	v_mfma_f32_16x16x32_bf16 v[96:99], v[176:179], v[192:195], v[96:99]
	v_mfma_f32_16x16x32_bf16 v[84:87], v[168:171], v[200:203], v[84:87]
	v_mfma_f32_16x16x32_bf16 v[80:83], v[176:179], v[200:203], v[80:83]
	v_mfma_f32_16x16x32_bf16 v[68:71], v[168:171], v[208:211], v[68:71]
	v_mfma_f32_16x16x32_bf16 v[64:67], v[176:179], v[208:211], v[64:67]
	v_mfma_f32_16x16x32_bf16 v[116:119], v[172:175], v[188:191], v[116:119]
	v_mfma_f32_16x16x32_bf16 v[112:115], v[180:183], v[188:191], v[112:115]
	v_mfma_f32_16x16x32_bf16 v[100:103], v[172:175], v[196:199], v[100:103]
	v_mfma_f32_16x16x32_bf16 v[96:99], v[180:183], v[196:199], v[96:99]
	v_mfma_f32_16x16x32_bf16 v[84:87], v[172:175], v[204:207], v[84:87]
	v_mfma_f32_16x16x32_bf16 v[80:83], v[180:183], v[204:207], v[80:83]
	v_mfma_f32_16x16x32_bf16 v[68:71], v[172:175], v[212:215], v[68:71]
	v_mfma_f32_16x16x32_bf16 v[64:67], v[180:183], v[212:215], v[64:67]
	s_barrier
	s_setprio 0
	s_add_i32 s55, s44, s33
	v_lshl_add_u64 v[216:217], s[26:27], 0, v[132:133]
	s_mov_b32 m0, s55
	ds_read_b128 v[184:187], v150 offset:16384
	ds_read_b128 v[188:191], v150 offset:17408
	ds_read_b128 v[192:195], v150 offset:18432
	ds_read_b128 v[196:199], v150 offset:19456
	ds_read_b128 v[200:203], v150 offset:20480
	ds_read_b128 v[204:207], v150 offset:21504
	ds_read_b128 v[208:211], v150 offset:22528
	ds_read_b128 v[212:215], v150 offset:23552
	global_load_lds_dwordx4 v[216:217], off
	s_add_i32 m0, s55, 0x2000
	s_add_u32 s56, s26, 0x40000
	v_lshl_add_u64 v[218:219], s[26:27], 0, v[128:129]
	s_addc_u32 s57, s27, 0
	s_add_i32 s55, s45, s33
	global_load_lds_dwordx4 v[218:219], off
	v_lshl_add_u64 v[220:221], s[56:57], 0, v[132:133]
	s_mov_b32 m0, s55
	v_lshl_add_u64 v[222:223], s[28:29], 0, v[130:131]
	global_load_lds_dwordx4 v[220:221], off
	v_lshl_add_u64 v[220:221], s[56:57], 0, v[128:129]
	s_add_i32 m0, s55, 0x2000
	s_nop 0
	global_load_lds_dwordx4 v[220:221], off
	v_lshl_add_u64 v[220:221], s[28:29], 0, v[134:135]
	s_mov_b32 m0, s23
	s_nop 0
	global_load_lds_dwordx4 v[220:221], off
	s_mov_b32 m0, s39
	s_nop 0
	global_load_lds_dwordx4 v[222:223], off
	s_waitcnt vmcnt(8)
	s_waitcnt lgkmcnt(0)
	s_setprio 1
	s_barrier
; #define PG8_STAGE(bufoff, gbase, voff) do { _Pragma("unroll") for (int _i = 0; _i < 2; ++_i) \
;         __builtin_amdgcn_global_load_lds((const unsigned*)((const char*)(gbase) + (voff)[_i]), (PG8_LAS unsigned*)(lds + (bufoff) + ldsw + _i * 8192), 16, 0, 0); } while (0)
; #define PG8_LDA(dst, b, h) do { _Pragma("unroll") for (int m = 0; m < 4; ++m) _Pragma("unroll") for (int k = 0; k < 2; ++k) dst[m][k] = *(const PG8_LAS bf16x8*)(lds + PG8_SA(b, h) + aoff + m * 2048 + k * 1024); } while (0)
; #define PG8_LDB(dst, b, h) do { _Pragma("unroll") for (int n = 0; n < 2; ++n) _Pragma("unroll") for (int k = 0; k < 2; ++k) dst[n][k] = *(const PG8_LAS bf16x8*)(lds + PG8_SB(b, h) + boff + n * 2048 + k * 1024); } while (0)
; #define PG8_MMA(ai, bj, At, Bt) do { __builtin_amdgcn_s_setprio(1); _Pragma("unroll") for (int m = 0; m < 4; ++m) _Pragma("unroll") for (int n = 0; n < 2; ++n) _Pragma("unroll") for (int k = 0; k < 2; ++k) \
;         acc[ai][bj][m][n] = __builtin_amdgcn_mfma_f32_16x16x32_bf16(Bt[n][k], At[m][k], acc[ai][bj][m][n], 0, 0, 0); __builtin_amdgcn_s_setprio(0); } while (0)
; #define PG8_WAIT_V(n) asm volatile("s_waitcnt vmcnt(" #n ")" ::: "memory")
; #define PG8_WAIT_L(n) asm volatile("s_waitcnt lgkmcnt(" #n ")" ::: "memory")
; #define PG8_BAR __builtin_amdgcn_s_barrier()
; #define PG8_SCHED __builtin_amdgcn_sched_barrier(0)
; template <class Epi, class Sched, bool ALIGN_EPI = false, bool SP2 = false>
; __device__ __forceinline__ void gemm_phase(PG8_LAS unsigned char* lds, const Gemm g, const Sched& S, const Epi& E) {
;     ...
;             PG8_WAIT_V(8); PG8_WAIT_L(0); PG8_BAR; PG8_MMA(1, 0, At, B0); PG8_MMA(1, 1, At, B1); PG8_BAR; PG8_SCHED;
;             PG8_LDB(B0, 1, 0); PG8_LDB(B1, 1, 1); PG8_SCHED; PG8_LDA(At, 1, 0); PG8_STAGE(PG8_SA(0, 1), a2 + hstep, voffA);
;             PG8_WAIT_V(8); PG8_WAIT_L(0); PG8_BAR; PG8_MMA(0, 0, At, B0); PG8_MMA(0, 1, At, B1); PG8_BAR; PG8_SCHED;
	v_mfma_f32_16x16x32_bf16 v[60:63], v[152:155], v[184:187], v[60:63]
	v_mfma_f32_16x16x32_bf16 v[56:59], v[160:163], v[184:187], v[56:59]
	v_mfma_f32_16x16x32_bf16 v[44:47], v[152:155], v[192:195], v[44:47]
	v_mfma_f32_16x16x32_bf16 v[40:43], v[160:163], v[192:195], v[40:43]
	v_mfma_f32_16x16x32_bf16 v[28:31], v[152:155], v[200:203], v[28:31]
	v_mfma_f32_16x16x32_bf16 v[24:27], v[160:163], v[200:203], v[24:27]
	v_mfma_f32_16x16x32_bf16 v[12:15], v[152:155], v[208:211], v[12:15]
	v_mfma_f32_16x16x32_bf16 v[8:11], v[160:163], v[208:211], v[8:11]
	v_mfma_f32_16x16x32_bf16 v[60:63], v[156:159], v[188:191], v[60:63]
	v_mfma_f32_16x16x32_bf16 v[56:59], v[164:167], v[188:191], v[56:59]
	v_mfma_f32_16x16x32_bf16 v[44:47], v[156:159], v[196:199], v[44:47]
	v_mfma_f32_16x16x32_bf16 v[40:43], v[164:167], v[196:199], v[40:43]
	v_mfma_f32_16x16x32_bf16 v[28:31], v[156:159], v[204:207], v[28:31]
	v_mfma_f32_16x16x32_bf16 v[24:27], v[164:167], v[204:207], v[24:27]
	v_mfma_f32_16x16x32_bf16 v[12:15], v[156:159], v[212:215], v[12:15]
	v_mfma_f32_16x16x32_bf16 v[8:11], v[164:167], v[212:215], v[8:11]
	v_mfma_f32_16x16x32_bf16 v[52:55], v[168:171], v[184:187], v[52:55]
	v_mfma_f32_16x16x32_bf16 v[48:51], v[176:179], v[184:187], v[48:51]
	v_mfma_f32_16x16x32_bf16 v[36:39], v[168:171], v[192:195], v[36:39]
	v_mfma_f32_16x16x32_bf16 v[32:35], v[176:179], v[192:195], v[32:35]
	v_mfma_f32_16x16x32_bf16 v[20:23], v[168:171], v[200:203], v[20:23]
	v_mfma_f32_16x16x32_bf16 v[16:19], v[176:179], v[200:203], v[16:19]
	v_mfma_f32_16x16x32_bf16 v[4:7], v[168:171], v[208:211], v[4:7]
	v_mfma_f32_16x16x32_bf16 v[0:3], v[176:179], v[208:211], v[0:3]
	v_mfma_f32_16x16x32_bf16 v[52:55], v[172:175], v[188:191], v[52:55]
	v_mfma_f32_16x16x32_bf16 v[48:51], v[180:183], v[188:191], v[48:51]
	v_mfma_f32_16x16x32_bf16 v[36:39], v[172:175], v[196:199], v[36:39]
	v_mfma_f32_16x16x32_bf16 v[32:35], v[180:183], v[196:199], v[32:35]
	v_mfma_f32_16x16x32_bf16 v[20:23], v[172:175], v[204:207], v[20:23]
	v_mfma_f32_16x16x32_bf16 v[16:19], v[180:183], v[204:207], v[16:19]
	v_mfma_f32_16x16x32_bf16 v[4:7], v[172:175], v[212:215], v[4:7]
	v_mfma_f32_16x16x32_bf16 v[0:3], v[180:183], v[212:215], v[0:3]
	s_barrier
	s_setprio 0
	s_add_i32 s55, 0, 0x18000
	v_add_u32_e32 v151, s55, v145
	s_add_i32 s56, 0, 0x1c000
	ds_read_b128 v[152:155], v151
	ds_read_b128 v[156:159], v151 offset:1024
	ds_read_b128 v[160:163], v151 offset:2048
	ds_read_b128 v[164:167], v151 offset:3072
	v_add_u32_e32 v151, s56, v145
	ds_read_b128 v[168:171], v151
	ds_read_b128 v[172:175], v151 offset:1024
	ds_read_b128 v[176:179], v151 offset:2048
	ds_read_b128 v[180:183], v151 offset:3072
	s_add_u32 s28, s28, 0x40000
	s_addc_u32 s29, s29, 0
	s_mov_b32 m0, s40
	v_lshl_add_u64 v[224:225], s[28:29], 0, v[134:135]
	ds_read_b128 v[184:187], v150 offset:32768
	ds_read_b128 v[188:191], v150 offset:33792
	ds_read_b128 v[192:195], v150 offset:34816
	ds_read_b128 v[196:199], v150 offset:35840
	ds_read_b128 v[200:203], v150 offset:36864
	ds_read_b128 v[204:207], v150 offset:37888
	ds_read_b128 v[208:211], v150 offset:38912
	ds_read_b128 v[212:215], v150 offset:39936
	global_load_lds_dwordx4 v[224:225], off
	v_lshl_add_u64 v[224:225], s[28:29], 0, v[130:131]
	s_mov_b32 m0, s41
	s_nop 0
	global_load_lds_dwordx4 v[224:225], off
	s_waitcnt vmcnt(8)
	s_waitcnt lgkmcnt(0)
	s_setprio 1
	s_barrier
	v_mfma_f32_16x16x32_bf16 v[124:127], v[152:155], v[184:187], v[124:127]
	v_mfma_f32_16x16x32_bf16 v[120:123], v[160:163], v[184:187], v[120:123]
	v_mfma_f32_16x16x32_bf16 v[108:111], v[152:155], v[192:195], v[108:111]
	v_mfma_f32_16x16x32_bf16 v[104:107], v[160:163], v[192:195], v[104:107]
	v_mfma_f32_16x16x32_bf16 v[92:95], v[152:155], v[200:203], v[92:95]
	v_mfma_f32_16x16x32_bf16 v[88:91], v[160:163], v[200:203], v[88:91]
	v_mfma_f32_16x16x32_bf16 v[76:79], v[152:155], v[208:211], v[76:79]
	v_mfma_f32_16x16x32_bf16 v[72:75], v[160:163], v[208:211], v[72:75]
	v_mfma_f32_16x16x32_bf16 v[124:127], v[156:159], v[188:191], v[124:127]
	v_mfma_f32_16x16x32_bf16 v[120:123], v[164:167], v[188:191], v[120:123]
	v_mfma_f32_16x16x32_bf16 v[108:111], v[156:159], v[196:199], v[108:111]
	v_mfma_f32_16x16x32_bf16 v[104:107], v[164:167], v[196:199], v[104:107]
	v_mfma_f32_16x16x32_bf16 v[92:95], v[156:159], v[204:207], v[92:95]
	v_mfma_f32_16x16x32_bf16 v[88:91], v[164:167], v[204:207], v[88:91]
	v_mfma_f32_16x16x32_bf16 v[76:79], v[156:159], v[212:215], v[76:79]
	v_mfma_f32_16x16x32_bf16 v[72:75], v[164:167], v[212:215], v[72:75]
	v_mfma_f32_16x16x32_bf16 v[116:119], v[168:171], v[184:187], v[116:119]
	v_mfma_f32_16x16x32_bf16 v[112:115], v[176:179], v[184:187], v[112:115]
	v_mfma_f32_16x16x32_bf16 v[100:103], v[168:171], v[192:195], v[100:103]
	v_mfma_f32_16x16x32_bf16 v[96:99], v[176:179], v[192:195], v[96:99]
	v_mfma_f32_16x16x32_bf16 v[84:87], v[168:171], v[200:203], v[84:87]
	v_mfma_f32_16x16x32_bf16 v[80:83], v[176:179], v[200:203], v[80:83]
	v_mfma_f32_16x16x32_bf16 v[68:71], v[168:171], v[208:211], v[68:71]
	v_mfma_f32_16x16x32_bf16 v[64:67], v[176:179], v[208:211], v[64:67]
	v_mfma_f32_16x16x32_bf16 v[116:119], v[172:175], v[188:191], v[116:119]
	v_mfma_f32_16x16x32_bf16 v[112:115], v[180:183], v[188:191], v[112:115]
	v_mfma_f32_16x16x32_bf16 v[100:103], v[172:175], v[196:199], v[100:103]
	v_mfma_f32_16x16x32_bf16 v[96:99], v[180:183], v[196:199], v[96:99]
	v_mfma_f32_16x16x32_bf16 v[84:87], v[172:175], v[204:207], v[84:87]
	v_mfma_f32_16x16x32_bf16 v[80:83], v[180:183], v[204:207], v[80:83]
	v_mfma_f32_16x16x32_bf16 v[68:71], v[172:175], v[212:215], v[68:71]
	v_mfma_f32_16x16x32_bf16 v[64:67], v[180:183], v[212:215], v[64:67]
	s_barrier
; #define PG8_STAGE(bufoff, gbase, voff) do { _Pragma("unroll") for (int _i = 0; _i < 2; ++_i) \
;         __builtin_amdgcn_global_load_lds((const unsigned*)((const char*)(gbase) + (voff)[_i]), (PG8_LAS unsigned*)(lds + (bufoff) + ldsw + _i * 8192), 16, 0, 0); } while (0)
; #define PG8_LDA(dst, b, h) do { _Pragma("unroll") for (int m = 0; m < 4; ++m) _Pragma("unroll") for (int k = 0; k < 2; ++k) dst[m][k] = *(const PG8_LAS bf16x8*)(lds + PG8_SA(b, h) + aoff + m * 2048 + k * 1024); } while (0)
; #define PG8_MMA(ai, bj, At, Bt) do { __builtin_amdgcn_s_setprio(1); _Pragma("unroll") for (int m = 0; m < 4; ++m) _Pragma("unroll") for (int n = 0; n < 2; ++n) _Pragma("unroll") for (int k = 0; k < 2; ++k) \
;         acc[ai][bj][m][n] = __builtin_amdgcn_mfma_f32_16x16x32_bf16(Bt[n][k], At[m][k], acc[ai][bj][m][n], 0, 0, 0); __builtin_amdgcn_s_setprio(0); } while (0)
; #define PG8_WAIT_V(n) asm volatile("s_waitcnt vmcnt(" #n ")" ::: "memory")
; #define PG8_WAIT_L(n) asm volatile("s_waitcnt lgkmcnt(" #n ")" ::: "memory")
; #define PG8_BAR __builtin_amdgcn_s_barrier()
; #define PG8_SCHED __builtin_amdgcn_sched_barrier(0)
; template <class Epi, class Sched, bool ALIGN_EPI = false, bool SP2 = false>
; __device__ __forceinline__ void gemm_phase(PG8_LAS unsigned char* lds, const Gemm g, const Sched& S, const Epi& E) {
;     ...
;         for (int t = 0; t < nt; t += 2) {
;             const bool last = (t == nt - 2);
;     ...
;             PG8_LDA(At, 1, 1); PG8_STAGE(PG8_SB(1, 0), b3, voffB); PG8_STAGE(PG8_SB(1, 1), b3 + hstep, voffB); PG8_STAGE(PG8_SA(1, 0), a3, voffA);
;             PG8_WAIT_V(8); PG8_WAIT_L(0); PG8_BAR; PG8_MMA(1, 0, At, B0); PG8_MMA(1, 1, At, B1); PG8_BAR; PG8_SCHED;
	s_setprio 0
	s_add_i32 s28, s55, s33
	v_lshl_add_u64 v[216:217], v[216:217], 0, s[10:11]
	s_mov_b32 m0, s28
	ds_read_b128 v[184:187], v150 offset:49152
	ds_read_b128 v[188:191], v150 offset:50176
	ds_read_b128 v[192:195], v150 offset:51200
	ds_read_b128 v[196:199], v150 offset:52224
	ds_read_b128 v[200:203], v150 offset:53248
	ds_read_b128 v[204:207], v150 offset:54272
	ds_read_b128 v[208:211], v150 offset:55296
	ds_read_b128 v[212:215], v150 offset:56320
	global_load_lds_dwordx4 v[216:217], off
	s_add_i32 m0, s28, 0x2000
	s_add_u32 s26, s26, 0x40080
	v_lshl_add_u64 v[216:217], v[218:219], 0, s[10:11]
	s_addc_u32 s27, s27, 0
	s_add_i32 s28, s56, s33
	global_load_lds_dwordx4 v[216:217], off
	v_lshl_add_u64 v[216:217], s[26:27], 0, v[132:133]
	s_mov_b32 m0, s28
	s_nop 0
	global_load_lds_dwordx4 v[216:217], off
	v_lshl_add_u64 v[216:217], s[26:27], 0, v[128:129]
	s_add_i32 m0, s28, 0x2000
	s_nop 0
	global_load_lds_dwordx4 v[216:217], off
	v_lshl_add_u64 v[216:217], v[220:221], 0, s[10:11]
	s_mov_b32 m0, s42
	s_nop 0
	global_load_lds_dwordx4 v[216:217], off
	v_lshl_add_u64 v[216:217], v[222:223], 0, s[10:11]
	s_mov_b32 m0, s43
	s_nop 0
	global_load_lds_dwordx4 v[216:217], off
	s_waitcnt vmcnt(8)
	s_waitcnt lgkmcnt(0)
	s_setprio 1
	s_barrier
	v_mfma_f32_16x16x32_bf16 v[60:63], v[152:155], v[184:187], v[60:63]
	v_mfma_f32_16x16x32_bf16 v[56:59], v[160:163], v[184:187], v[56:59]
	v_mfma_f32_16x16x32_bf16 v[44:47], v[152:155], v[192:195], v[44:47]
	v_mfma_f32_16x16x32_bf16 v[40:43], v[160:163], v[192:195], v[40:43]
	v_mfma_f32_16x16x32_bf16 v[28:31], v[152:155], v[200:203], v[28:31]
	v_mfma_f32_16x16x32_bf16 v[24:27], v[160:163], v[200:203], v[24:27]
	v_mfma_f32_16x16x32_bf16 v[12:15], v[152:155], v[208:211], v[12:15]
	v_mfma_f32_16x16x32_bf16 v[8:11], v[160:163], v[208:211], v[8:11]
	v_mfma_f32_16x16x32_bf16 v[60:63], v[156:159], v[188:191], v[60:63]
	v_mfma_f32_16x16x32_bf16 v[56:59], v[164:167], v[188:191], v[56:59]
	v_mfma_f32_16x16x32_bf16 v[44:47], v[156:159], v[196:199], v[44:47]
	v_mfma_f32_16x16x32_bf16 v[40:43], v[164:167], v[196:199], v[40:43]
	v_mfma_f32_16x16x32_bf16 v[28:31], v[156:159], v[204:207], v[28:31]
	v_mfma_f32_16x16x32_bf16 v[24:27], v[164:167], v[204:207], v[24:27]
	v_mfma_f32_16x16x32_bf16 v[12:15], v[156:159], v[212:215], v[12:15]
	v_mfma_f32_16x16x32_bf16 v[8:11], v[164:167], v[212:215], v[8:11]
	v_mfma_f32_16x16x32_bf16 v[52:55], v[168:171], v[184:187], v[52:55]
	v_mfma_f32_16x16x32_bf16 v[48:51], v[176:179], v[184:187], v[48:51]
	v_mfma_f32_16x16x32_bf16 v[36:39], v[168:171], v[192:195], v[36:39]
	v_mfma_f32_16x16x32_bf16 v[32:35], v[176:179], v[192:195], v[32:35]
	v_mfma_f32_16x16x32_bf16 v[20:23], v[168:171], v[200:203], v[20:23]
	v_mfma_f32_16x16x32_bf16 v[16:19], v[176:179], v[200:203], v[16:19]
	v_mfma_f32_16x16x32_bf16 v[4:7], v[168:171], v[208:211], v[4:7]
	v_mfma_f32_16x16x32_bf16 v[0:3], v[176:179], v[208:211], v[0:3]
	v_mfma_f32_16x16x32_bf16 v[52:55], v[172:175], v[188:191], v[52:55]
	v_mfma_f32_16x16x32_bf16 v[48:51], v[180:183], v[188:191], v[48:51]
	v_mfma_f32_16x16x32_bf16 v[36:39], v[172:175], v[196:199], v[36:39]
	v_mfma_f32_16x16x32_bf16 v[32:35], v[180:183], v[196:199], v[32:35]
	v_mfma_f32_16x16x32_bf16 v[20:23], v[172:175], v[204:207], v[20:23]
	v_mfma_f32_16x16x32_bf16 v[16:19], v[180:183], v[204:207], v[16:19]
	v_mfma_f32_16x16x32_bf16 v[4:7], v[172:175], v[212:215], v[4:7]
	v_mfma_f32_16x16x32_bf16 v[0:3], v[180:183], v[212:215], v[0:3]
	s_barrier
	s_setprio 0
	s_add_i32 s54, s54, 2
	s_add_u32 s24, s24, 0x100
	s_addc_u32 s25, s25, 0
	s_add_u32 s52, s52, 0x100
	s_addc_u32 s53, s53, 0
	s_cmp_gt_u32 s54, 13
	s_cbranch_scc0 .LBB0_1219
	s_and_b64 vcc, exec, s[12:13]
	s_cbranch_vccz .LBB0_1222
	s_barrier
